# v34 plus snake ordering of the MFMAs within each k-group of the GEMM K-loops
# baseline (speedup 1.0000x reference)
; #define PG8_STAGE(bufoff, gbase, voff) do { _Pragma("unroll") for (int _i = 0; _i < 2; ++_i) \
;         __builtin_amdgcn_global_load_lds((const unsigned*)((const char*)(gbase) + (voff)[_i]), (LAS unsigned*)(lds + (bufoff) + ldsw + _i * 8192), 16, 0, 0); } while (0)
; #define PG8_LDA(dst, b, h) do { _Pragma("unroll") for (int m = 0; m < 4; ++m) _Pragma("unroll") for (int k = 0; k < 2; ++k) dst[m][k] = *(const LAS bf16x8*)(lds + PG8_SA(b, h) + aoff + m * 2048 + k * 1024); } while (0)
; #define PG8_LDB(dst, b, h) do { _Pragma("unroll") for (int n = 0; n < 2; ++n) _Pragma("unroll") for (int k = 0; k < 2; ++k) dst[n][k] = *(const LAS bf16x8*)(lds + PG8_SB(b, h) + boff + n * 2048 + k * 1024); } while (0)
; #define PG8_MMA(ai, bj, At, Bt) do { __builtin_amdgcn_s_setprio(1); _Pragma("unroll") for (int m = 0; m < 4; ++m) _Pragma("unroll") for (int n = 0; n < 2; ++n) _Pragma("unroll") for (int k = 0; k < 2; ++k) \
;         acc[ai][bj][m][n] = __builtin_amdgcn_mfma_f32_16x16x32_bf16(Bt[n][k], At[m][k], acc[ai][bj][m][n], 0, 0, 0); __builtin_amdgcn_s_setprio(0); } while (0)
; #define PG8_WAIT_L(n) asm volatile("s_waitcnt lgkmcnt(" #n ")" ::: "memory")
; #define PG8_BAR __builtin_amdgcn_s_barrier()
; #define PG8_SCHED __builtin_amdgcn_sched_barrier(0)
; template <class Epi>
; DEVI void gemm_phase(LAS unsigned char* lds, const bf16_t* gA, const bf16_t* gBt, const int lda, const int ldb, const int K, const StaticOrder S_, const Epi E) {
;     ...
;             const char* a1 = cA + (size_t)(t + 1) * kstep;
;             const char* a2 = last ? nA : cA + (size_t)(t + 2) * kstep; const char* b2 = last ? nB : cB + (size_t)(t + 2) * kstep;
;             const char* a3 = a2 + kstep; const char* b3 = b2 + kstep;
;             PG8_LDB(B0, 0, 0); PG8_SCHED; PG8_LDA(At, 0, 0); PG8_STAGE(PG8_SA(1, 1), a1 + hstepA, voffA);
;             PG8_WAIT_L(8); PG8_BAR; PG8_WAIT_L(0); PG8_MMA(0, 0, At, B0); PG8_BAR; PG8_SCHED;
;             PG8_LDB(B1, 0, 1); PG8_STAGE(PG8_SB(0, 0), b2, voffB);
;             PG8_BAR; PG8_WAIT_L(0); PG8_MMA(0, 1, At, B1); PG8_BAR;
;             PG8_LDA(At, 0, 1); PG8_STAGE(PG8_SA(0, 0), a2, voffA);
;             PG8_BAR; PG8_WAIT_L(0); PG8_MMA(1, 0, At, B0); PG8_BAR; PG8_SCHED;
.LBB0_259:
	ds_read_b128 v[158:161], v151
	ds_read_b128 v[162:165], v151 offset:1024
	ds_read_b128 v[166:169], v151 offset:2048
	ds_read_b128 v[170:173], v151 offset:3072
	s_add_i32 s79, s26, 2
	s_add_u32 s28, s24, 0x80
	s_addc_u32 s27, s25, 0
	s_cmp_eq_u32 s96, s26
	s_cselect_b32 s26, s4, s28
	s_cselect_b32 s27, s5, s27
	s_cselect_b32 s29, s23, s78
	s_cselect_b32 s28, s22, s77
	v_lshl_add_u64 v[144:145], s[24:25], 0, v[138:139]
	s_add_i32 m0, s37, 0xc000
	ds_read_b128 v[174:177], v152
	ds_read_b128 v[178:181], v152 offset:1024
	ds_read_b128 v[182:185], v152 offset:2048
	ds_read_b128 v[186:189], v152 offset:3072
	ds_read_b128 v[190:193], v152 offset:4096
	ds_read_b128 v[198:201], v152 offset:5120
	ds_read_b128 v[202:205], v152 offset:6144
	ds_read_b128 v[206:209], v152 offset:7168
	global_load_lds_dwordx4 v[144:145], off
	v_lshl_add_u64 v[144:145], s[24:25], 0, v[140:141]
	s_add_i32 m0, s37, 0xe000
	s_nop 0
	global_load_lds_dwordx4 v[144:145], off
	s_waitcnt lgkmcnt(8)
	s_barrier
	s_waitcnt lgkmcnt(0)
	v_mfma_f32_16x16x32_bf16 v[120:123], v[158:161], v[174:177], v[120:123]
	v_mfma_f32_16x16x32_bf16 v[116:119], v[166:169], v[174:177], v[116:119]
	v_mfma_f32_16x16x32_bf16 v[100:103], v[166:169], v[182:185], v[100:103]
	v_mfma_f32_16x16x32_bf16 v[108:111], v[158:161], v[182:185], v[108:111]
	v_mfma_f32_16x16x32_bf16 v[92:95], v[158:161], v[190:193], v[92:95]
	v_mfma_f32_16x16x32_bf16 v[84:87], v[166:169], v[190:193], v[84:87]
	v_mfma_f32_16x16x32_bf16 v[68:71], v[166:169], v[202:205], v[68:71]
	v_mfma_f32_16x16x32_bf16 v[76:79], v[158:161], v[202:205], v[76:79]
	v_mfma_f32_16x16x32_bf16 v[120:123], v[162:165], v[178:181], v[120:123]
	v_mfma_f32_16x16x32_bf16 v[116:119], v[170:173], v[178:181], v[116:119]
	v_mfma_f32_16x16x32_bf16 v[100:103], v[170:173], v[186:189], v[100:103]
	v_mfma_f32_16x16x32_bf16 v[108:111], v[162:165], v[186:189], v[108:111]
	v_mfma_f32_16x16x32_bf16 v[92:95], v[162:165], v[198:201], v[92:95]
	v_mfma_f32_16x16x32_bf16 v[84:87], v[170:173], v[198:201], v[84:87]
	v_mfma_f32_16x16x32_bf16 v[68:71], v[170:173], v[206:209], v[68:71]
	v_mfma_f32_16x16x32_bf16 v[76:79], v[162:165], v[206:209], v[76:79]
	s_barrier
	s_add_i32 vcc_lo, s41, s36
	v_lshl_add_u64 v[144:145], s[28:29], 0, v[130:131]
	s_mov_b32 m0, vcc_lo
	ds_read_b128 v[210:213], v153
	ds_read_b128 v[214:217], v153 offset:1024
	ds_read_b128 v[218:221], v153 offset:2048
	ds_read_b128 v[222:225], v153 offset:3072
	global_load_lds_dwordx4 v[144:145], off
	v_lshl_add_u64 v[194:195], s[28:29], 0, v[134:135]
	s_add_i32 m0, vcc_lo, 0x2000
	s_nop 0
	global_load_lds_dwordx4 v[194:195], off
	s_barrier
	s_waitcnt lgkmcnt(0)
	v_mfma_f32_16x16x32_bf16 v[124:127], v[210:213], v[174:177], v[124:127]
	v_mfma_f32_16x16x32_bf16 v[112:115], v[218:221], v[174:177], v[112:115]
	v_mfma_f32_16x16x32_bf16 v[96:99], v[218:221], v[182:185], v[96:99]
	v_mfma_f32_16x16x32_bf16 v[104:107], v[210:213], v[182:185], v[104:107]
	v_mfma_f32_16x16x32_bf16 v[88:91], v[210:213], v[190:193], v[88:91]
	v_mfma_f32_16x16x32_bf16 v[80:83], v[218:221], v[190:193], v[80:83]
	v_mfma_f32_16x16x32_bf16 v[64:67], v[218:221], v[202:205], v[64:67]
	v_mfma_f32_16x16x32_bf16 v[72:75], v[210:213], v[202:205], v[72:75]
	v_mfma_f32_16x16x32_bf16 v[124:127], v[214:217], v[178:181], v[124:127]
	v_mfma_f32_16x16x32_bf16 v[112:115], v[222:225], v[178:181], v[112:115]
	v_mfma_f32_16x16x32_bf16 v[96:99], v[222:225], v[186:189], v[96:99]
	v_mfma_f32_16x16x32_bf16 v[104:107], v[214:217], v[186:189], v[104:107]
	v_mfma_f32_16x16x32_bf16 v[88:91], v[214:217], v[198:201], v[88:91]
	v_mfma_f32_16x16x32_bf16 v[80:83], v[222:225], v[198:201], v[80:83]
	v_mfma_f32_16x16x32_bf16 v[64:67], v[222:225], v[206:209], v[64:67]
	v_mfma_f32_16x16x32_bf16 v[72:75], v[214:217], v[206:209], v[72:75]
	s_mov_b32 m0, s37
	v_lshl_add_u64 v[226:227], s[26:27], 0, v[128:129]
	s_barrier
	ds_read_b128 v[174:177], v152 offset:16384
	ds_read_b128 v[178:181], v152 offset:17408
	ds_read_b128 v[182:185], v152 offset:18432
	ds_read_b128 v[186:189], v152 offset:19456
	ds_read_b128 v[190:193], v152 offset:20480
	ds_read_b128 v[198:201], v152 offset:21504
	ds_read_b128 v[202:205], v152 offset:22528
	ds_read_b128 v[206:209], v152 offset:23552
	global_load_lds_dwordx4 v[226:227], off
	v_lshl_add_u64 v[228:229], s[26:27], 0, v[132:133]
	s_mov_b32 m0, s48
	s_nop 0
	global_load_lds_dwordx4 v[228:229], off
	s_barrier
	s_waitcnt lgkmcnt(0)
	v_mfma_f32_16x16x32_bf16 v[60:63], v[158:161], v[174:177], v[60:63]
	v_mfma_f32_16x16x32_bf16 v[56:59], v[166:169], v[174:177], v[56:59]
	v_mfma_f32_16x16x32_bf16 v[40:43], v[166:169], v[182:185], v[40:43]
	v_mfma_f32_16x16x32_bf16 v[44:47], v[158:161], v[182:185], v[44:47]
	v_mfma_f32_16x16x32_bf16 v[28:31], v[158:161], v[190:193], v[28:31]
	v_mfma_f32_16x16x32_bf16 v[24:27], v[166:169], v[190:193], v[24:27]
	v_mfma_f32_16x16x32_bf16 v[8:11], v[166:169], v[202:205], v[8:11]
	v_mfma_f32_16x16x32_bf16 v[12:15], v[158:161], v[202:205], v[12:15]
	v_mfma_f32_16x16x32_bf16 v[60:63], v[162:165], v[178:181], v[60:63]
	v_mfma_f32_16x16x32_bf16 v[56:59], v[170:173], v[178:181], v[56:59]
	v_mfma_f32_16x16x32_bf16 v[40:43], v[170:173], v[186:189], v[40:43]
	v_mfma_f32_16x16x32_bf16 v[44:47], v[162:165], v[186:189], v[44:47]
	v_mfma_f32_16x16x32_bf16 v[28:31], v[162:165], v[198:201], v[28:31]
	v_mfma_f32_16x16x32_bf16 v[24:27], v[170:173], v[198:201], v[24:27]
	v_mfma_f32_16x16x32_bf16 v[8:11], v[170:173], v[206:209], v[8:11]
	v_mfma_f32_16x16x32_bf16 v[12:15], v[162:165], v[206:209], v[12:15]
	s_barrier
; #define PG8_STAGE(bufoff, gbase, voff) do { _Pragma("unroll") for (int _i = 0; _i < 2; ++_i) \
;         __builtin_amdgcn_global_load_lds((const unsigned*)((const char*)(gbase) + (voff)[_i]), (LAS unsigned*)(lds + (bufoff) + ldsw + _i * 8192), 16, 0, 0); } while (0)
; #define PG8_LDA(dst, b, h) do { _Pragma("unroll") for (int m = 0; m < 4; ++m) _Pragma("unroll") for (int k = 0; k < 2; ++k) dst[m][k] = *(const LAS bf16x8*)(lds + PG8_SA(b, h) + aoff + m * 2048 + k * 1024); } while (0)
; #define PG8_LDB(dst, b, h) do { _Pragma("unroll") for (int n = 0; n < 2; ++n) _Pragma("unroll") for (int k = 0; k < 2; ++k) dst[n][k] = *(const LAS bf16x8*)(lds + PG8_SB(b, h) + boff + n * 2048 + k * 1024); } while (0)
; #define PG8_MMA(ai, bj, At, Bt) do { __builtin_amdgcn_s_setprio(1); _Pragma("unroll") for (int m = 0; m < 4; ++m) _Pragma("unroll") for (int n = 0; n < 2; ++n) _Pragma("unroll") for (int k = 0; k < 2; ++k) \
;         acc[ai][bj][m][n] = __builtin_amdgcn_mfma_f32_16x16x32_bf16(Bt[n][k], At[m][k], acc[ai][bj][m][n], 0, 0, 0); __builtin_amdgcn_s_setprio(0); } while (0)
; #define PG8_WAIT_V(n) asm volatile("s_waitcnt vmcnt(" #n ")" ::: "memory")
; #define PG8_WAIT_L(n) asm volatile("s_waitcnt lgkmcnt(" #n ")" ::: "memory")
; #define PG8_BAR __builtin_amdgcn_s_barrier()
; #define PG8_SCHED __builtin_amdgcn_sched_barrier(0)
; template <class Epi>
; DEVI void gemm_phase(LAS unsigned char* lds, const bf16_t* gA, const bf16_t* gBt, const int lda, const int ldb, const int K, const StaticOrder S_, const Epi E) {
;     ...
;             PG8_STAGE(PG8_SB(0, 1), b2 + hstepB, voffB);
;             PG8_WAIT_V(6); PG8_BAR; PG8_MMA(1, 1, At, B1); PG8_BAR;
;             PG8_LDB(B0, 1, 0); PG8_SCHED; PG8_LDA(At, 1, 0); PG8_STAGE(PG8_SA(0, 1), a2 + hstepA, voffA);
;             PG8_WAIT_L(8); PG8_BAR; PG8_WAIT_L(0); PG8_MMA(0, 0, At, B0); PG8_BAR; PG8_SCHED;
;             PG8_LDB(B1, 1, 1); PG8_STAGE(PG8_SB(1, 0), b3, voffB);
	s_add_u32 s28, s28, s8
	s_addc_u32 s29, s29, s9
	s_add_i32 vcc_lo, s0, s36
	v_lshl_add_u64 v[230:231], s[28:29], 0, v[130:131]
	s_mov_b32 m0, vcc_lo
	v_lshl_add_u64 v[232:233], s[28:29], 0, v[134:135]
	global_load_lds_dwordx4 v[230:231], off
	s_add_i32 m0, vcc_lo, 0x2000
	s_nop 0
	global_load_lds_dwordx4 v[232:233], off
	s_waitcnt vmcnt(6)
	s_barrier
	v_mfma_f32_16x16x32_bf16 v[52:55], v[210:213], v[174:177], v[52:55]
	v_mfma_f32_16x16x32_bf16 v[48:51], v[218:221], v[174:177], v[48:51]
	v_mfma_f32_16x16x32_bf16 v[32:35], v[218:221], v[182:185], v[32:35]
	v_mfma_f32_16x16x32_bf16 v[36:39], v[210:213], v[182:185], v[36:39]
	v_mfma_f32_16x16x32_bf16 v[20:23], v[210:213], v[190:193], v[20:23]
	v_mfma_f32_16x16x32_bf16 v[16:19], v[218:221], v[190:193], v[16:19]
	v_mfma_f32_16x16x32_bf16 v[0:3], v[218:221], v[202:205], v[0:3]
	v_mfma_f32_16x16x32_bf16 v[4:7], v[210:213], v[202:205], v[4:7]
	v_mfma_f32_16x16x32_bf16 v[52:55], v[214:217], v[178:181], v[52:55]
	v_mfma_f32_16x16x32_bf16 v[48:51], v[222:225], v[178:181], v[48:51]
	v_mfma_f32_16x16x32_bf16 v[32:35], v[222:225], v[186:189], v[32:35]
	v_mfma_f32_16x16x32_bf16 v[36:39], v[214:217], v[186:189], v[36:39]
	v_mfma_f32_16x16x32_bf16 v[20:23], v[214:217], v[198:201], v[20:23]
	v_mfma_f32_16x16x32_bf16 v[16:19], v[222:225], v[198:201], v[16:19]
	v_mfma_f32_16x16x32_bf16 v[0:3], v[222:225], v[206:209], v[0:3]
	v_mfma_f32_16x16x32_bf16 v[4:7], v[214:217], v[206:209], v[4:7]
	s_barrier
	ds_read_b128 v[158:161], v154
	ds_read_b128 v[162:165], v154 offset:1024
	ds_read_b128 v[166:169], v154 offset:2048
	ds_read_b128 v[170:173], v154 offset:3072
	s_add_u32 s26, s26, s2
	s_addc_u32 s27, s27, s3
	s_mov_b32 m0, s49
	v_lshl_add_u64 v[210:211], s[26:27], 0, v[128:129]
	ds_read_b128 v[174:177], v152 offset:32768
	ds_read_b128 v[178:181], v152 offset:33792
	ds_read_b128 v[182:185], v152 offset:34816
	ds_read_b128 v[186:189], v152 offset:35840
	ds_read_b128 v[190:193], v152 offset:36864
	ds_read_b128 v[198:201], v152 offset:37888
	ds_read_b128 v[202:205], v152 offset:38912
	ds_read_b128 v[206:209], v152 offset:39936
	global_load_lds_dwordx4 v[210:211], off
	v_lshl_add_u64 v[210:211], s[26:27], 0, v[132:133]
	s_mov_b32 m0, s51
	s_nop 0
	global_load_lds_dwordx4 v[210:211], off
	s_waitcnt lgkmcnt(8)
	s_barrier
	s_waitcnt lgkmcnt(0)
	v_mfma_f32_16x16x32_bf16 v[120:123], v[158:161], v[174:177], v[120:123]
	v_mfma_f32_16x16x32_bf16 v[116:119], v[166:169], v[174:177], v[116:119]
	v_mfma_f32_16x16x32_bf16 v[100:103], v[166:169], v[182:185], v[100:103]
	v_mfma_f32_16x16x32_bf16 v[108:111], v[158:161], v[182:185], v[108:111]
	v_mfma_f32_16x16x32_bf16 v[92:95], v[158:161], v[190:193], v[92:95]
	v_mfma_f32_16x16x32_bf16 v[84:87], v[166:169], v[190:193], v[84:87]
	v_mfma_f32_16x16x32_bf16 v[68:71], v[166:169], v[202:205], v[68:71]
	v_mfma_f32_16x16x32_bf16 v[76:79], v[158:161], v[202:205], v[76:79]
	v_mfma_f32_16x16x32_bf16 v[120:123], v[162:165], v[178:181], v[120:123]
	v_mfma_f32_16x16x32_bf16 v[116:119], v[170:173], v[178:181], v[116:119]
	v_mfma_f32_16x16x32_bf16 v[100:103], v[170:173], v[186:189], v[100:103]
	v_mfma_f32_16x16x32_bf16 v[108:111], v[162:165], v[186:189], v[108:111]
	v_mfma_f32_16x16x32_bf16 v[92:95], v[162:165], v[198:201], v[92:95]
	v_mfma_f32_16x16x32_bf16 v[84:87], v[170:173], v[198:201], v[84:87]
	v_mfma_f32_16x16x32_bf16 v[68:71], v[170:173], v[206:209], v[68:71]
	v_mfma_f32_16x16x32_bf16 v[76:79], v[162:165], v[206:209], v[76:79]
	s_barrier
	s_add_i32 s26, s1, s36
	v_lshl_add_u64 v[144:145], v[144:145], 0, s[20:21]
	s_mov_b32 m0, s26
	ds_read_b128 v[210:213], v155
	ds_read_b128 v[214:217], v155 offset:1024
	ds_read_b128 v[218:221], v155 offset:2048
	ds_read_b128 v[222:225], v155 offset:3072
	global_load_lds_dwordx4 v[144:145], off
	v_lshl_add_u64 v[144:145], v[194:195], 0, s[20:21]
	s_add_i32 m0, s26, 0x2000
	s_nop 0
	global_load_lds_dwordx4 v[144:145], off
	s_barrier
; #define PG8_STAGE(bufoff, gbase, voff) do { _Pragma("unroll") for (int _i = 0; _i < 2; ++_i) \
;         __builtin_amdgcn_global_load_lds((const unsigned*)((const char*)(gbase) + (voff)[_i]), (LAS unsigned*)(lds + (bufoff) + ldsw + _i * 8192), 16, 0, 0); } while (0)
; #define PG8_LDA(dst, b, h) do { _Pragma("unroll") for (int m = 0; m < 4; ++m) _Pragma("unroll") for (int k = 0; k < 2; ++k) dst[m][k] = *(const LAS bf16x8*)(lds + PG8_SA(b, h) + aoff + m * 2048 + k * 1024); } while (0)
; #define PG8_MMA(ai, bj, At, Bt) do { __builtin_amdgcn_s_setprio(1); _Pragma("unroll") for (int m = 0; m < 4; ++m) _Pragma("unroll") for (int n = 0; n < 2; ++n) _Pragma("unroll") for (int k = 0; k < 2; ++k) \
;         acc[ai][bj][m][n] = __builtin_amdgcn_mfma_f32_16x16x32_bf16(Bt[n][k], At[m][k], acc[ai][bj][m][n], 0, 0, 0); __builtin_amdgcn_s_setprio(0); } while (0)
; #define PG8_WAIT_V(n) asm volatile("s_waitcnt vmcnt(" #n ")" ::: "memory")
; #define PG8_WAIT_L(n) asm volatile("s_waitcnt lgkmcnt(" #n ")" ::: "memory")
; #define PG8_BAR __builtin_amdgcn_s_barrier()
; #define PG8_SCHED __builtin_amdgcn_sched_barrier(0)
; template <class Epi>
; DEVI void gemm_phase(LAS unsigned char* lds, const bf16_t* gA, const bf16_t* gBt, const int lda, const int ldb, const int K, const StaticOrder S_, const Epi E) {
;     ...
;             PG8_BAR; PG8_WAIT_L(0); PG8_MMA(0, 1, At, B1); PG8_BAR;
;             PG8_LDA(At, 1, 1); PG8_STAGE(PG8_SA(1, 0), a3, voffA);
;             PG8_BAR; PG8_WAIT_L(0); PG8_MMA(1, 0, At, B0); PG8_BAR; PG8_SCHED;
;             PG8_STAGE(PG8_SB(1, 1), b3 + hstepB, voffB);
;             PG8_WAIT_V(6); PG8_BAR; PG8_MMA(1, 1, At, B1); PG8_BAR;
	s_waitcnt lgkmcnt(0)
	v_mfma_f32_16x16x32_bf16 v[124:127], v[210:213], v[174:177], v[124:127]
	v_mfma_f32_16x16x32_bf16 v[112:115], v[218:221], v[174:177], v[112:115]
	v_mfma_f32_16x16x32_bf16 v[96:99], v[218:221], v[182:185], v[96:99]
	v_mfma_f32_16x16x32_bf16 v[104:107], v[210:213], v[182:185], v[104:107]
	v_mfma_f32_16x16x32_bf16 v[88:91], v[210:213], v[190:193], v[88:91]
	v_mfma_f32_16x16x32_bf16 v[80:83], v[218:221], v[190:193], v[80:83]
	v_mfma_f32_16x16x32_bf16 v[64:67], v[218:221], v[202:205], v[64:67]
	v_mfma_f32_16x16x32_bf16 v[72:75], v[210:213], v[202:205], v[72:75]
	v_mfma_f32_16x16x32_bf16 v[124:127], v[214:217], v[178:181], v[124:127]
	v_mfma_f32_16x16x32_bf16 v[112:115], v[222:225], v[178:181], v[112:115]
	v_mfma_f32_16x16x32_bf16 v[96:99], v[222:225], v[186:189], v[96:99]
	v_mfma_f32_16x16x32_bf16 v[104:107], v[214:217], v[186:189], v[104:107]
	v_mfma_f32_16x16x32_bf16 v[88:91], v[214:217], v[198:201], v[88:91]
	v_mfma_f32_16x16x32_bf16 v[80:83], v[222:225], v[198:201], v[80:83]
	v_mfma_f32_16x16x32_bf16 v[64:67], v[222:225], v[206:209], v[64:67]
	v_mfma_f32_16x16x32_bf16 v[72:75], v[214:217], v[206:209], v[72:75]
	s_mov_b32 m0, s50
	v_lshl_add_u64 v[144:145], v[226:227], 0, s[20:21]
	s_barrier
	ds_read_b128 v[174:177], v152 offset:49152
	ds_read_b128 v[178:181], v152 offset:50176
	ds_read_b128 v[182:185], v152 offset:51200
	ds_read_b128 v[186:189], v152 offset:52224
	ds_read_b128 v[190:193], v152 offset:53248
	ds_read_b128 v[198:201], v152 offset:54272
	ds_read_b128 v[202:205], v152 offset:55296
	ds_read_b128 v[206:209], v152 offset:56320
	global_load_lds_dwordx4 v[144:145], off
	v_lshl_add_u64 v[144:145], v[228:229], 0, s[20:21]
	s_mov_b32 m0, s60
	s_nop 0
	global_load_lds_dwordx4 v[144:145], off
	s_barrier
	s_waitcnt lgkmcnt(0)
	v_mfma_f32_16x16x32_bf16 v[60:63], v[158:161], v[174:177], v[60:63]
	v_mfma_f32_16x16x32_bf16 v[56:59], v[166:169], v[174:177], v[56:59]
	v_mfma_f32_16x16x32_bf16 v[40:43], v[166:169], v[182:185], v[40:43]
	v_mfma_f32_16x16x32_bf16 v[44:47], v[158:161], v[182:185], v[44:47]
	v_mfma_f32_16x16x32_bf16 v[28:31], v[158:161], v[190:193], v[28:31]
	v_mfma_f32_16x16x32_bf16 v[24:27], v[166:169], v[190:193], v[24:27]
	v_mfma_f32_16x16x32_bf16 v[8:11], v[166:169], v[202:205], v[8:11]
	v_mfma_f32_16x16x32_bf16 v[12:15], v[158:161], v[202:205], v[12:15]
	v_mfma_f32_16x16x32_bf16 v[60:63], v[162:165], v[178:181], v[60:63]
	v_mfma_f32_16x16x32_bf16 v[56:59], v[170:173], v[178:181], v[56:59]
	v_mfma_f32_16x16x32_bf16 v[40:43], v[170:173], v[186:189], v[40:43]
	v_mfma_f32_16x16x32_bf16 v[44:47], v[162:165], v[186:189], v[44:47]
	v_mfma_f32_16x16x32_bf16 v[28:31], v[162:165], v[198:201], v[28:31]
	v_mfma_f32_16x16x32_bf16 v[24:27], v[170:173], v[198:201], v[24:27]
	v_mfma_f32_16x16x32_bf16 v[8:11], v[170:173], v[206:209], v[8:11]
	v_mfma_f32_16x16x32_bf16 v[12:15], v[162:165], v[206:209], v[12:15]
	s_barrier
	s_add_i32 s26, s31, s36
	v_lshl_add_u64 v[144:145], v[230:231], 0, s[20:21]
	s_mov_b32 m0, s26
	s_nop 0
	global_load_lds_dwordx4 v[144:145], off
	v_lshl_add_u64 v[144:145], v[232:233], 0, s[20:21]
	s_add_i32 m0, s26, 0x2000
	s_nop 0
	global_load_lds_dwordx4 v[144:145], off
	s_waitcnt vmcnt(6)
	s_barrier
	v_mfma_f32_16x16x32_bf16 v[52:55], v[210:213], v[174:177], v[52:55]
	v_mfma_f32_16x16x32_bf16 v[48:51], v[218:221], v[174:177], v[48:51]
	v_mfma_f32_16x16x32_bf16 v[32:35], v[218:221], v[182:185], v[32:35]
	v_mfma_f32_16x16x32_bf16 v[36:39], v[210:213], v[182:185], v[36:39]
	v_mfma_f32_16x16x32_bf16 v[20:23], v[210:213], v[190:193], v[20:23]
	v_mfma_f32_16x16x32_bf16 v[16:19], v[218:221], v[190:193], v[16:19]
	v_mfma_f32_16x16x32_bf16 v[0:3], v[218:221], v[202:205], v[0:3]
	v_mfma_f32_16x16x32_bf16 v[4:7], v[210:213], v[202:205], v[4:7]
	v_mfma_f32_16x16x32_bf16 v[52:55], v[214:217], v[178:181], v[52:55]
	v_mfma_f32_16x16x32_bf16 v[48:51], v[222:225], v[178:181], v[48:51]
	v_mfma_f32_16x16x32_bf16 v[32:35], v[222:225], v[186:189], v[32:35]
	v_mfma_f32_16x16x32_bf16 v[36:39], v[214:217], v[186:189], v[36:39]
	v_mfma_f32_16x16x32_bf16 v[20:23], v[214:217], v[198:201], v[20:23]
	v_mfma_f32_16x16x32_bf16 v[16:19], v[222:225], v[198:201], v[16:19]
	v_mfma_f32_16x16x32_bf16 v[0:3], v[222:225], v[206:209], v[0:3]
	v_mfma_f32_16x16x32_bf16 v[4:7], v[214:217], v[206:209], v[4:7]
	s_add_u32 s24, s24, 0x100
	s_addc_u32 s25, s25, 0
	s_add_u32 s77, s77, 0x100
	s_addc_u32 s78, s78, 0
	s_cmp_ge_i32 s79, s61
	s_mov_b32 s26, s79
	s_barrier
	s_cbranch_scc0 .LBB0_259

; #define PG8_STAGE(bufoff, gbase, voff) do { _Pragma("unroll") for (int _i = 0; _i < 2; ++_i) \
;         __builtin_amdgcn_global_load_lds((const unsigned*)((const char*)(gbase) + (voff)[_i]), (LAS unsigned*)(lds + (bufoff) + ldsw + _i * 8192), 16, 0, 0); } while (0)
; #define PG8_LDA(dst, b, h) do { _Pragma("unroll") for (int m = 0; m < 4; ++m) _Pragma("unroll") for (int k = 0; k < 2; ++k) dst[m][k] = *(const LAS bf16x8*)(lds + PG8_SA(b, h) + aoff + m * 2048 + k * 1024); } while (0)
; #define PG8_LDB(dst, b, h) do { _Pragma("unroll") for (int n = 0; n < 2; ++n) _Pragma("unroll") for (int k = 0; k < 2; ++k) dst[n][k] = *(const LAS bf16x8*)(lds + PG8_SB(b, h) + boff + n * 2048 + k * 1024); } while (0)
; #define PG8_MMA(ai, bj, At, Bt) do { __builtin_amdgcn_s_setprio(1); _Pragma("unroll") for (int m = 0; m < 4; ++m) _Pragma("unroll") for (int n = 0; n < 2; ++n) _Pragma("unroll") for (int k = 0; k < 2; ++k) \
;         acc[ai][bj][m][n] = __builtin_amdgcn_mfma_f32_16x16x32_bf16(Bt[n][k], At[m][k], acc[ai][bj][m][n], 0, 0, 0); __builtin_amdgcn_s_setprio(0); } while (0)
; #define PG8_WAIT_L(n) asm volatile("s_waitcnt lgkmcnt(" #n ")" ::: "memory")
; #define PG8_BAR __builtin_amdgcn_s_barrier()
; #define PG8_SCHED __builtin_amdgcn_sched_barrier(0)
; template <class Epi>
; DEVI void gemm_phase(LAS unsigned char* lds, const bf16_t* gA, const bf16_t* gBt, const int lda, const int ldb, const int K, const StaticOrder S_, const Epi E) {
;     ...
;             const char* a1 = cA + (size_t)(t + 1) * kstep;
;             const char* a2 = last ? nA : cA + (size_t)(t + 2) * kstep; const char* b2 = last ? nB : cB + (size_t)(t + 2) * kstep;
;             const char* a3 = a2 + kstep; const char* b3 = b2 + kstep;
;             PG8_LDB(B0, 0, 0); PG8_SCHED; PG8_LDA(At, 0, 0); PG8_STAGE(PG8_SA(1, 1), a1 + hstepA, voffA);
;             PG8_WAIT_L(8); PG8_BAR; PG8_WAIT_L(0); PG8_MMA(0, 0, At, B0); PG8_BAR; PG8_SCHED;
;             PG8_LDB(B1, 0, 1); PG8_STAGE(PG8_SB(0, 0), b2, voffB);
;             PG8_BAR; PG8_WAIT_L(0); PG8_MMA(0, 1, At, B1); PG8_BAR;
;             PG8_LDA(At, 0, 1); PG8_STAGE(PG8_SA(0, 0), a2, voffA);
;             PG8_BAR; PG8_WAIT_L(0); PG8_MMA(1, 0, At, B0); PG8_BAR; PG8_SCHED;
.LBB0_388:
	ds_read_b128 v[128:131], v201
	ds_read_b128 v[132:135], v201 offset:1024
	ds_read_b128 v[136:139], v201 offset:2048
	ds_read_b128 v[140:143], v201 offset:3072
	s_add_i32 s74, s16, 2
	s_add_u32 s40, s14, 0x80
	s_addc_u32 s17, s15, 0
	s_cmp_eq_u32 s29, s16
	s_cselect_b32 s16, s12, s40
	s_cselect_b32 s17, s13, s17
	s_cselect_b32 s41, s43, s73
	s_cselect_b32 s40, s42, s72
	v_lshl_add_u64 v[164:165], s[14:15], 0, v[174:175]
	s_add_i32 m0, s24, 0xc000
	ds_read_b128 v[144:147], v202
	ds_read_b128 v[148:151], v202 offset:1024
	ds_read_b128 v[152:155], v202 offset:2048
	ds_read_b128 v[156:159], v202 offset:3072
	ds_read_b128 v[160:163], v202 offset:4096
	ds_read_b128 v[180:183], v202 offset:5120
	ds_read_b128 v[184:187], v202 offset:6144
	ds_read_b128 v[188:191], v202 offset:7168
	global_load_lds_dwordx4 v[164:165], off
	v_lshl_add_u64 v[164:165], s[14:15], 0, v[176:177]
	s_add_i32 m0, s24, 0xe000
	s_nop 0
	global_load_lds_dwordx4 v[164:165], off
	s_waitcnt lgkmcnt(8)
	s_barrier
	s_waitcnt lgkmcnt(0)
	v_mfma_f32_16x16x32_bf16 v[124:127], v[128:131], v[144:147], v[124:127]
	v_mfma_f32_16x16x32_bf16 v[120:123], v[136:139], v[144:147], v[120:123]
	v_mfma_f32_16x16x32_bf16 v[104:107], v[136:139], v[152:155], v[104:107]
	v_mfma_f32_16x16x32_bf16 v[108:111], v[128:131], v[152:155], v[108:111]
	v_mfma_f32_16x16x32_bf16 v[92:95], v[128:131], v[160:163], v[92:95]
	v_mfma_f32_16x16x32_bf16 v[88:91], v[136:139], v[160:163], v[88:91]
	v_mfma_f32_16x16x32_bf16 v[72:75], v[136:139], v[184:187], v[72:75]
	v_mfma_f32_16x16x32_bf16 v[76:79], v[128:131], v[184:187], v[76:79]
	v_mfma_f32_16x16x32_bf16 v[124:127], v[132:135], v[148:151], v[124:127]
	v_mfma_f32_16x16x32_bf16 v[120:123], v[140:143], v[148:151], v[120:123]
	v_mfma_f32_16x16x32_bf16 v[104:107], v[140:143], v[156:159], v[104:107]
	v_mfma_f32_16x16x32_bf16 v[108:111], v[132:135], v[156:159], v[108:111]
	v_mfma_f32_16x16x32_bf16 v[92:95], v[132:135], v[180:183], v[92:95]
	v_mfma_f32_16x16x32_bf16 v[88:91], v[140:143], v[180:183], v[88:91]
	v_mfma_f32_16x16x32_bf16 v[72:75], v[140:143], v[188:191], v[72:75]
	v_mfma_f32_16x16x32_bf16 v[76:79], v[132:135], v[188:191], v[76:79]
	s_barrier
	s_add_i32 s75, s97, s22
	v_lshl_add_u64 v[164:165], s[40:41], 0, v[168:169]
	s_mov_b32 m0, s75
	ds_read_b128 v[192:195], v203
	ds_read_b128 v[206:209], v203 offset:1024
	ds_read_b128 v[210:213], v203 offset:2048
	ds_read_b128 v[214:217], v203 offset:3072
	global_load_lds_dwordx4 v[164:165], off
	v_lshl_add_u64 v[218:219], s[40:41], 0, v[172:173]
	s_add_i32 m0, s75, 0x2000
	s_nop 0
	global_load_lds_dwordx4 v[218:219], off
	s_barrier
	s_waitcnt lgkmcnt(0)
	v_mfma_f32_16x16x32_bf16 v[116:119], v[192:195], v[144:147], v[116:119]
	v_mfma_f32_16x16x32_bf16 v[112:115], v[210:213], v[144:147], v[112:115]
	v_mfma_f32_16x16x32_bf16 v[96:99], v[210:213], v[152:155], v[96:99]
	v_mfma_f32_16x16x32_bf16 v[100:103], v[192:195], v[152:155], v[100:103]
	v_mfma_f32_16x16x32_bf16 v[84:87], v[192:195], v[160:163], v[84:87]
	v_mfma_f32_16x16x32_bf16 v[80:83], v[210:213], v[160:163], v[80:83]
	v_mfma_f32_16x16x32_bf16 v[64:67], v[210:213], v[184:187], v[64:67]
	v_mfma_f32_16x16x32_bf16 v[68:71], v[192:195], v[184:187], v[68:71]
	v_mfma_f32_16x16x32_bf16 v[116:119], v[206:209], v[148:151], v[116:119]
	v_mfma_f32_16x16x32_bf16 v[112:115], v[214:217], v[148:151], v[112:115]
	v_mfma_f32_16x16x32_bf16 v[96:99], v[214:217], v[156:159], v[96:99]
	v_mfma_f32_16x16x32_bf16 v[100:103], v[206:209], v[156:159], v[100:103]
	v_mfma_f32_16x16x32_bf16 v[84:87], v[206:209], v[180:183], v[84:87]
	v_mfma_f32_16x16x32_bf16 v[80:83], v[214:217], v[180:183], v[80:83]
	v_mfma_f32_16x16x32_bf16 v[64:67], v[214:217], v[188:191], v[64:67]
	v_mfma_f32_16x16x32_bf16 v[68:71], v[206:209], v[188:191], v[68:71]
	s_mov_b32 m0, s24
	v_lshl_add_u64 v[220:221], s[16:17], 0, v[166:167]
	s_barrier
	ds_read_b128 v[144:147], v202 offset:16384
	ds_read_b128 v[148:151], v202 offset:17408
	ds_read_b128 v[152:155], v202 offset:18432
	ds_read_b128 v[156:159], v202 offset:19456
	ds_read_b128 v[160:163], v202 offset:20480
	ds_read_b128 v[180:183], v202 offset:21504
	ds_read_b128 v[184:187], v202 offset:22528
	ds_read_b128 v[188:191], v202 offset:23552
	global_load_lds_dwordx4 v[220:221], off
	v_lshl_add_u64 v[222:223], s[16:17], 0, v[170:171]
	s_mov_b32 m0, s25
	s_nop 0
	global_load_lds_dwordx4 v[222:223], off
	s_barrier
	s_waitcnt lgkmcnt(0)
	v_mfma_f32_16x16x32_bf16 v[60:63], v[128:131], v[144:147], v[60:63]
	v_mfma_f32_16x16x32_bf16 v[56:59], v[136:139], v[144:147], v[56:59]
	v_mfma_f32_16x16x32_bf16 v[40:43], v[136:139], v[152:155], v[40:43]
	v_mfma_f32_16x16x32_bf16 v[44:47], v[128:131], v[152:155], v[44:47]
	v_mfma_f32_16x16x32_bf16 v[28:31], v[128:131], v[160:163], v[28:31]
	v_mfma_f32_16x16x32_bf16 v[24:27], v[136:139], v[160:163], v[24:27]
	v_mfma_f32_16x16x32_bf16 v[8:11], v[136:139], v[184:187], v[8:11]
	v_mfma_f32_16x16x32_bf16 v[12:15], v[128:131], v[184:187], v[12:15]
	v_mfma_f32_16x16x32_bf16 v[60:63], v[132:135], v[148:151], v[60:63]
	v_mfma_f32_16x16x32_bf16 v[56:59], v[140:143], v[148:151], v[56:59]
	v_mfma_f32_16x16x32_bf16 v[40:43], v[140:143], v[156:159], v[40:43]
	v_mfma_f32_16x16x32_bf16 v[44:47], v[132:135], v[156:159], v[44:47]
	v_mfma_f32_16x16x32_bf16 v[28:31], v[132:135], v[180:183], v[28:31]
	v_mfma_f32_16x16x32_bf16 v[24:27], v[140:143], v[180:183], v[24:27]
	v_mfma_f32_16x16x32_bf16 v[8:11], v[140:143], v[188:191], v[8:11]
	v_mfma_f32_16x16x32_bf16 v[12:15], v[132:135], v[188:191], v[12:15]
	s_barrier
; #define PG8_STAGE(bufoff, gbase, voff) do { _Pragma("unroll") for (int _i = 0; _i < 2; ++_i) \
;         __builtin_amdgcn_global_load_lds((const unsigned*)((const char*)(gbase) + (voff)[_i]), (LAS unsigned*)(lds + (bufoff) + ldsw + _i * 8192), 16, 0, 0); } while (0)
; #define PG8_LDA(dst, b, h) do { _Pragma("unroll") for (int m = 0; m < 4; ++m) _Pragma("unroll") for (int k = 0; k < 2; ++k) dst[m][k] = *(const LAS bf16x8*)(lds + PG8_SA(b, h) + aoff + m * 2048 + k * 1024); } while (0)
; #define PG8_LDB(dst, b, h) do { _Pragma("unroll") for (int n = 0; n < 2; ++n) _Pragma("unroll") for (int k = 0; k < 2; ++k) dst[n][k] = *(const LAS bf16x8*)(lds + PG8_SB(b, h) + boff + n * 2048 + k * 1024); } while (0)
; #define PG8_MMA(ai, bj, At, Bt) do { __builtin_amdgcn_s_setprio(1); _Pragma("unroll") for (int m = 0; m < 4; ++m) _Pragma("unroll") for (int n = 0; n < 2; ++n) _Pragma("unroll") for (int k = 0; k < 2; ++k) \
;         acc[ai][bj][m][n] = __builtin_amdgcn_mfma_f32_16x16x32_bf16(Bt[n][k], At[m][k], acc[ai][bj][m][n], 0, 0, 0); __builtin_amdgcn_s_setprio(0); } while (0)
; #define PG8_WAIT_V(n) asm volatile("s_waitcnt vmcnt(" #n ")" ::: "memory")
; #define PG8_WAIT_L(n) asm volatile("s_waitcnt lgkmcnt(" #n ")" ::: "memory")
; #define PG8_BAR __builtin_amdgcn_s_barrier()
; #define PG8_SCHED __builtin_amdgcn_sched_barrier(0)
; template <class Epi>
; DEVI void gemm_phase(LAS unsigned char* lds, const bf16_t* gA, const bf16_t* gBt, const int lda, const int ldb, const int K, const StaticOrder S_, const Epi E) {
;     ...
;             PG8_STAGE(PG8_SB(0, 1), b2 + hstepB, voffB);
;             PG8_WAIT_V(6); PG8_BAR; PG8_MMA(1, 1, At, B1); PG8_BAR;
;             PG8_LDB(B0, 1, 0); PG8_SCHED; PG8_LDA(At, 1, 0); PG8_STAGE(PG8_SA(0, 1), a2 + hstepA, voffA);
;             PG8_WAIT_L(8); PG8_BAR; PG8_WAIT_L(0); PG8_MMA(0, 0, At, B0); PG8_BAR; PG8_SCHED;
;             PG8_LDB(B1, 1, 1); PG8_STAGE(PG8_SB(1, 0), b3, voffB);
;             PG8_BAR; PG8_WAIT_L(0); PG8_MMA(0, 1, At, B1); PG8_BAR;
;             PG8_LDA(At, 1, 1); PG8_STAGE(PG8_SA(1, 0), a3, voffA);
;             PG8_BAR; PG8_WAIT_L(0); PG8_MMA(1, 0, At, B0); PG8_BAR; PG8_SCHED;
;             PG8_STAGE(PG8_SB(1, 1), b3 + hstepB, voffB);
	s_add_u32 s40, s40, s0
	s_addc_u32 s41, s41, s1
	s_add_i32 s75, s50, s22
	v_lshl_add_u64 v[224:225], s[40:41], 0, v[168:169]
	s_mov_b32 m0, s75
	v_lshl_add_u64 v[226:227], s[40:41], 0, v[172:173]
	global_load_lds_dwordx4 v[224:225], off
	s_add_i32 m0, s75, 0x2000
	s_nop 0
	global_load_lds_dwordx4 v[226:227], off
	s_waitcnt vmcnt(6)
	s_barrier
	v_mfma_f32_16x16x32_bf16 v[52:55], v[192:195], v[144:147], v[52:55]
	v_mfma_f32_16x16x32_bf16 v[48:51], v[210:213], v[144:147], v[48:51]
	v_mfma_f32_16x16x32_bf16 v[32:35], v[210:213], v[152:155], v[32:35]
	v_mfma_f32_16x16x32_bf16 v[36:39], v[192:195], v[152:155], v[36:39]
	v_mfma_f32_16x16x32_bf16 v[20:23], v[192:195], v[160:163], v[20:23]
	v_mfma_f32_16x16x32_bf16 v[16:19], v[210:213], v[160:163], v[16:19]
	v_mfma_f32_16x16x32_bf16 v[0:3], v[210:213], v[184:187], v[0:3]
	v_mfma_f32_16x16x32_bf16 v[4:7], v[192:195], v[184:187], v[4:7]
	v_mfma_f32_16x16x32_bf16 v[52:55], v[206:209], v[148:151], v[52:55]
	v_mfma_f32_16x16x32_bf16 v[48:51], v[214:217], v[148:151], v[48:51]
	v_mfma_f32_16x16x32_bf16 v[32:35], v[214:217], v[156:159], v[32:35]
	v_mfma_f32_16x16x32_bf16 v[36:39], v[206:209], v[156:159], v[36:39]
	v_mfma_f32_16x16x32_bf16 v[20:23], v[206:209], v[180:183], v[20:23]
	v_mfma_f32_16x16x32_bf16 v[16:19], v[214:217], v[180:183], v[16:19]
	v_mfma_f32_16x16x32_bf16 v[0:3], v[214:217], v[188:191], v[0:3]
	v_mfma_f32_16x16x32_bf16 v[4:7], v[206:209], v[188:191], v[4:7]
	s_add_i32 s40, 0, 0x18000
	v_add_u32_e32 v140, s40, v199
	s_barrier
	ds_read_b128 v[128:131], v140
	ds_read_b128 v[132:135], v140 offset:1024
	ds_read_b128 v[136:139], v140 offset:2048
	ds_read_b128 v[140:143], v140 offset:3072
	s_add_u32 s16, s16, s48
	s_addc_u32 s17, s17, s49
	s_mov_b32 m0, s26
	v_lshl_add_u64 v[192:193], s[16:17], 0, v[166:167]
	ds_read_b128 v[144:147], v202 offset:32768
	ds_read_b128 v[148:151], v202 offset:33792
	ds_read_b128 v[152:155], v202 offset:34816
	ds_read_b128 v[156:159], v202 offset:35840
	ds_read_b128 v[160:163], v202 offset:36864
	ds_read_b128 v[180:183], v202 offset:37888
	ds_read_b128 v[184:187], v202 offset:38912
	ds_read_b128 v[188:191], v202 offset:39936
	global_load_lds_dwordx4 v[192:193], off
	v_lshl_add_u64 v[192:193], s[16:17], 0, v[170:171]
	s_mov_b32 m0, s27
	s_nop 0
	global_load_lds_dwordx4 v[192:193], off
	s_waitcnt lgkmcnt(8)
	s_barrier
	s_waitcnt lgkmcnt(0)
	v_mfma_f32_16x16x32_bf16 v[124:127], v[128:131], v[144:147], v[124:127]
	v_mfma_f32_16x16x32_bf16 v[120:123], v[136:139], v[144:147], v[120:123]
	v_mfma_f32_16x16x32_bf16 v[104:107], v[136:139], v[152:155], v[104:107]
	v_mfma_f32_16x16x32_bf16 v[108:111], v[128:131], v[152:155], v[108:111]
	v_mfma_f32_16x16x32_bf16 v[92:95], v[128:131], v[160:163], v[92:95]
	v_mfma_f32_16x16x32_bf16 v[88:91], v[136:139], v[160:163], v[88:91]
	v_mfma_f32_16x16x32_bf16 v[72:75], v[136:139], v[184:187], v[72:75]
	v_mfma_f32_16x16x32_bf16 v[76:79], v[128:131], v[184:187], v[76:79]
	v_mfma_f32_16x16x32_bf16 v[124:127], v[132:135], v[148:151], v[124:127]
	v_mfma_f32_16x16x32_bf16 v[120:123], v[140:143], v[148:151], v[120:123]
	v_mfma_f32_16x16x32_bf16 v[104:107], v[140:143], v[156:159], v[104:107]
	v_mfma_f32_16x16x32_bf16 v[108:111], v[132:135], v[156:159], v[108:111]
	v_mfma_f32_16x16x32_bf16 v[92:95], v[132:135], v[180:183], v[92:95]
	v_mfma_f32_16x16x32_bf16 v[88:91], v[140:143], v[180:183], v[88:91]
	v_mfma_f32_16x16x32_bf16 v[72:75], v[140:143], v[188:191], v[72:75]
	v_mfma_f32_16x16x32_bf16 v[76:79], v[132:135], v[188:191], v[76:79]
	s_barrier
	s_add_i32 s16, 0, 0x1c000
	s_add_i32 s17, s40, s22
	v_add_u32_e32 v214, s16, v199
	v_lshl_add_u64 v[164:165], v[164:165], 0, s[10:11]
	s_mov_b32 m0, s17
	ds_read_b128 v[192:195], v214
	ds_read_b128 v[206:209], v214 offset:1024
	ds_read_b128 v[210:213], v214 offset:2048
	ds_read_b128 v[214:217], v214 offset:3072
	global_load_lds_dwordx4 v[164:165], off
	v_lshl_add_u64 v[164:165], v[218:219], 0, s[10:11]
	s_add_i32 m0, s17, 0x2000
	s_nop 0
	global_load_lds_dwordx4 v[164:165], off
	s_barrier
; #define PG8_STAGE(bufoff, gbase, voff) do { _Pragma("unroll") for (int _i = 0; _i < 2; ++_i) \
;         __builtin_amdgcn_global_load_lds((const unsigned*)((const char*)(gbase) + (voff)[_i]), (LAS unsigned*)(lds + (bufoff) + ldsw + _i * 8192), 16, 0, 0); } while (0)
; #define PG8_LDA(dst, b, h) do { _Pragma("unroll") for (int m = 0; m < 4; ++m) _Pragma("unroll") for (int k = 0; k < 2; ++k) dst[m][k] = *(const LAS bf16x8*)(lds + PG8_SA(b, h) + aoff + m * 2048 + k * 1024); } while (0)
; #define PG8_MMA(ai, bj, At, Bt) do { __builtin_amdgcn_s_setprio(1); _Pragma("unroll") for (int m = 0; m < 4; ++m) _Pragma("unroll") for (int n = 0; n < 2; ++n) _Pragma("unroll") for (int k = 0; k < 2; ++k) \
;         acc[ai][bj][m][n] = __builtin_amdgcn_mfma_f32_16x16x32_bf16(Bt[n][k], At[m][k], acc[ai][bj][m][n], 0, 0, 0); __builtin_amdgcn_s_setprio(0); } while (0)
; #define PG8_WAIT_V(n) asm volatile("s_waitcnt vmcnt(" #n ")" ::: "memory")
; #define PG8_WAIT_L(n) asm volatile("s_waitcnt lgkmcnt(" #n ")" ::: "memory")
; #define PG8_BAR __builtin_amdgcn_s_barrier()
; #define PG8_SCHED __builtin_amdgcn_sched_barrier(0)
; template <class Epi>
; DEVI void gemm_phase(LAS unsigned char* lds, const bf16_t* gA, const bf16_t* gBt, const int lda, const int ldb, const int K, const StaticOrder S_, const Epi E) {
;     ...
;             PG8_BAR; PG8_WAIT_L(0); PG8_MMA(0, 1, At, B1); PG8_BAR;
;             PG8_LDA(At, 1, 1); PG8_STAGE(PG8_SA(1, 0), a3, voffA);
;             PG8_BAR; PG8_WAIT_L(0); PG8_MMA(1, 0, At, B0); PG8_BAR; PG8_SCHED;
;             PG8_STAGE(PG8_SB(1, 1), b3 + hstepB, voffB);
;             PG8_WAIT_V(6); PG8_BAR; PG8_MMA(1, 1, At, B1); PG8_BAR;
	s_waitcnt lgkmcnt(0)
	v_mfma_f32_16x16x32_bf16 v[116:119], v[192:195], v[144:147], v[116:119]
	v_mfma_f32_16x16x32_bf16 v[112:115], v[210:213], v[144:147], v[112:115]
	v_mfma_f32_16x16x32_bf16 v[96:99], v[210:213], v[152:155], v[96:99]
	v_mfma_f32_16x16x32_bf16 v[100:103], v[192:195], v[152:155], v[100:103]
	v_mfma_f32_16x16x32_bf16 v[84:87], v[192:195], v[160:163], v[84:87]
	v_mfma_f32_16x16x32_bf16 v[80:83], v[210:213], v[160:163], v[80:83]
	v_mfma_f32_16x16x32_bf16 v[64:67], v[210:213], v[184:187], v[64:67]
	v_mfma_f32_16x16x32_bf16 v[68:71], v[192:195], v[184:187], v[68:71]
	v_mfma_f32_16x16x32_bf16 v[116:119], v[206:209], v[148:151], v[116:119]
	v_mfma_f32_16x16x32_bf16 v[112:115], v[214:217], v[148:151], v[112:115]
	v_mfma_f32_16x16x32_bf16 v[96:99], v[214:217], v[156:159], v[96:99]
	v_mfma_f32_16x16x32_bf16 v[100:103], v[206:209], v[156:159], v[100:103]
	v_mfma_f32_16x16x32_bf16 v[84:87], v[206:209], v[180:183], v[84:87]
	v_mfma_f32_16x16x32_bf16 v[80:83], v[214:217], v[180:183], v[80:83]
	v_mfma_f32_16x16x32_bf16 v[64:67], v[214:217], v[188:191], v[64:67]
	v_mfma_f32_16x16x32_bf16 v[68:71], v[206:209], v[188:191], v[68:71]
	s_mov_b32 m0, s18
	v_lshl_add_u64 v[164:165], v[220:221], 0, s[10:11]
	s_barrier
	ds_read_b128 v[144:147], v202 offset:49152
	ds_read_b128 v[148:151], v202 offset:50176
	ds_read_b128 v[152:155], v202 offset:51200
	ds_read_b128 v[156:159], v202 offset:52224
	ds_read_b128 v[160:163], v202 offset:53248
	ds_read_b128 v[180:183], v202 offset:54272
	ds_read_b128 v[184:187], v202 offset:55296
	ds_read_b128 v[188:191], v202 offset:56320
	global_load_lds_dwordx4 v[164:165], off
	v_lshl_add_u64 v[164:165], v[222:223], 0, s[10:11]
	s_mov_b32 m0, s19
	s_nop 0
	global_load_lds_dwordx4 v[164:165], off
	s_barrier
	s_waitcnt lgkmcnt(0)
	v_mfma_f32_16x16x32_bf16 v[60:63], v[128:131], v[144:147], v[60:63]
	v_mfma_f32_16x16x32_bf16 v[56:59], v[136:139], v[144:147], v[56:59]
	v_mfma_f32_16x16x32_bf16 v[40:43], v[136:139], v[152:155], v[40:43]
	v_mfma_f32_16x16x32_bf16 v[44:47], v[128:131], v[152:155], v[44:47]
	v_mfma_f32_16x16x32_bf16 v[28:31], v[128:131], v[160:163], v[28:31]
	v_mfma_f32_16x16x32_bf16 v[24:27], v[136:139], v[160:163], v[24:27]
	v_mfma_f32_16x16x32_bf16 v[8:11], v[136:139], v[184:187], v[8:11]
	v_mfma_f32_16x16x32_bf16 v[12:15], v[128:131], v[184:187], v[12:15]
	v_mfma_f32_16x16x32_bf16 v[60:63], v[132:135], v[148:151], v[60:63]
	v_mfma_f32_16x16x32_bf16 v[56:59], v[140:143], v[148:151], v[56:59]
	v_mfma_f32_16x16x32_bf16 v[40:43], v[140:143], v[156:159], v[40:43]
	v_mfma_f32_16x16x32_bf16 v[44:47], v[132:135], v[156:159], v[44:47]
	v_mfma_f32_16x16x32_bf16 v[28:31], v[132:135], v[180:183], v[28:31]
	v_mfma_f32_16x16x32_bf16 v[24:27], v[140:143], v[180:183], v[24:27]
	v_mfma_f32_16x16x32_bf16 v[8:11], v[140:143], v[188:191], v[8:11]
	v_mfma_f32_16x16x32_bf16 v[12:15], v[132:135], v[188:191], v[12:15]
	s_barrier
	s_add_i32 s16, s16, s22
	v_lshl_add_u64 v[128:129], v[224:225], 0, s[10:11]
	s_mov_b32 m0, s16
	s_nop 0
	global_load_lds_dwordx4 v[128:129], off
	v_lshl_add_u64 v[128:129], v[226:227], 0, s[10:11]
	s_add_i32 m0, s16, 0x2000
	s_nop 0
	global_load_lds_dwordx4 v[128:129], off
	s_waitcnt vmcnt(6)
	s_barrier
	v_mfma_f32_16x16x32_bf16 v[52:55], v[192:195], v[144:147], v[52:55]
	v_mfma_f32_16x16x32_bf16 v[48:51], v[210:213], v[144:147], v[48:51]
	v_mfma_f32_16x16x32_bf16 v[32:35], v[210:213], v[152:155], v[32:35]
	v_mfma_f32_16x16x32_bf16 v[36:39], v[192:195], v[152:155], v[36:39]
	v_mfma_f32_16x16x32_bf16 v[20:23], v[192:195], v[160:163], v[20:23]
	v_mfma_f32_16x16x32_bf16 v[16:19], v[210:213], v[160:163], v[16:19]
	v_mfma_f32_16x16x32_bf16 v[0:3], v[210:213], v[184:187], v[0:3]
	v_mfma_f32_16x16x32_bf16 v[4:7], v[192:195], v[184:187], v[4:7]
	v_mfma_f32_16x16x32_bf16 v[52:55], v[206:209], v[148:151], v[52:55]
	v_mfma_f32_16x16x32_bf16 v[48:51], v[214:217], v[148:151], v[48:51]
	v_mfma_f32_16x16x32_bf16 v[32:35], v[214:217], v[156:159], v[32:35]
	v_mfma_f32_16x16x32_bf16 v[36:39], v[206:209], v[156:159], v[36:39]
	v_mfma_f32_16x16x32_bf16 v[20:23], v[206:209], v[180:183], v[20:23]
	v_mfma_f32_16x16x32_bf16 v[16:19], v[214:217], v[180:183], v[16:19]
	v_mfma_f32_16x16x32_bf16 v[0:3], v[214:217], v[188:191], v[0:3]
	v_mfma_f32_16x16x32_bf16 v[4:7], v[206:209], v[188:191], v[4:7]
	s_add_u32 s14, s14, 0x100
	s_addc_u32 s15, s15, 0
	s_add_u32 s72, s72, 0x100
	s_addc_u32 s73, s73, 0
	s_cmp_ge_i32 s74, s28
	s_mov_b32 s16, s74
	s_barrier
	s_cbranch_scc0 .LBB0_388

; #define PG8_STAGE(bufoff, gbase, voff) do { _Pragma("unroll") for (int _i = 0; _i < 2; ++_i) \
;         __builtin_amdgcn_global_load_lds((const unsigned*)((const char*)(gbase) + (voff)[_i]), (LAS unsigned*)(lds + (bufoff) + ldsw + _i * 8192), 16, 0, 0); } while (0)
; #define PG8_LDA(dst, b, h) do { _Pragma("unroll") for (int m = 0; m < 4; ++m) _Pragma("unroll") for (int k = 0; k < 2; ++k) dst[m][k] = *(const LAS bf16x8*)(lds + PG8_SA(b, h) + aoff + m * 2048 + k * 1024); } while (0)
; #define PG8_LDB(dst, b, h) do { _Pragma("unroll") for (int n = 0; n < 2; ++n) _Pragma("unroll") for (int k = 0; k < 2; ++k) dst[n][k] = *(const LAS bf16x8*)(lds + PG8_SB(b, h) + boff + n * 2048 + k * 1024); } while (0)
; #define PG8_MMA(ai, bj, At, Bt) do { __builtin_amdgcn_s_setprio(1); _Pragma("unroll") for (int m = 0; m < 4; ++m) _Pragma("unroll") for (int n = 0; n < 2; ++n) _Pragma("unroll") for (int k = 0; k < 2; ++k) \
;         acc[ai][bj][m][n] = __builtin_amdgcn_mfma_f32_16x16x32_bf16(Bt[n][k], At[m][k], acc[ai][bj][m][n], 0, 0, 0); __builtin_amdgcn_s_setprio(0); } while (0)
; #define PG8_WAIT_L(n) asm volatile("s_waitcnt lgkmcnt(" #n ")" ::: "memory")
; #define PG8_BAR __builtin_amdgcn_s_barrier()
; #define PG8_SCHED __builtin_amdgcn_sched_barrier(0)
; template <class Epi>
; DEVI void gemm_phase(LAS unsigned char* lds, const bf16_t* gA, const bf16_t* gBt, const int lda, const int ldb, const int K, const StaticOrder S_, const Epi E) {
;     ...
;         for (int t = 0; t < nt; t += 2) {
;             const bool last = (t == nt - 2);
;             const char* a1 = cA + (size_t)(t + 1) * kstep;
;             const char* a2 = last ? nA : cA + (size_t)(t + 2) * kstep; const char* b2 = last ? nB : cB + (size_t)(t + 2) * kstep;
;             const char* a3 = a2 + kstep; const char* b3 = b2 + kstep;
;             PG8_LDB(B0, 0, 0); PG8_SCHED; PG8_LDA(At, 0, 0); PG8_STAGE(PG8_SA(1, 1), a1 + hstepA, voffA);
;             PG8_WAIT_L(8); PG8_BAR; PG8_WAIT_L(0); PG8_MMA(0, 0, At, B0); PG8_BAR; PG8_SCHED;
;             PG8_LDB(B1, 0, 1); PG8_STAGE(PG8_SB(0, 0), b2, voffB);
;             PG8_BAR; PG8_WAIT_L(0); PG8_MMA(0, 1, At, B1); PG8_BAR;
;             PG8_LDA(At, 0, 1); PG8_STAGE(PG8_SA(0, 0), a2, voffA);
;             PG8_BAR; PG8_WAIT_L(0); PG8_MMA(1, 0, At, B0); PG8_BAR; PG8_SCHED;
.LBB0_519:
	ds_read_b128 v[160:163], v153
	ds_read_b128 v[164:167], v153 offset:1024
	ds_read_b128 v[168:171], v153 offset:2048
	ds_read_b128 v[172:175], v153 offset:3072
	s_add_i32 s77, s16, 2
	s_add_u32 s40, s14, 0x80
	s_addc_u32 s17, s15, 0
	s_cmp_eq_u32 s26, s16
	s_cselect_b32 s16, s48, s40
	s_cselect_b32 s17, s49, s17
	s_cselect_b32 s41, s61, s69
	s_cselect_b32 s40, s60, s68
	v_lshl_add_u64 v[144:145], s[14:15], 0, v[138:139]
	s_add_i32 m0, s19, 0xc000
	ds_read_b128 v[176:179], v154
	ds_read_b128 v[180:183], v154 offset:1024
	ds_read_b128 v[184:187], v154 offset:2048
	ds_read_b128 v[188:191], v154 offset:3072
	ds_read_b128 v[192:195], v154 offset:4096
	ds_read_b128 v[198:201], v154 offset:5120
	ds_read_b128 v[202:205], v154 offset:6144
	ds_read_b128 v[206:209], v154 offset:7168
	global_load_lds_dwordx4 v[144:145], off
	v_lshl_add_u64 v[144:145], s[14:15], 0, v[140:141]
	s_add_i32 m0, s19, 0xe000
	s_nop 0
	global_load_lds_dwordx4 v[144:145], off
	s_waitcnt lgkmcnt(8)
	s_barrier
	s_waitcnt lgkmcnt(0)
	v_mfma_f32_16x16x32_bf16 v[124:127], v[160:163], v[176:179], v[124:127]
	v_mfma_f32_16x16x32_bf16 v[120:123], v[168:171], v[176:179], v[120:123]
	v_mfma_f32_16x16x32_bf16 v[104:107], v[168:171], v[184:187], v[104:107]
	v_mfma_f32_16x16x32_bf16 v[108:111], v[160:163], v[184:187], v[108:111]
	v_mfma_f32_16x16x32_bf16 v[92:95], v[160:163], v[192:195], v[92:95]
	v_mfma_f32_16x16x32_bf16 v[88:91], v[168:171], v[192:195], v[88:91]
	v_mfma_f32_16x16x32_bf16 v[72:75], v[168:171], v[202:205], v[72:75]
	v_mfma_f32_16x16x32_bf16 v[76:79], v[160:163], v[202:205], v[76:79]
	v_mfma_f32_16x16x32_bf16 v[124:127], v[164:167], v[180:183], v[124:127]
	v_mfma_f32_16x16x32_bf16 v[120:123], v[172:175], v[180:183], v[120:123]
	v_mfma_f32_16x16x32_bf16 v[104:107], v[172:175], v[188:191], v[104:107]
	v_mfma_f32_16x16x32_bf16 v[108:111], v[164:167], v[188:191], v[108:111]
	v_mfma_f32_16x16x32_bf16 v[92:95], v[164:167], v[198:201], v[92:95]
	v_mfma_f32_16x16x32_bf16 v[88:91], v[172:175], v[198:201], v[88:91]
	v_mfma_f32_16x16x32_bf16 v[72:75], v[172:175], v[206:209], v[72:75]
	v_mfma_f32_16x16x32_bf16 v[76:79], v[164:167], v[206:209], v[76:79]
	s_barrier
	s_add_i32 s78, s31, s18
	v_lshl_add_u64 v[144:145], s[40:41], 0, v[130:131]
	s_mov_b32 m0, s78
	ds_read_b128 v[210:213], v155
	ds_read_b128 v[214:217], v155 offset:1024
	ds_read_b128 v[218:221], v155 offset:2048
	ds_read_b128 v[222:225], v155 offset:3072
	global_load_lds_dwordx4 v[144:145], off
	v_lshl_add_u64 v[226:227], s[40:41], 0, v[134:135]
	s_add_i32 m0, s78, 0x2000
	s_nop 0
	global_load_lds_dwordx4 v[226:227], off
	s_barrier
	s_waitcnt lgkmcnt(0)
	v_mfma_f32_16x16x32_bf16 v[116:119], v[210:213], v[176:179], v[116:119]
	v_mfma_f32_16x16x32_bf16 v[112:115], v[218:221], v[176:179], v[112:115]
	v_mfma_f32_16x16x32_bf16 v[96:99], v[218:221], v[184:187], v[96:99]
	v_mfma_f32_16x16x32_bf16 v[100:103], v[210:213], v[184:187], v[100:103]
	v_mfma_f32_16x16x32_bf16 v[84:87], v[210:213], v[192:195], v[84:87]
	v_mfma_f32_16x16x32_bf16 v[80:83], v[218:221], v[192:195], v[80:83]
	v_mfma_f32_16x16x32_bf16 v[64:67], v[218:221], v[202:205], v[64:67]
	v_mfma_f32_16x16x32_bf16 v[68:71], v[210:213], v[202:205], v[68:71]
	v_mfma_f32_16x16x32_bf16 v[116:119], v[214:217], v[180:183], v[116:119]
	v_mfma_f32_16x16x32_bf16 v[112:115], v[222:225], v[180:183], v[112:115]
	v_mfma_f32_16x16x32_bf16 v[96:99], v[222:225], v[188:191], v[96:99]
	v_mfma_f32_16x16x32_bf16 v[100:103], v[214:217], v[188:191], v[100:103]
	v_mfma_f32_16x16x32_bf16 v[84:87], v[214:217], v[198:201], v[84:87]
	v_mfma_f32_16x16x32_bf16 v[80:83], v[222:225], v[198:201], v[80:83]
	v_mfma_f32_16x16x32_bf16 v[64:67], v[222:225], v[206:209], v[64:67]
	v_mfma_f32_16x16x32_bf16 v[68:71], v[214:217], v[206:209], v[68:71]
	s_mov_b32 m0, s19
	v_lshl_add_u64 v[228:229], s[16:17], 0, v[128:129]
	s_barrier
	ds_read_b128 v[176:179], v154 offset:16384
	ds_read_b128 v[180:183], v154 offset:17408
	ds_read_b128 v[184:187], v154 offset:18432
	ds_read_b128 v[188:191], v154 offset:19456
	ds_read_b128 v[192:195], v154 offset:20480
	ds_read_b128 v[198:201], v154 offset:21504
	ds_read_b128 v[202:205], v154 offset:22528
	ds_read_b128 v[206:209], v154 offset:23552
	global_load_lds_dwordx4 v[228:229], off
	v_lshl_add_u64 v[230:231], s[16:17], 0, v[132:133]
	s_mov_b32 m0, s20
	s_nop 0
	global_load_lds_dwordx4 v[230:231], off
	s_barrier
	s_waitcnt lgkmcnt(0)
	v_mfma_f32_16x16x32_bf16 v[60:63], v[160:163], v[176:179], v[60:63]
	v_mfma_f32_16x16x32_bf16 v[56:59], v[168:171], v[176:179], v[56:59]
	v_mfma_f32_16x16x32_bf16 v[40:43], v[168:171], v[184:187], v[40:43]
	v_mfma_f32_16x16x32_bf16 v[44:47], v[160:163], v[184:187], v[44:47]
	v_mfma_f32_16x16x32_bf16 v[28:31], v[160:163], v[192:195], v[28:31]
	v_mfma_f32_16x16x32_bf16 v[24:27], v[168:171], v[192:195], v[24:27]
	v_mfma_f32_16x16x32_bf16 v[8:11], v[168:171], v[202:205], v[8:11]
	v_mfma_f32_16x16x32_bf16 v[12:15], v[160:163], v[202:205], v[12:15]
	v_mfma_f32_16x16x32_bf16 v[60:63], v[164:167], v[180:183], v[60:63]
	v_mfma_f32_16x16x32_bf16 v[56:59], v[172:175], v[180:183], v[56:59]
	v_mfma_f32_16x16x32_bf16 v[40:43], v[172:175], v[188:191], v[40:43]
	v_mfma_f32_16x16x32_bf16 v[44:47], v[164:167], v[188:191], v[44:47]
	v_mfma_f32_16x16x32_bf16 v[28:31], v[164:167], v[198:201], v[28:31]
	v_mfma_f32_16x16x32_bf16 v[24:27], v[172:175], v[198:201], v[24:27]
	v_mfma_f32_16x16x32_bf16 v[8:11], v[172:175], v[206:209], v[8:11]
	v_mfma_f32_16x16x32_bf16 v[12:15], v[164:167], v[206:209], v[12:15]
	s_barrier
; #define PG8_STAGE(bufoff, gbase, voff) do { _Pragma("unroll") for (int _i = 0; _i < 2; ++_i) \
;         __builtin_amdgcn_global_load_lds((const unsigned*)((const char*)(gbase) + (voff)[_i]), (LAS unsigned*)(lds + (bufoff) + ldsw + _i * 8192), 16, 0, 0); } while (0)
; #define PG8_LDA(dst, b, h) do { _Pragma("unroll") for (int m = 0; m < 4; ++m) _Pragma("unroll") for (int k = 0; k < 2; ++k) dst[m][k] = *(const LAS bf16x8*)(lds + PG8_SA(b, h) + aoff + m * 2048 + k * 1024); } while (0)
; #define PG8_LDB(dst, b, h) do { _Pragma("unroll") for (int n = 0; n < 2; ++n) _Pragma("unroll") for (int k = 0; k < 2; ++k) dst[n][k] = *(const LAS bf16x8*)(lds + PG8_SB(b, h) + boff + n * 2048 + k * 1024); } while (0)
; #define PG8_MMA(ai, bj, At, Bt) do { __builtin_amdgcn_s_setprio(1); _Pragma("unroll") for (int m = 0; m < 4; ++m) _Pragma("unroll") for (int n = 0; n < 2; ++n) _Pragma("unroll") for (int k = 0; k < 2; ++k) \
;         acc[ai][bj][m][n] = __builtin_amdgcn_mfma_f32_16x16x32_bf16(Bt[n][k], At[m][k], acc[ai][bj][m][n], 0, 0, 0); __builtin_amdgcn_s_setprio(0); } while (0)
; #define PG8_WAIT_V(n) asm volatile("s_waitcnt vmcnt(" #n ")" ::: "memory")
; #define PG8_WAIT_L(n) asm volatile("s_waitcnt lgkmcnt(" #n ")" ::: "memory")
; #define PG8_BAR __builtin_amdgcn_s_barrier()
; #define PG8_SCHED __builtin_amdgcn_sched_barrier(0)
; template <class Epi>
; DEVI void gemm_phase(LAS unsigned char* lds, const bf16_t* gA, const bf16_t* gBt, const int lda, const int ldb, const int K, const StaticOrder S_, const Epi E) {
;     ...
;             PG8_STAGE(PG8_SB(0, 1), b2 + hstepB, voffB);
;             PG8_WAIT_V(6); PG8_BAR; PG8_MMA(1, 1, At, B1); PG8_BAR;
;             PG8_LDB(B0, 1, 0); PG8_SCHED; PG8_LDA(At, 1, 0); PG8_STAGE(PG8_SA(0, 1), a2 + hstepA, voffA);
;             PG8_WAIT_L(8); PG8_BAR; PG8_WAIT_L(0); PG8_MMA(0, 0, At, B0); PG8_BAR; PG8_SCHED;
;             PG8_LDB(B1, 1, 1); PG8_STAGE(PG8_SB(1, 0), b3, voffB);
;             PG8_BAR; PG8_WAIT_L(0); PG8_MMA(0, 1, At, B1); PG8_BAR;
;             PG8_LDA(At, 1, 1); PG8_STAGE(PG8_SA(1, 0), a3, voffA);
;             PG8_BAR; PG8_WAIT_L(0); PG8_MMA(1, 0, At, B0); PG8_BAR; PG8_SCHED;
;             PG8_STAGE(PG8_SB(1, 1), b3 + hstepB, voffB);
	s_add_u32 s40, s40, s2
	s_addc_u32 s41, s41, s3
	s_add_i32 s78, s34, s18
	v_lshl_add_u64 v[232:233], s[40:41], 0, v[130:131]
	s_mov_b32 m0, s78
	v_lshl_add_u64 v[234:235], s[40:41], 0, v[134:135]
	global_load_lds_dwordx4 v[232:233], off
	s_add_i32 m0, s78, 0x2000
	s_nop 0
	global_load_lds_dwordx4 v[234:235], off
	s_waitcnt vmcnt(6)
	s_barrier
	v_mfma_f32_16x16x32_bf16 v[52:55], v[210:213], v[176:179], v[52:55]
	v_mfma_f32_16x16x32_bf16 v[48:51], v[218:221], v[176:179], v[48:51]
	v_mfma_f32_16x16x32_bf16 v[32:35], v[218:221], v[184:187], v[32:35]
	v_mfma_f32_16x16x32_bf16 v[36:39], v[210:213], v[184:187], v[36:39]
	v_mfma_f32_16x16x32_bf16 v[20:23], v[210:213], v[192:195], v[20:23]
	v_mfma_f32_16x16x32_bf16 v[16:19], v[218:221], v[192:195], v[16:19]
	v_mfma_f32_16x16x32_bf16 v[0:3], v[218:221], v[202:205], v[0:3]
	v_mfma_f32_16x16x32_bf16 v[4:7], v[210:213], v[202:205], v[4:7]
	v_mfma_f32_16x16x32_bf16 v[52:55], v[214:217], v[180:183], v[52:55]
	v_mfma_f32_16x16x32_bf16 v[48:51], v[222:225], v[180:183], v[48:51]
	v_mfma_f32_16x16x32_bf16 v[32:35], v[222:225], v[188:191], v[32:35]
	v_mfma_f32_16x16x32_bf16 v[36:39], v[214:217], v[188:191], v[36:39]
	v_mfma_f32_16x16x32_bf16 v[20:23], v[214:217], v[198:201], v[20:23]
	v_mfma_f32_16x16x32_bf16 v[16:19], v[222:225], v[198:201], v[16:19]
	v_mfma_f32_16x16x32_bf16 v[0:3], v[222:225], v[206:209], v[0:3]
	v_mfma_f32_16x16x32_bf16 v[4:7], v[214:217], v[206:209], v[4:7]
	s_barrier
	ds_read_b128 v[160:163], v156
	ds_read_b128 v[164:167], v156 offset:1024
	ds_read_b128 v[168:171], v156 offset:2048
	ds_read_b128 v[172:175], v156 offset:3072
	s_add_u32 s16, s16, s0
	s_addc_u32 s17, s17, s1
	s_mov_b32 m0, s21
	v_lshl_add_u64 v[210:211], s[16:17], 0, v[128:129]
	ds_read_b128 v[176:179], v154 offset:32768
	ds_read_b128 v[180:183], v154 offset:33792
	ds_read_b128 v[184:187], v154 offset:34816
	ds_read_b128 v[188:191], v154 offset:35840
	ds_read_b128 v[192:195], v154 offset:36864
	ds_read_b128 v[198:201], v154 offset:37888
	ds_read_b128 v[202:205], v154 offset:38912
	ds_read_b128 v[206:209], v154 offset:39936
	global_load_lds_dwordx4 v[210:211], off
	v_lshl_add_u64 v[210:211], s[16:17], 0, v[132:133]
	s_mov_b32 m0, s22
	s_nop 0
	global_load_lds_dwordx4 v[210:211], off
	s_waitcnt lgkmcnt(8)
	s_barrier
	s_waitcnt lgkmcnt(0)
	v_mfma_f32_16x16x32_bf16 v[124:127], v[160:163], v[176:179], v[124:127]
	v_mfma_f32_16x16x32_bf16 v[120:123], v[168:171], v[176:179], v[120:123]
	v_mfma_f32_16x16x32_bf16 v[104:107], v[168:171], v[184:187], v[104:107]
	v_mfma_f32_16x16x32_bf16 v[108:111], v[160:163], v[184:187], v[108:111]
	v_mfma_f32_16x16x32_bf16 v[92:95], v[160:163], v[192:195], v[92:95]
	v_mfma_f32_16x16x32_bf16 v[88:91], v[168:171], v[192:195], v[88:91]
	v_mfma_f32_16x16x32_bf16 v[72:75], v[168:171], v[202:205], v[72:75]
	v_mfma_f32_16x16x32_bf16 v[76:79], v[160:163], v[202:205], v[76:79]
	v_mfma_f32_16x16x32_bf16 v[124:127], v[164:167], v[180:183], v[124:127]
	v_mfma_f32_16x16x32_bf16 v[120:123], v[172:175], v[180:183], v[120:123]
	v_mfma_f32_16x16x32_bf16 v[104:107], v[172:175], v[188:191], v[104:107]
	v_mfma_f32_16x16x32_bf16 v[108:111], v[164:167], v[188:191], v[108:111]
	v_mfma_f32_16x16x32_bf16 v[92:95], v[164:167], v[198:201], v[92:95]
	v_mfma_f32_16x16x32_bf16 v[88:91], v[172:175], v[198:201], v[88:91]
	v_mfma_f32_16x16x32_bf16 v[72:75], v[172:175], v[206:209], v[72:75]
	v_mfma_f32_16x16x32_bf16 v[76:79], v[164:167], v[206:209], v[76:79]
	s_barrier
	s_add_i32 s16, s35, s18
	v_lshl_add_u64 v[144:145], v[144:145], 0, s[46:47]
	s_mov_b32 m0, s16
	ds_read_b128 v[210:213], v157
	ds_read_b128 v[214:217], v157 offset:1024
	ds_read_b128 v[218:221], v157 offset:2048
	ds_read_b128 v[222:225], v157 offset:3072
	global_load_lds_dwordx4 v[144:145], off
	v_lshl_add_u64 v[144:145], v[226:227], 0, s[46:47]
	s_add_i32 m0, s16, 0x2000
	s_nop 0
	global_load_lds_dwordx4 v[144:145], off
	s_barrier
; #define PG8_STAGE(bufoff, gbase, voff) do { _Pragma("unroll") for (int _i = 0; _i < 2; ++_i) \
;         __builtin_amdgcn_global_load_lds((const unsigned*)((const char*)(gbase) + (voff)[_i]), (LAS unsigned*)(lds + (bufoff) + ldsw + _i * 8192), 16, 0, 0); } while (0)
; #define PG8_LDA(dst, b, h) do { _Pragma("unroll") for (int m = 0; m < 4; ++m) _Pragma("unroll") for (int k = 0; k < 2; ++k) dst[m][k] = *(const LAS bf16x8*)(lds + PG8_SA(b, h) + aoff + m * 2048 + k * 1024); } while (0)
; #define PG8_MMA(ai, bj, At, Bt) do { __builtin_amdgcn_s_setprio(1); _Pragma("unroll") for (int m = 0; m < 4; ++m) _Pragma("unroll") for (int n = 0; n < 2; ++n) _Pragma("unroll") for (int k = 0; k < 2; ++k) \
;         acc[ai][bj][m][n] = __builtin_amdgcn_mfma_f32_16x16x32_bf16(Bt[n][k], At[m][k], acc[ai][bj][m][n], 0, 0, 0); __builtin_amdgcn_s_setprio(0); } while (0)
; #define PG8_WAIT_V(n) asm volatile("s_waitcnt vmcnt(" #n ")" ::: "memory")
; #define PG8_WAIT_L(n) asm volatile("s_waitcnt lgkmcnt(" #n ")" ::: "memory")
; #define PG8_BAR __builtin_amdgcn_s_barrier()
; #define PG8_SCHED __builtin_amdgcn_sched_barrier(0)
; template <class Epi>
; DEVI void gemm_phase(LAS unsigned char* lds, const bf16_t* gA, const bf16_t* gBt, const int lda, const int ldb, const int K, const StaticOrder S_, const Epi E) {
;     ...
;             PG8_BAR; PG8_WAIT_L(0); PG8_MMA(0, 1, At, B1); PG8_BAR;
;             PG8_LDA(At, 1, 1); PG8_STAGE(PG8_SA(1, 0), a3, voffA);
;             PG8_BAR; PG8_WAIT_L(0); PG8_MMA(1, 0, At, B0); PG8_BAR; PG8_SCHED;
;             PG8_STAGE(PG8_SB(1, 1), b3 + hstepB, voffB);
;             PG8_WAIT_V(6); PG8_BAR; PG8_MMA(1, 1, At, B1); PG8_BAR;
	s_waitcnt lgkmcnt(0)
	v_mfma_f32_16x16x32_bf16 v[116:119], v[210:213], v[176:179], v[116:119]
	v_mfma_f32_16x16x32_bf16 v[112:115], v[218:221], v[176:179], v[112:115]
	v_mfma_f32_16x16x32_bf16 v[96:99], v[218:221], v[184:187], v[96:99]
	v_mfma_f32_16x16x32_bf16 v[100:103], v[210:213], v[184:187], v[100:103]
	v_mfma_f32_16x16x32_bf16 v[84:87], v[210:213], v[192:195], v[84:87]
	v_mfma_f32_16x16x32_bf16 v[80:83], v[218:221], v[192:195], v[80:83]
	v_mfma_f32_16x16x32_bf16 v[64:67], v[218:221], v[202:205], v[64:67]
	v_mfma_f32_16x16x32_bf16 v[68:71], v[210:213], v[202:205], v[68:71]
	v_mfma_f32_16x16x32_bf16 v[116:119], v[214:217], v[180:183], v[116:119]
	v_mfma_f32_16x16x32_bf16 v[112:115], v[222:225], v[180:183], v[112:115]
	v_mfma_f32_16x16x32_bf16 v[96:99], v[222:225], v[188:191], v[96:99]
	v_mfma_f32_16x16x32_bf16 v[100:103], v[214:217], v[188:191], v[100:103]
	v_mfma_f32_16x16x32_bf16 v[84:87], v[214:217], v[198:201], v[84:87]
	v_mfma_f32_16x16x32_bf16 v[80:83], v[222:225], v[198:201], v[80:83]
	v_mfma_f32_16x16x32_bf16 v[64:67], v[222:225], v[206:209], v[64:67]
	v_mfma_f32_16x16x32_bf16 v[68:71], v[214:217], v[206:209], v[68:71]
	s_mov_b32 m0, s23
	v_lshl_add_u64 v[144:145], v[228:229], 0, s[46:47]
	s_barrier
	ds_read_b128 v[176:179], v154 offset:49152
	ds_read_b128 v[180:183], v154 offset:50176
	ds_read_b128 v[184:187], v154 offset:51200
	ds_read_b128 v[188:191], v154 offset:52224
	ds_read_b128 v[192:195], v154 offset:53248
	ds_read_b128 v[198:201], v154 offset:54272
	ds_read_b128 v[202:205], v154 offset:55296
	ds_read_b128 v[206:209], v154 offset:56320
	global_load_lds_dwordx4 v[144:145], off
	v_lshl_add_u64 v[144:145], v[230:231], 0, s[46:47]
	s_mov_b32 m0, s24
	s_nop 0
	global_load_lds_dwordx4 v[144:145], off
	s_barrier
	s_waitcnt lgkmcnt(0)
	v_mfma_f32_16x16x32_bf16 v[60:63], v[160:163], v[176:179], v[60:63]
	v_mfma_f32_16x16x32_bf16 v[56:59], v[168:171], v[176:179], v[56:59]
	v_mfma_f32_16x16x32_bf16 v[40:43], v[168:171], v[184:187], v[40:43]
	v_mfma_f32_16x16x32_bf16 v[44:47], v[160:163], v[184:187], v[44:47]
	v_mfma_f32_16x16x32_bf16 v[28:31], v[160:163], v[192:195], v[28:31]
	v_mfma_f32_16x16x32_bf16 v[24:27], v[168:171], v[192:195], v[24:27]
	v_mfma_f32_16x16x32_bf16 v[8:11], v[168:171], v[202:205], v[8:11]
	v_mfma_f32_16x16x32_bf16 v[12:15], v[160:163], v[202:205], v[12:15]
	v_mfma_f32_16x16x32_bf16 v[60:63], v[164:167], v[180:183], v[60:63]
	v_mfma_f32_16x16x32_bf16 v[56:59], v[172:175], v[180:183], v[56:59]
	v_mfma_f32_16x16x32_bf16 v[40:43], v[172:175], v[188:191], v[40:43]
	v_mfma_f32_16x16x32_bf16 v[44:47], v[164:167], v[188:191], v[44:47]
	v_mfma_f32_16x16x32_bf16 v[28:31], v[164:167], v[198:201], v[28:31]
	v_mfma_f32_16x16x32_bf16 v[24:27], v[172:175], v[198:201], v[24:27]
	v_mfma_f32_16x16x32_bf16 v[8:11], v[172:175], v[206:209], v[8:11]
	v_mfma_f32_16x16x32_bf16 v[12:15], v[164:167], v[206:209], v[12:15]
	s_barrier
	s_add_i32 s16, s50, s18
	v_lshl_add_u64 v[144:145], v[232:233], 0, s[46:47]
	s_mov_b32 m0, s16
	s_nop 0
	global_load_lds_dwordx4 v[144:145], off
	v_lshl_add_u64 v[144:145], v[234:235], 0, s[46:47]
	s_add_i32 m0, s16, 0x2000
	s_nop 0
	global_load_lds_dwordx4 v[144:145], off
	s_waitcnt vmcnt(6)
	s_barrier
	v_mfma_f32_16x16x32_bf16 v[52:55], v[210:213], v[176:179], v[52:55]
	v_mfma_f32_16x16x32_bf16 v[48:51], v[218:221], v[176:179], v[48:51]
	v_mfma_f32_16x16x32_bf16 v[32:35], v[218:221], v[184:187], v[32:35]
	v_mfma_f32_16x16x32_bf16 v[36:39], v[210:213], v[184:187], v[36:39]
	v_mfma_f32_16x16x32_bf16 v[20:23], v[210:213], v[192:195], v[20:23]
	v_mfma_f32_16x16x32_bf16 v[16:19], v[218:221], v[192:195], v[16:19]
	v_mfma_f32_16x16x32_bf16 v[0:3], v[218:221], v[202:205], v[0:3]
	v_mfma_f32_16x16x32_bf16 v[4:7], v[210:213], v[202:205], v[4:7]
	v_mfma_f32_16x16x32_bf16 v[52:55], v[214:217], v[180:183], v[52:55]
	v_mfma_f32_16x16x32_bf16 v[48:51], v[222:225], v[180:183], v[48:51]
	v_mfma_f32_16x16x32_bf16 v[32:35], v[222:225], v[188:191], v[32:35]
	v_mfma_f32_16x16x32_bf16 v[36:39], v[214:217], v[188:191], v[36:39]
	v_mfma_f32_16x16x32_bf16 v[20:23], v[214:217], v[198:201], v[20:23]
	v_mfma_f32_16x16x32_bf16 v[16:19], v[222:225], v[198:201], v[16:19]
	v_mfma_f32_16x16x32_bf16 v[0:3], v[222:225], v[206:209], v[0:3]
	v_mfma_f32_16x16x32_bf16 v[4:7], v[214:217], v[206:209], v[4:7]
	s_add_u32 s14, s14, 0x100
	s_addc_u32 s15, s15, 0
	s_add_u32 s68, s68, 0x100
	s_addc_u32 s69, s69, 0
	s_cmp_ge_i32 s77, s25
	s_mov_b32 s16, s77
	s_barrier
	s_cbranch_scc0 .LBB0_519
	v_readlane_b32 s78, v240, 54
	v_readlane_b32 s79, v240, 55

; #define PG8_STAGE(bufoff, gbase, voff) do { _Pragma("unroll") for (int _i = 0; _i < 2; ++_i) \
;         __builtin_amdgcn_global_load_lds((const unsigned*)((const char*)(gbase) + (voff)[_i]), (LAS unsigned*)(lds + (bufoff) + ldsw + _i * 8192), 16, 0, 0); } while (0)
; #define PG8_LDA(dst, b, h) do { _Pragma("unroll") for (int m = 0; m < 4; ++m) _Pragma("unroll") for (int k = 0; k < 2; ++k) dst[m][k] = *(const LAS bf16x8*)(lds + PG8_SA(b, h) + aoff + m * 2048 + k * 1024); } while (0)
; #define PG8_LDB(dst, b, h) do { _Pragma("unroll") for (int n = 0; n < 2; ++n) _Pragma("unroll") for (int k = 0; k < 2; ++k) dst[n][k] = *(const LAS bf16x8*)(lds + PG8_SB(b, h) + boff + n * 2048 + k * 1024); } while (0)
; #define PG8_MMA(ai, bj, At, Bt) do { __builtin_amdgcn_s_setprio(1); _Pragma("unroll") for (int m = 0; m < 4; ++m) _Pragma("unroll") for (int n = 0; n < 2; ++n) _Pragma("unroll") for (int k = 0; k < 2; ++k) \
;         acc[ai][bj][m][n] = __builtin_amdgcn_mfma_f32_16x16x32_bf16(Bt[n][k], At[m][k], acc[ai][bj][m][n], 0, 0, 0); __builtin_amdgcn_s_setprio(0); } while (0)
; #define PG8_WAIT_L(n) asm volatile("s_waitcnt lgkmcnt(" #n ")" ::: "memory")
; #define PG8_BAR __builtin_amdgcn_s_barrier()
; #define PG8_SCHED __builtin_amdgcn_sched_barrier(0)
; template <class Epi>
; DEVI void gemm_phase(LAS unsigned char* lds, const bf16_t* gA, const bf16_t* gBt, const int lda, const int ldb, const int K, const StaticOrder S_, const Epi E) {
;     ...
;         for (int t = 0; t < nt; t += 2) {
;             const bool last = (t == nt - 2);
;             const char* a1 = cA + (size_t)(t + 1) * kstep;
;             const char* a2 = last ? nA : cA + (size_t)(t + 2) * kstep; const char* b2 = last ? nB : cB + (size_t)(t + 2) * kstep;
;             const char* a3 = a2 + kstep; const char* b3 = b2 + kstep;
;             PG8_LDB(B0, 0, 0); PG8_SCHED; PG8_LDA(At, 0, 0); PG8_STAGE(PG8_SA(1, 1), a1 + hstepA, voffA);
;             PG8_WAIT_L(8); PG8_BAR; PG8_WAIT_L(0); PG8_MMA(0, 0, At, B0); PG8_BAR; PG8_SCHED;
;             PG8_LDB(B1, 0, 1); PG8_STAGE(PG8_SB(0, 0), b2, voffB);
;             PG8_BAR; PG8_WAIT_L(0); PG8_MMA(0, 1, At, B1); PG8_BAR;
;             PG8_LDA(At, 0, 1); PG8_STAGE(PG8_SA(0, 0), a2, voffA);
;             PG8_BAR; PG8_WAIT_L(0); PG8_MMA(1, 0, At, B0); PG8_BAR; PG8_SCHED;
.LBB0_744:
	ds_read_b128 v[160:163], v153
	ds_read_b128 v[164:167], v153 offset:1024
	ds_read_b128 v[168:171], v153 offset:2048
	ds_read_b128 v[172:175], v153 offset:3072
	s_add_i32 s77, s16, 2
	s_add_u32 s40, s14, 0x80
	s_addc_u32 s17, s15, 0
	s_cmp_eq_u32 s26, s16
	s_cselect_b32 s16, s48, s40
	s_cselect_b32 s17, s49, s17
	s_cselect_b32 s41, s61, s65
	s_cselect_b32 s40, s60, s64
	v_lshl_add_u64 v[144:145], s[14:15], 0, v[138:139]
	s_add_i32 m0, s19, 0xc000
	ds_read_b128 v[176:179], v154
	ds_read_b128 v[180:183], v154 offset:1024
	ds_read_b128 v[184:187], v154 offset:2048
	ds_read_b128 v[188:191], v154 offset:3072
	ds_read_b128 v[192:195], v154 offset:4096
	ds_read_b128 v[198:201], v154 offset:5120
	ds_read_b128 v[202:205], v154 offset:6144
	ds_read_b128 v[206:209], v154 offset:7168
	global_load_lds_dwordx4 v[144:145], off
	v_lshl_add_u64 v[144:145], s[14:15], 0, v[140:141]
	s_add_i32 m0, s19, 0xe000
	s_nop 0
	global_load_lds_dwordx4 v[144:145], off
	s_waitcnt lgkmcnt(8)
	s_barrier
	s_waitcnt lgkmcnt(0)
	v_mfma_f32_16x16x32_bf16 v[124:127], v[160:163], v[176:179], v[124:127]
	v_mfma_f32_16x16x32_bf16 v[120:123], v[168:171], v[176:179], v[120:123]
	v_mfma_f32_16x16x32_bf16 v[104:107], v[168:171], v[184:187], v[104:107]
	v_mfma_f32_16x16x32_bf16 v[108:111], v[160:163], v[184:187], v[108:111]
	v_mfma_f32_16x16x32_bf16 v[92:95], v[160:163], v[192:195], v[92:95]
	v_mfma_f32_16x16x32_bf16 v[88:91], v[168:171], v[192:195], v[88:91]
	v_mfma_f32_16x16x32_bf16 v[72:75], v[168:171], v[202:205], v[72:75]
	v_mfma_f32_16x16x32_bf16 v[76:79], v[160:163], v[202:205], v[76:79]
	v_mfma_f32_16x16x32_bf16 v[124:127], v[164:167], v[180:183], v[124:127]
	v_mfma_f32_16x16x32_bf16 v[120:123], v[172:175], v[180:183], v[120:123]
	v_mfma_f32_16x16x32_bf16 v[104:107], v[172:175], v[188:191], v[104:107]
	v_mfma_f32_16x16x32_bf16 v[108:111], v[164:167], v[188:191], v[108:111]
	v_mfma_f32_16x16x32_bf16 v[92:95], v[164:167], v[198:201], v[92:95]
	v_mfma_f32_16x16x32_bf16 v[88:91], v[172:175], v[198:201], v[88:91]
	v_mfma_f32_16x16x32_bf16 v[72:75], v[172:175], v[206:209], v[72:75]
	v_mfma_f32_16x16x32_bf16 v[76:79], v[164:167], v[206:209], v[76:79]
	s_barrier
	s_add_i32 s78, s31, s18
	v_lshl_add_u64 v[144:145], s[40:41], 0, v[130:131]
	s_mov_b32 m0, s78
	ds_read_b128 v[210:213], v155
	ds_read_b128 v[214:217], v155 offset:1024
	ds_read_b128 v[218:221], v155 offset:2048
	ds_read_b128 v[222:225], v155 offset:3072
	global_load_lds_dwordx4 v[144:145], off
	v_lshl_add_u64 v[226:227], s[40:41], 0, v[134:135]
	s_add_i32 m0, s78, 0x2000
	s_nop 0
	global_load_lds_dwordx4 v[226:227], off
	s_barrier
	s_waitcnt lgkmcnt(0)
	v_mfma_f32_16x16x32_bf16 v[116:119], v[210:213], v[176:179], v[116:119]
	v_mfma_f32_16x16x32_bf16 v[112:115], v[218:221], v[176:179], v[112:115]
	v_mfma_f32_16x16x32_bf16 v[96:99], v[218:221], v[184:187], v[96:99]
	v_mfma_f32_16x16x32_bf16 v[100:103], v[210:213], v[184:187], v[100:103]
	v_mfma_f32_16x16x32_bf16 v[84:87], v[210:213], v[192:195], v[84:87]
	v_mfma_f32_16x16x32_bf16 v[80:83], v[218:221], v[192:195], v[80:83]
	v_mfma_f32_16x16x32_bf16 v[64:67], v[218:221], v[202:205], v[64:67]
	v_mfma_f32_16x16x32_bf16 v[68:71], v[210:213], v[202:205], v[68:71]
	v_mfma_f32_16x16x32_bf16 v[116:119], v[214:217], v[180:183], v[116:119]
	v_mfma_f32_16x16x32_bf16 v[112:115], v[222:225], v[180:183], v[112:115]
	v_mfma_f32_16x16x32_bf16 v[96:99], v[222:225], v[188:191], v[96:99]
	v_mfma_f32_16x16x32_bf16 v[100:103], v[214:217], v[188:191], v[100:103]
	v_mfma_f32_16x16x32_bf16 v[84:87], v[214:217], v[198:201], v[84:87]
	v_mfma_f32_16x16x32_bf16 v[80:83], v[222:225], v[198:201], v[80:83]
	v_mfma_f32_16x16x32_bf16 v[64:67], v[222:225], v[206:209], v[64:67]
	v_mfma_f32_16x16x32_bf16 v[68:71], v[214:217], v[206:209], v[68:71]
	s_mov_b32 m0, s19
	v_lshl_add_u64 v[228:229], s[16:17], 0, v[128:129]
	s_barrier
	ds_read_b128 v[176:179], v154 offset:16384
	ds_read_b128 v[180:183], v154 offset:17408
	ds_read_b128 v[184:187], v154 offset:18432
	ds_read_b128 v[188:191], v154 offset:19456
	ds_read_b128 v[192:195], v154 offset:20480
	ds_read_b128 v[198:201], v154 offset:21504
	ds_read_b128 v[202:205], v154 offset:22528
	ds_read_b128 v[206:209], v154 offset:23552
	global_load_lds_dwordx4 v[228:229], off
	v_lshl_add_u64 v[230:231], s[16:17], 0, v[132:133]
	s_mov_b32 m0, s20
	s_nop 0
	global_load_lds_dwordx4 v[230:231], off
	s_barrier
	s_waitcnt lgkmcnt(0)
	v_mfma_f32_16x16x32_bf16 v[60:63], v[160:163], v[176:179], v[60:63]
	v_mfma_f32_16x16x32_bf16 v[56:59], v[168:171], v[176:179], v[56:59]
	v_mfma_f32_16x16x32_bf16 v[40:43], v[168:171], v[184:187], v[40:43]
	v_mfma_f32_16x16x32_bf16 v[44:47], v[160:163], v[184:187], v[44:47]
	v_mfma_f32_16x16x32_bf16 v[28:31], v[160:163], v[192:195], v[28:31]
	v_mfma_f32_16x16x32_bf16 v[24:27], v[168:171], v[192:195], v[24:27]
	v_mfma_f32_16x16x32_bf16 v[8:11], v[168:171], v[202:205], v[8:11]
	v_mfma_f32_16x16x32_bf16 v[12:15], v[160:163], v[202:205], v[12:15]
	v_mfma_f32_16x16x32_bf16 v[60:63], v[164:167], v[180:183], v[60:63]
	v_mfma_f32_16x16x32_bf16 v[56:59], v[172:175], v[180:183], v[56:59]
	v_mfma_f32_16x16x32_bf16 v[40:43], v[172:175], v[188:191], v[40:43]
	v_mfma_f32_16x16x32_bf16 v[44:47], v[164:167], v[188:191], v[44:47]
	v_mfma_f32_16x16x32_bf16 v[28:31], v[164:167], v[198:201], v[28:31]
	v_mfma_f32_16x16x32_bf16 v[24:27], v[172:175], v[198:201], v[24:27]
	v_mfma_f32_16x16x32_bf16 v[8:11], v[172:175], v[206:209], v[8:11]
	v_mfma_f32_16x16x32_bf16 v[12:15], v[164:167], v[206:209], v[12:15]
	s_barrier
; #define PG8_STAGE(bufoff, gbase, voff) do { _Pragma("unroll") for (int _i = 0; _i < 2; ++_i) \
;         __builtin_amdgcn_global_load_lds((const unsigned*)((const char*)(gbase) + (voff)[_i]), (LAS unsigned*)(lds + (bufoff) + ldsw + _i * 8192), 16, 0, 0); } while (0)
; #define PG8_LDA(dst, b, h) do { _Pragma("unroll") for (int m = 0; m < 4; ++m) _Pragma("unroll") for (int k = 0; k < 2; ++k) dst[m][k] = *(const LAS bf16x8*)(lds + PG8_SA(b, h) + aoff + m * 2048 + k * 1024); } while (0)
; #define PG8_LDB(dst, b, h) do { _Pragma("unroll") for (int n = 0; n < 2; ++n) _Pragma("unroll") for (int k = 0; k < 2; ++k) dst[n][k] = *(const LAS bf16x8*)(lds + PG8_SB(b, h) + boff + n * 2048 + k * 1024); } while (0)
; #define PG8_MMA(ai, bj, At, Bt) do { __builtin_amdgcn_s_setprio(1); _Pragma("unroll") for (int m = 0; m < 4; ++m) _Pragma("unroll") for (int n = 0; n < 2; ++n) _Pragma("unroll") for (int k = 0; k < 2; ++k) \
;         acc[ai][bj][m][n] = __builtin_amdgcn_mfma_f32_16x16x32_bf16(Bt[n][k], At[m][k], acc[ai][bj][m][n], 0, 0, 0); __builtin_amdgcn_s_setprio(0); } while (0)
; #define PG8_WAIT_V(n) asm volatile("s_waitcnt vmcnt(" #n ")" ::: "memory")
; #define PG8_WAIT_L(n) asm volatile("s_waitcnt lgkmcnt(" #n ")" ::: "memory")
; #define PG8_BAR __builtin_amdgcn_s_barrier()
; #define PG8_SCHED __builtin_amdgcn_sched_barrier(0)
; template <class Epi>
; DEVI void gemm_phase(LAS unsigned char* lds, const bf16_t* gA, const bf16_t* gBt, const int lda, const int ldb, const int K, const StaticOrder S_, const Epi E) {
;     ...
;             PG8_STAGE(PG8_SB(0, 1), b2 + hstepB, voffB);
;             PG8_WAIT_V(6); PG8_BAR; PG8_MMA(1, 1, At, B1); PG8_BAR;
;             PG8_LDB(B0, 1, 0); PG8_SCHED; PG8_LDA(At, 1, 0); PG8_STAGE(PG8_SA(0, 1), a2 + hstepA, voffA);
;             PG8_WAIT_L(8); PG8_BAR; PG8_WAIT_L(0); PG8_MMA(0, 0, At, B0); PG8_BAR; PG8_SCHED;
;             PG8_LDB(B1, 1, 1); PG8_STAGE(PG8_SB(1, 0), b3, voffB);
;             PG8_BAR; PG8_WAIT_L(0); PG8_MMA(0, 1, At, B1); PG8_BAR;
;             PG8_LDA(At, 1, 1); PG8_STAGE(PG8_SA(1, 0), a3, voffA);
;             PG8_BAR; PG8_WAIT_L(0); PG8_MMA(1, 0, At, B0); PG8_BAR; PG8_SCHED;
;             PG8_STAGE(PG8_SB(1, 1), b3 + hstepB, voffB);
	s_add_u32 s40, s40, s2
	s_addc_u32 s41, s41, s3
	s_add_i32 s78, s34, s18
	v_lshl_add_u64 v[232:233], s[40:41], 0, v[130:131]
	s_mov_b32 m0, s78
	v_lshl_add_u64 v[234:235], s[40:41], 0, v[134:135]
	global_load_lds_dwordx4 v[232:233], off
	s_add_i32 m0, s78, 0x2000
	s_nop 0
	global_load_lds_dwordx4 v[234:235], off
	s_waitcnt vmcnt(6)
	s_barrier
	v_mfma_f32_16x16x32_bf16 v[52:55], v[210:213], v[176:179], v[52:55]
	v_mfma_f32_16x16x32_bf16 v[48:51], v[218:221], v[176:179], v[48:51]
	v_mfma_f32_16x16x32_bf16 v[32:35], v[218:221], v[184:187], v[32:35]
	v_mfma_f32_16x16x32_bf16 v[36:39], v[210:213], v[184:187], v[36:39]
	v_mfma_f32_16x16x32_bf16 v[20:23], v[210:213], v[192:195], v[20:23]
	v_mfma_f32_16x16x32_bf16 v[16:19], v[218:221], v[192:195], v[16:19]
	v_mfma_f32_16x16x32_bf16 v[0:3], v[218:221], v[202:205], v[0:3]
	v_mfma_f32_16x16x32_bf16 v[4:7], v[210:213], v[202:205], v[4:7]
	v_mfma_f32_16x16x32_bf16 v[52:55], v[214:217], v[180:183], v[52:55]
	v_mfma_f32_16x16x32_bf16 v[48:51], v[222:225], v[180:183], v[48:51]
	v_mfma_f32_16x16x32_bf16 v[32:35], v[222:225], v[188:191], v[32:35]
	v_mfma_f32_16x16x32_bf16 v[36:39], v[214:217], v[188:191], v[36:39]
	v_mfma_f32_16x16x32_bf16 v[20:23], v[214:217], v[198:201], v[20:23]
	v_mfma_f32_16x16x32_bf16 v[16:19], v[222:225], v[198:201], v[16:19]
	v_mfma_f32_16x16x32_bf16 v[0:3], v[222:225], v[206:209], v[0:3]
	v_mfma_f32_16x16x32_bf16 v[4:7], v[214:217], v[206:209], v[4:7]
	s_barrier
	ds_read_b128 v[160:163], v156
	ds_read_b128 v[164:167], v156 offset:1024
	ds_read_b128 v[168:171], v156 offset:2048
	ds_read_b128 v[172:175], v156 offset:3072
	s_add_u32 s16, s16, s0
	s_addc_u32 s17, s17, s1
	s_mov_b32 m0, s21
	v_lshl_add_u64 v[210:211], s[16:17], 0, v[128:129]
	ds_read_b128 v[176:179], v154 offset:32768
	ds_read_b128 v[180:183], v154 offset:33792
	ds_read_b128 v[184:187], v154 offset:34816
	ds_read_b128 v[188:191], v154 offset:35840
	ds_read_b128 v[192:195], v154 offset:36864
	ds_read_b128 v[198:201], v154 offset:37888
	ds_read_b128 v[202:205], v154 offset:38912
	ds_read_b128 v[206:209], v154 offset:39936
	global_load_lds_dwordx4 v[210:211], off
	v_lshl_add_u64 v[210:211], s[16:17], 0, v[132:133]
	s_mov_b32 m0, s22
	s_nop 0
	global_load_lds_dwordx4 v[210:211], off
	s_waitcnt lgkmcnt(8)
	s_barrier
	s_waitcnt lgkmcnt(0)
	v_mfma_f32_16x16x32_bf16 v[124:127], v[160:163], v[176:179], v[124:127]
	v_mfma_f32_16x16x32_bf16 v[120:123], v[168:171], v[176:179], v[120:123]
	v_mfma_f32_16x16x32_bf16 v[104:107], v[168:171], v[184:187], v[104:107]
	v_mfma_f32_16x16x32_bf16 v[108:111], v[160:163], v[184:187], v[108:111]
	v_mfma_f32_16x16x32_bf16 v[92:95], v[160:163], v[192:195], v[92:95]
	v_mfma_f32_16x16x32_bf16 v[88:91], v[168:171], v[192:195], v[88:91]
	v_mfma_f32_16x16x32_bf16 v[72:75], v[168:171], v[202:205], v[72:75]
	v_mfma_f32_16x16x32_bf16 v[76:79], v[160:163], v[202:205], v[76:79]
	v_mfma_f32_16x16x32_bf16 v[124:127], v[164:167], v[180:183], v[124:127]
	v_mfma_f32_16x16x32_bf16 v[120:123], v[172:175], v[180:183], v[120:123]
	v_mfma_f32_16x16x32_bf16 v[104:107], v[172:175], v[188:191], v[104:107]
	v_mfma_f32_16x16x32_bf16 v[108:111], v[164:167], v[188:191], v[108:111]
	v_mfma_f32_16x16x32_bf16 v[92:95], v[164:167], v[198:201], v[92:95]
	v_mfma_f32_16x16x32_bf16 v[88:91], v[172:175], v[198:201], v[88:91]
	v_mfma_f32_16x16x32_bf16 v[72:75], v[172:175], v[206:209], v[72:75]
	v_mfma_f32_16x16x32_bf16 v[76:79], v[164:167], v[206:209], v[76:79]
	s_barrier
	s_add_i32 s16, s35, s18
	v_lshl_add_u64 v[144:145], v[144:145], 0, s[46:47]
	s_mov_b32 m0, s16
	ds_read_b128 v[210:213], v157
	ds_read_b128 v[214:217], v157 offset:1024
	ds_read_b128 v[218:221], v157 offset:2048
	ds_read_b128 v[222:225], v157 offset:3072
	global_load_lds_dwordx4 v[144:145], off
	v_lshl_add_u64 v[144:145], v[226:227], 0, s[46:47]
	s_add_i32 m0, s16, 0x2000
	s_nop 0
	global_load_lds_dwordx4 v[144:145], off
	s_barrier
; #define PG8_STAGE(bufoff, gbase, voff) do { _Pragma("unroll") for (int _i = 0; _i < 2; ++_i) \
;         __builtin_amdgcn_global_load_lds((const unsigned*)((const char*)(gbase) + (voff)[_i]), (LAS unsigned*)(lds + (bufoff) + ldsw + _i * 8192), 16, 0, 0); } while (0)
; #define PG8_LDA(dst, b, h) do { _Pragma("unroll") for (int m = 0; m < 4; ++m) _Pragma("unroll") for (int k = 0; k < 2; ++k) dst[m][k] = *(const LAS bf16x8*)(lds + PG8_SA(b, h) + aoff + m * 2048 + k * 1024); } while (0)
; #define PG8_MMA(ai, bj, At, Bt) do { __builtin_amdgcn_s_setprio(1); _Pragma("unroll") for (int m = 0; m < 4; ++m) _Pragma("unroll") for (int n = 0; n < 2; ++n) _Pragma("unroll") for (int k = 0; k < 2; ++k) \
;         acc[ai][bj][m][n] = __builtin_amdgcn_mfma_f32_16x16x32_bf16(Bt[n][k], At[m][k], acc[ai][bj][m][n], 0, 0, 0); __builtin_amdgcn_s_setprio(0); } while (0)
; #define PG8_WAIT_V(n) asm volatile("s_waitcnt vmcnt(" #n ")" ::: "memory")
; #define PG8_WAIT_L(n) asm volatile("s_waitcnt lgkmcnt(" #n ")" ::: "memory")
; #define PG8_BAR __builtin_amdgcn_s_barrier()
; #define PG8_SCHED __builtin_amdgcn_sched_barrier(0)
; template <class Epi>
; DEVI void gemm_phase(LAS unsigned char* lds, const bf16_t* gA, const bf16_t* gBt, const int lda, const int ldb, const int K, const StaticOrder S_, const Epi E) {
;     ...
;             PG8_BAR; PG8_WAIT_L(0); PG8_MMA(0, 1, At, B1); PG8_BAR;
;             PG8_LDA(At, 1, 1); PG8_STAGE(PG8_SA(1, 0), a3, voffA);
;             PG8_BAR; PG8_WAIT_L(0); PG8_MMA(1, 0, At, B0); PG8_BAR; PG8_SCHED;
;             PG8_STAGE(PG8_SB(1, 1), b3 + hstepB, voffB);
;             PG8_WAIT_V(6); PG8_BAR; PG8_MMA(1, 1, At, B1); PG8_BAR;
	s_waitcnt lgkmcnt(0)
	v_mfma_f32_16x16x32_bf16 v[116:119], v[210:213], v[176:179], v[116:119]
	v_mfma_f32_16x16x32_bf16 v[112:115], v[218:221], v[176:179], v[112:115]
	v_mfma_f32_16x16x32_bf16 v[96:99], v[218:221], v[184:187], v[96:99]
	v_mfma_f32_16x16x32_bf16 v[100:103], v[210:213], v[184:187], v[100:103]
	v_mfma_f32_16x16x32_bf16 v[84:87], v[210:213], v[192:195], v[84:87]
	v_mfma_f32_16x16x32_bf16 v[80:83], v[218:221], v[192:195], v[80:83]
	v_mfma_f32_16x16x32_bf16 v[64:67], v[218:221], v[202:205], v[64:67]
	v_mfma_f32_16x16x32_bf16 v[68:71], v[210:213], v[202:205], v[68:71]
	v_mfma_f32_16x16x32_bf16 v[116:119], v[214:217], v[180:183], v[116:119]
	v_mfma_f32_16x16x32_bf16 v[112:115], v[222:225], v[180:183], v[112:115]
	v_mfma_f32_16x16x32_bf16 v[96:99], v[222:225], v[188:191], v[96:99]
	v_mfma_f32_16x16x32_bf16 v[100:103], v[214:217], v[188:191], v[100:103]
	v_mfma_f32_16x16x32_bf16 v[84:87], v[214:217], v[198:201], v[84:87]
	v_mfma_f32_16x16x32_bf16 v[80:83], v[222:225], v[198:201], v[80:83]
	v_mfma_f32_16x16x32_bf16 v[64:67], v[222:225], v[206:209], v[64:67]
	v_mfma_f32_16x16x32_bf16 v[68:71], v[214:217], v[206:209], v[68:71]
	s_mov_b32 m0, s23
	v_lshl_add_u64 v[144:145], v[228:229], 0, s[46:47]
	s_barrier
	ds_read_b128 v[176:179], v154 offset:49152
	ds_read_b128 v[180:183], v154 offset:50176
	ds_read_b128 v[184:187], v154 offset:51200
	ds_read_b128 v[188:191], v154 offset:52224
	ds_read_b128 v[192:195], v154 offset:53248
	ds_read_b128 v[198:201], v154 offset:54272
	ds_read_b128 v[202:205], v154 offset:55296
	ds_read_b128 v[206:209], v154 offset:56320
	global_load_lds_dwordx4 v[144:145], off
	v_lshl_add_u64 v[144:145], v[230:231], 0, s[46:47]
	s_mov_b32 m0, s24
	s_nop 0
	global_load_lds_dwordx4 v[144:145], off
	s_barrier
	s_waitcnt lgkmcnt(0)
	v_mfma_f32_16x16x32_bf16 v[60:63], v[160:163], v[176:179], v[60:63]
	v_mfma_f32_16x16x32_bf16 v[56:59], v[168:171], v[176:179], v[56:59]
	v_mfma_f32_16x16x32_bf16 v[40:43], v[168:171], v[184:187], v[40:43]
	v_mfma_f32_16x16x32_bf16 v[44:47], v[160:163], v[184:187], v[44:47]
	v_mfma_f32_16x16x32_bf16 v[28:31], v[160:163], v[192:195], v[28:31]
	v_mfma_f32_16x16x32_bf16 v[24:27], v[168:171], v[192:195], v[24:27]
	v_mfma_f32_16x16x32_bf16 v[8:11], v[168:171], v[202:205], v[8:11]
	v_mfma_f32_16x16x32_bf16 v[12:15], v[160:163], v[202:205], v[12:15]
	v_mfma_f32_16x16x32_bf16 v[60:63], v[164:167], v[180:183], v[60:63]
	v_mfma_f32_16x16x32_bf16 v[56:59], v[172:175], v[180:183], v[56:59]
	v_mfma_f32_16x16x32_bf16 v[40:43], v[172:175], v[188:191], v[40:43]
	v_mfma_f32_16x16x32_bf16 v[44:47], v[164:167], v[188:191], v[44:47]
	v_mfma_f32_16x16x32_bf16 v[28:31], v[164:167], v[198:201], v[28:31]
	v_mfma_f32_16x16x32_bf16 v[24:27], v[172:175], v[198:201], v[24:27]
	v_mfma_f32_16x16x32_bf16 v[8:11], v[172:175], v[206:209], v[8:11]
	v_mfma_f32_16x16x32_bf16 v[12:15], v[164:167], v[206:209], v[12:15]
	s_barrier
	s_add_i32 s16, s50, s18
	v_lshl_add_u64 v[144:145], v[232:233], 0, s[46:47]
	s_mov_b32 m0, s16
	s_nop 0
	global_load_lds_dwordx4 v[144:145], off
	v_lshl_add_u64 v[144:145], v[234:235], 0, s[46:47]
	s_add_i32 m0, s16, 0x2000
	s_nop 0
	global_load_lds_dwordx4 v[144:145], off
	s_waitcnt vmcnt(6)
	s_barrier
	v_mfma_f32_16x16x32_bf16 v[52:55], v[210:213], v[176:179], v[52:55]
	v_mfma_f32_16x16x32_bf16 v[48:51], v[218:221], v[176:179], v[48:51]
	v_mfma_f32_16x16x32_bf16 v[32:35], v[218:221], v[184:187], v[32:35]
	v_mfma_f32_16x16x32_bf16 v[36:39], v[210:213], v[184:187], v[36:39]
	v_mfma_f32_16x16x32_bf16 v[20:23], v[210:213], v[192:195], v[20:23]
	v_mfma_f32_16x16x32_bf16 v[16:19], v[218:221], v[192:195], v[16:19]
	v_mfma_f32_16x16x32_bf16 v[0:3], v[218:221], v[202:205], v[0:3]
	v_mfma_f32_16x16x32_bf16 v[4:7], v[210:213], v[202:205], v[4:7]
	v_mfma_f32_16x16x32_bf16 v[52:55], v[214:217], v[180:183], v[52:55]
	v_mfma_f32_16x16x32_bf16 v[48:51], v[222:225], v[180:183], v[48:51]
	v_mfma_f32_16x16x32_bf16 v[32:35], v[222:225], v[188:191], v[32:35]
	v_mfma_f32_16x16x32_bf16 v[36:39], v[214:217], v[188:191], v[36:39]
	v_mfma_f32_16x16x32_bf16 v[20:23], v[214:217], v[198:201], v[20:23]
	v_mfma_f32_16x16x32_bf16 v[16:19], v[222:225], v[198:201], v[16:19]
	v_mfma_f32_16x16x32_bf16 v[0:3], v[222:225], v[206:209], v[0:3]
	v_mfma_f32_16x16x32_bf16 v[4:7], v[214:217], v[206:209], v[4:7]
	s_add_u32 s14, s14, 0x100
	s_addc_u32 s15, s15, 0
	s_add_u32 s64, s64, 0x100
	s_addc_u32 s65, s65, 0
	s_cmp_ge_i32 s77, s25
	s_mov_b32 s16, s77
	s_barrier
	s_cbranch_scc0 .LBB0_744
	v_readlane_b32 s78, v240, 54
	v_readlane_b32 s79, v240, 55

; #define PG8_STAGE(bufoff, gbase, voff) do { _Pragma("unroll") for (int _i = 0; _i < 2; ++_i) \
;         __builtin_amdgcn_global_load_lds((const unsigned*)((const char*)(gbase) + (voff)[_i]), (LAS unsigned*)(lds + (bufoff) + ldsw + _i * 8192), 16, 0, 0); } while (0)
; #define PG8_LDA(dst, b, h) do { _Pragma("unroll") for (int m = 0; m < 4; ++m) _Pragma("unroll") for (int k = 0; k < 2; ++k) dst[m][k] = *(const LAS bf16x8*)(lds + PG8_SA(b, h) + aoff + m * 2048 + k * 1024); } while (0)
; #define PG8_LDB(dst, b, h) do { _Pragma("unroll") for (int n = 0; n < 2; ++n) _Pragma("unroll") for (int k = 0; k < 2; ++k) dst[n][k] = *(const LAS bf16x8*)(lds + PG8_SB(b, h) + boff + n * 2048 + k * 1024); } while (0)
; #define PG8_MMA(ai, bj, At, Bt) do { __builtin_amdgcn_s_setprio(1); _Pragma("unroll") for (int m = 0; m < 4; ++m) _Pragma("unroll") for (int n = 0; n < 2; ++n) _Pragma("unroll") for (int k = 0; k < 2; ++k) \
;         acc[ai][bj][m][n] = __builtin_amdgcn_mfma_f32_16x16x32_bf16(Bt[n][k], At[m][k], acc[ai][bj][m][n], 0, 0, 0); __builtin_amdgcn_s_setprio(0); } while (0)
; #define PG8_WAIT_L(n) asm volatile("s_waitcnt lgkmcnt(" #n ")" ::: "memory")
; #define PG8_BAR __builtin_amdgcn_s_barrier()
; #define PG8_SCHED __builtin_amdgcn_sched_barrier(0)
; template <class Epi>
; DEVI void gemm_phase(LAS unsigned char* lds, const bf16_t* gA, const bf16_t* gBt, const int lda, const int ldb, const int K, const StaticOrder S_, const Epi E) {
;     ...
;         for (int t = 0; t < nt; t += 2) {
;             const bool last = (t == nt - 2);
;             const char* a1 = cA + (size_t)(t + 1) * kstep;
;             const char* a2 = last ? nA : cA + (size_t)(t + 2) * kstep; const char* b2 = last ? nB : cB + (size_t)(t + 2) * kstep;
;             const char* a3 = a2 + kstep; const char* b3 = b2 + kstep;
;             PG8_LDB(B0, 0, 0); PG8_SCHED; PG8_LDA(At, 0, 0); PG8_STAGE(PG8_SA(1, 1), a1 + hstepA, voffA);
;             PG8_WAIT_L(8); PG8_BAR; PG8_WAIT_L(0); PG8_MMA(0, 0, At, B0); PG8_BAR; PG8_SCHED;
;             PG8_LDB(B1, 0, 1); PG8_STAGE(PG8_SB(0, 0), b2, voffB);
;             PG8_BAR; PG8_WAIT_L(0); PG8_MMA(0, 1, At, B1); PG8_BAR;
;             PG8_LDA(At, 0, 1); PG8_STAGE(PG8_SA(0, 0), a2, voffA);
;             PG8_BAR; PG8_WAIT_L(0); PG8_MMA(1, 0, At, B0); PG8_BAR; PG8_SCHED;
.LBB0_800:
	ds_read_b128 v[160:163], v153
	ds_read_b128 v[164:167], v153 offset:1024
	ds_read_b128 v[168:171], v153 offset:2048
	ds_read_b128 v[172:175], v153 offset:3072
	s_add_i32 s76, s16, 2
	s_add_u32 s40, s14, 0x80
	s_addc_u32 s17, s15, 0
	s_cmp_eq_u32 s26, s16
	s_cselect_b32 s16, s48, s40
	s_cselect_b32 s17, s49, s17
	s_cselect_b32 s41, s61, s65
	s_cselect_b32 s40, s60, s64
	v_lshl_add_u64 v[144:145], s[14:15], 0, v[138:139]
	s_add_i32 m0, s19, 0xc000
	ds_read_b128 v[176:179], v154
	ds_read_b128 v[180:183], v154 offset:1024
	ds_read_b128 v[184:187], v154 offset:2048
	ds_read_b128 v[188:191], v154 offset:3072
	ds_read_b128 v[192:195], v154 offset:4096
	ds_read_b128 v[198:201], v154 offset:5120
	ds_read_b128 v[202:205], v154 offset:6144
	ds_read_b128 v[206:209], v154 offset:7168
	global_load_lds_dwordx4 v[144:145], off
	v_lshl_add_u64 v[144:145], s[14:15], 0, v[140:141]
	s_add_i32 m0, s19, 0xe000
	s_nop 0
	global_load_lds_dwordx4 v[144:145], off
	s_waitcnt lgkmcnt(8)
	s_barrier
	s_waitcnt lgkmcnt(0)
	v_mfma_f32_16x16x32_bf16 v[124:127], v[160:163], v[176:179], v[124:127]
	v_mfma_f32_16x16x32_bf16 v[120:123], v[168:171], v[176:179], v[120:123]
	v_mfma_f32_16x16x32_bf16 v[104:107], v[168:171], v[184:187], v[104:107]
	v_mfma_f32_16x16x32_bf16 v[108:111], v[160:163], v[184:187], v[108:111]
	v_mfma_f32_16x16x32_bf16 v[92:95], v[160:163], v[192:195], v[92:95]
	v_mfma_f32_16x16x32_bf16 v[88:91], v[168:171], v[192:195], v[88:91]
	v_mfma_f32_16x16x32_bf16 v[72:75], v[168:171], v[202:205], v[72:75]
	v_mfma_f32_16x16x32_bf16 v[76:79], v[160:163], v[202:205], v[76:79]
	v_mfma_f32_16x16x32_bf16 v[124:127], v[164:167], v[180:183], v[124:127]
	v_mfma_f32_16x16x32_bf16 v[120:123], v[172:175], v[180:183], v[120:123]
	v_mfma_f32_16x16x32_bf16 v[104:107], v[172:175], v[188:191], v[104:107]
	v_mfma_f32_16x16x32_bf16 v[108:111], v[164:167], v[188:191], v[108:111]
	v_mfma_f32_16x16x32_bf16 v[92:95], v[164:167], v[198:201], v[92:95]
	v_mfma_f32_16x16x32_bf16 v[88:91], v[172:175], v[198:201], v[88:91]
	v_mfma_f32_16x16x32_bf16 v[72:75], v[172:175], v[206:209], v[72:75]
	v_mfma_f32_16x16x32_bf16 v[76:79], v[164:167], v[206:209], v[76:79]
	s_barrier
	s_add_i32 s77, s31, s18
	v_lshl_add_u64 v[144:145], s[40:41], 0, v[130:131]
	s_mov_b32 m0, s77
	ds_read_b128 v[210:213], v155
	ds_read_b128 v[214:217], v155 offset:1024
	ds_read_b128 v[218:221], v155 offset:2048
	ds_read_b128 v[222:225], v155 offset:3072
	global_load_lds_dwordx4 v[144:145], off
	v_lshl_add_u64 v[226:227], s[40:41], 0, v[134:135]
	s_add_i32 m0, s77, 0x2000
	s_nop 0
	global_load_lds_dwordx4 v[226:227], off
	s_barrier
	s_waitcnt lgkmcnt(0)
	v_mfma_f32_16x16x32_bf16 v[116:119], v[210:213], v[176:179], v[116:119]
	v_mfma_f32_16x16x32_bf16 v[112:115], v[218:221], v[176:179], v[112:115]
	v_mfma_f32_16x16x32_bf16 v[96:99], v[218:221], v[184:187], v[96:99]
	v_mfma_f32_16x16x32_bf16 v[100:103], v[210:213], v[184:187], v[100:103]
	v_mfma_f32_16x16x32_bf16 v[84:87], v[210:213], v[192:195], v[84:87]
	v_mfma_f32_16x16x32_bf16 v[80:83], v[218:221], v[192:195], v[80:83]
	v_mfma_f32_16x16x32_bf16 v[64:67], v[218:221], v[202:205], v[64:67]
	v_mfma_f32_16x16x32_bf16 v[68:71], v[210:213], v[202:205], v[68:71]
	v_mfma_f32_16x16x32_bf16 v[116:119], v[214:217], v[180:183], v[116:119]
	v_mfma_f32_16x16x32_bf16 v[112:115], v[222:225], v[180:183], v[112:115]
	v_mfma_f32_16x16x32_bf16 v[96:99], v[222:225], v[188:191], v[96:99]
	v_mfma_f32_16x16x32_bf16 v[100:103], v[214:217], v[188:191], v[100:103]
	v_mfma_f32_16x16x32_bf16 v[84:87], v[214:217], v[198:201], v[84:87]
	v_mfma_f32_16x16x32_bf16 v[80:83], v[222:225], v[198:201], v[80:83]
	v_mfma_f32_16x16x32_bf16 v[64:67], v[222:225], v[206:209], v[64:67]
	v_mfma_f32_16x16x32_bf16 v[68:71], v[214:217], v[206:209], v[68:71]
	s_mov_b32 m0, s19
	v_lshl_add_u64 v[228:229], s[16:17], 0, v[128:129]
	s_barrier
	ds_read_b128 v[176:179], v154 offset:16384
	ds_read_b128 v[180:183], v154 offset:17408
	ds_read_b128 v[184:187], v154 offset:18432
	ds_read_b128 v[188:191], v154 offset:19456
	ds_read_b128 v[192:195], v154 offset:20480
	ds_read_b128 v[198:201], v154 offset:21504
	ds_read_b128 v[202:205], v154 offset:22528
	ds_read_b128 v[206:209], v154 offset:23552
	global_load_lds_dwordx4 v[228:229], off
	v_lshl_add_u64 v[230:231], s[16:17], 0, v[132:133]
	s_mov_b32 m0, s20
	s_nop 0
	global_load_lds_dwordx4 v[230:231], off
	s_barrier
	s_waitcnt lgkmcnt(0)
	v_mfma_f32_16x16x32_bf16 v[60:63], v[160:163], v[176:179], v[60:63]
	v_mfma_f32_16x16x32_bf16 v[56:59], v[168:171], v[176:179], v[56:59]
	v_mfma_f32_16x16x32_bf16 v[40:43], v[168:171], v[184:187], v[40:43]
	v_mfma_f32_16x16x32_bf16 v[44:47], v[160:163], v[184:187], v[44:47]
	v_mfma_f32_16x16x32_bf16 v[28:31], v[160:163], v[192:195], v[28:31]
	v_mfma_f32_16x16x32_bf16 v[24:27], v[168:171], v[192:195], v[24:27]
	v_mfma_f32_16x16x32_bf16 v[8:11], v[168:171], v[202:205], v[8:11]
	v_mfma_f32_16x16x32_bf16 v[12:15], v[160:163], v[202:205], v[12:15]
	v_mfma_f32_16x16x32_bf16 v[60:63], v[164:167], v[180:183], v[60:63]
	v_mfma_f32_16x16x32_bf16 v[56:59], v[172:175], v[180:183], v[56:59]
	v_mfma_f32_16x16x32_bf16 v[40:43], v[172:175], v[188:191], v[40:43]
	v_mfma_f32_16x16x32_bf16 v[44:47], v[164:167], v[188:191], v[44:47]
	v_mfma_f32_16x16x32_bf16 v[28:31], v[164:167], v[198:201], v[28:31]
	v_mfma_f32_16x16x32_bf16 v[24:27], v[172:175], v[198:201], v[24:27]
	v_mfma_f32_16x16x32_bf16 v[8:11], v[172:175], v[206:209], v[8:11]
	v_mfma_f32_16x16x32_bf16 v[12:15], v[164:167], v[206:209], v[12:15]
	s_barrier
; #define PG8_STAGE(bufoff, gbase, voff) do { _Pragma("unroll") for (int _i = 0; _i < 2; ++_i) \
;         __builtin_amdgcn_global_load_lds((const unsigned*)((const char*)(gbase) + (voff)[_i]), (LAS unsigned*)(lds + (bufoff) + ldsw + _i * 8192), 16, 0, 0); } while (0)
; #define PG8_LDA(dst, b, h) do { _Pragma("unroll") for (int m = 0; m < 4; ++m) _Pragma("unroll") for (int k = 0; k < 2; ++k) dst[m][k] = *(const LAS bf16x8*)(lds + PG8_SA(b, h) + aoff + m * 2048 + k * 1024); } while (0)
; #define PG8_LDB(dst, b, h) do { _Pragma("unroll") for (int n = 0; n < 2; ++n) _Pragma("unroll") for (int k = 0; k < 2; ++k) dst[n][k] = *(const LAS bf16x8*)(lds + PG8_SB(b, h) + boff + n * 2048 + k * 1024); } while (0)
; #define PG8_MMA(ai, bj, At, Bt) do { __builtin_amdgcn_s_setprio(1); _Pragma("unroll") for (int m = 0; m < 4; ++m) _Pragma("unroll") for (int n = 0; n < 2; ++n) _Pragma("unroll") for (int k = 0; k < 2; ++k) \
;         acc[ai][bj][m][n] = __builtin_amdgcn_mfma_f32_16x16x32_bf16(Bt[n][k], At[m][k], acc[ai][bj][m][n], 0, 0, 0); __builtin_amdgcn_s_setprio(0); } while (0)
; #define PG8_WAIT_V(n) asm volatile("s_waitcnt vmcnt(" #n ")" ::: "memory")
; #define PG8_WAIT_L(n) asm volatile("s_waitcnt lgkmcnt(" #n ")" ::: "memory")
; #define PG8_BAR __builtin_amdgcn_s_barrier()
; #define PG8_SCHED __builtin_amdgcn_sched_barrier(0)
; template <class Epi>
; DEVI void gemm_phase(LAS unsigned char* lds, const bf16_t* gA, const bf16_t* gBt, const int lda, const int ldb, const int K, const StaticOrder S_, const Epi E) {
;     ...
;             PG8_STAGE(PG8_SB(0, 1), b2 + hstepB, voffB);
;             PG8_WAIT_V(6); PG8_BAR; PG8_MMA(1, 1, At, B1); PG8_BAR;
;             PG8_LDB(B0, 1, 0); PG8_SCHED; PG8_LDA(At, 1, 0); PG8_STAGE(PG8_SA(0, 1), a2 + hstepA, voffA);
;             PG8_WAIT_L(8); PG8_BAR; PG8_WAIT_L(0); PG8_MMA(0, 0, At, B0); PG8_BAR; PG8_SCHED;
;             PG8_LDB(B1, 1, 1); PG8_STAGE(PG8_SB(1, 0), b3, voffB);
;             PG8_BAR; PG8_WAIT_L(0); PG8_MMA(0, 1, At, B1); PG8_BAR;
;             PG8_LDA(At, 1, 1); PG8_STAGE(PG8_SA(1, 0), a3, voffA);
;             PG8_BAR; PG8_WAIT_L(0); PG8_MMA(1, 0, At, B0); PG8_BAR; PG8_SCHED;
;             PG8_STAGE(PG8_SB(1, 1), b3 + hstepB, voffB);
	s_add_u32 s40, s40, s2
	s_addc_u32 s41, s41, s3
	s_add_i32 s77, s34, s18
	v_lshl_add_u64 v[232:233], s[40:41], 0, v[130:131]
	s_mov_b32 m0, s77
	v_lshl_add_u64 v[234:235], s[40:41], 0, v[134:135]
	global_load_lds_dwordx4 v[232:233], off
	s_add_i32 m0, s77, 0x2000
	s_nop 0
	global_load_lds_dwordx4 v[234:235], off
	s_waitcnt vmcnt(6)
	s_barrier
	v_mfma_f32_16x16x32_bf16 v[52:55], v[210:213], v[176:179], v[52:55]
	v_mfma_f32_16x16x32_bf16 v[48:51], v[218:221], v[176:179], v[48:51]
	v_mfma_f32_16x16x32_bf16 v[32:35], v[218:221], v[184:187], v[32:35]
	v_mfma_f32_16x16x32_bf16 v[36:39], v[210:213], v[184:187], v[36:39]
	v_mfma_f32_16x16x32_bf16 v[20:23], v[210:213], v[192:195], v[20:23]
	v_mfma_f32_16x16x32_bf16 v[16:19], v[218:221], v[192:195], v[16:19]
	v_mfma_f32_16x16x32_bf16 v[0:3], v[218:221], v[202:205], v[0:3]
	v_mfma_f32_16x16x32_bf16 v[4:7], v[210:213], v[202:205], v[4:7]
	v_mfma_f32_16x16x32_bf16 v[52:55], v[214:217], v[180:183], v[52:55]
	v_mfma_f32_16x16x32_bf16 v[48:51], v[222:225], v[180:183], v[48:51]
	v_mfma_f32_16x16x32_bf16 v[32:35], v[222:225], v[188:191], v[32:35]
	v_mfma_f32_16x16x32_bf16 v[36:39], v[214:217], v[188:191], v[36:39]
	v_mfma_f32_16x16x32_bf16 v[20:23], v[214:217], v[198:201], v[20:23]
	v_mfma_f32_16x16x32_bf16 v[16:19], v[222:225], v[198:201], v[16:19]
	v_mfma_f32_16x16x32_bf16 v[0:3], v[222:225], v[206:209], v[0:3]
	v_mfma_f32_16x16x32_bf16 v[4:7], v[214:217], v[206:209], v[4:7]
	s_barrier
	ds_read_b128 v[160:163], v156
	ds_read_b128 v[164:167], v156 offset:1024
	ds_read_b128 v[168:171], v156 offset:2048
	ds_read_b128 v[172:175], v156 offset:3072
	s_add_u32 s16, s16, s0
	s_addc_u32 s17, s17, s1
	s_mov_b32 m0, s21
	v_lshl_add_u64 v[210:211], s[16:17], 0, v[128:129]
	ds_read_b128 v[176:179], v154 offset:32768
	ds_read_b128 v[180:183], v154 offset:33792
	ds_read_b128 v[184:187], v154 offset:34816
	ds_read_b128 v[188:191], v154 offset:35840
	ds_read_b128 v[192:195], v154 offset:36864
	ds_read_b128 v[198:201], v154 offset:37888
	ds_read_b128 v[202:205], v154 offset:38912
	ds_read_b128 v[206:209], v154 offset:39936
	global_load_lds_dwordx4 v[210:211], off
	v_lshl_add_u64 v[210:211], s[16:17], 0, v[132:133]
	s_mov_b32 m0, s22
	s_nop 0
	global_load_lds_dwordx4 v[210:211], off
	s_waitcnt lgkmcnt(8)
	s_barrier
	s_waitcnt lgkmcnt(0)
	v_mfma_f32_16x16x32_bf16 v[124:127], v[160:163], v[176:179], v[124:127]
	v_mfma_f32_16x16x32_bf16 v[120:123], v[168:171], v[176:179], v[120:123]
	v_mfma_f32_16x16x32_bf16 v[104:107], v[168:171], v[184:187], v[104:107]
	v_mfma_f32_16x16x32_bf16 v[108:111], v[160:163], v[184:187], v[108:111]
	v_mfma_f32_16x16x32_bf16 v[92:95], v[160:163], v[192:195], v[92:95]
	v_mfma_f32_16x16x32_bf16 v[88:91], v[168:171], v[192:195], v[88:91]
	v_mfma_f32_16x16x32_bf16 v[72:75], v[168:171], v[202:205], v[72:75]
	v_mfma_f32_16x16x32_bf16 v[76:79], v[160:163], v[202:205], v[76:79]
	v_mfma_f32_16x16x32_bf16 v[124:127], v[164:167], v[180:183], v[124:127]
	v_mfma_f32_16x16x32_bf16 v[120:123], v[172:175], v[180:183], v[120:123]
	v_mfma_f32_16x16x32_bf16 v[104:107], v[172:175], v[188:191], v[104:107]
	v_mfma_f32_16x16x32_bf16 v[108:111], v[164:167], v[188:191], v[108:111]
	v_mfma_f32_16x16x32_bf16 v[92:95], v[164:167], v[198:201], v[92:95]
	v_mfma_f32_16x16x32_bf16 v[88:91], v[172:175], v[198:201], v[88:91]
	v_mfma_f32_16x16x32_bf16 v[72:75], v[172:175], v[206:209], v[72:75]
	v_mfma_f32_16x16x32_bf16 v[76:79], v[164:167], v[206:209], v[76:79]
	s_barrier
	s_add_i32 s16, s35, s18
	v_lshl_add_u64 v[144:145], v[144:145], 0, s[46:47]
	s_mov_b32 m0, s16
	ds_read_b128 v[210:213], v157
	ds_read_b128 v[214:217], v157 offset:1024
	ds_read_b128 v[218:221], v157 offset:2048
	ds_read_b128 v[222:225], v157 offset:3072
	global_load_lds_dwordx4 v[144:145], off
	v_lshl_add_u64 v[144:145], v[226:227], 0, s[46:47]
	s_add_i32 m0, s16, 0x2000
	s_nop 0
	global_load_lds_dwordx4 v[144:145], off
	s_barrier
; #define PG8_STAGE(bufoff, gbase, voff) do { _Pragma("unroll") for (int _i = 0; _i < 2; ++_i) \
;         __builtin_amdgcn_global_load_lds((const unsigned*)((const char*)(gbase) + (voff)[_i]), (LAS unsigned*)(lds + (bufoff) + ldsw + _i * 8192), 16, 0, 0); } while (0)
; #define PG8_LDA(dst, b, h) do { _Pragma("unroll") for (int m = 0; m < 4; ++m) _Pragma("unroll") for (int k = 0; k < 2; ++k) dst[m][k] = *(const LAS bf16x8*)(lds + PG8_SA(b, h) + aoff + m * 2048 + k * 1024); } while (0)
; #define PG8_MMA(ai, bj, At, Bt) do { __builtin_amdgcn_s_setprio(1); _Pragma("unroll") for (int m = 0; m < 4; ++m) _Pragma("unroll") for (int n = 0; n < 2; ++n) _Pragma("unroll") for (int k = 0; k < 2; ++k) \
;         acc[ai][bj][m][n] = __builtin_amdgcn_mfma_f32_16x16x32_bf16(Bt[n][k], At[m][k], acc[ai][bj][m][n], 0, 0, 0); __builtin_amdgcn_s_setprio(0); } while (0)
; #define PG8_WAIT_V(n) asm volatile("s_waitcnt vmcnt(" #n ")" ::: "memory")
; #define PG8_WAIT_L(n) asm volatile("s_waitcnt lgkmcnt(" #n ")" ::: "memory")
; #define PG8_BAR __builtin_amdgcn_s_barrier()
; #define PG8_SCHED __builtin_amdgcn_sched_barrier(0)
; template <class Epi>
; DEVI void gemm_phase(LAS unsigned char* lds, const bf16_t* gA, const bf16_t* gBt, const int lda, const int ldb, const int K, const StaticOrder S_, const Epi E) {
;     ...
;             PG8_BAR; PG8_WAIT_L(0); PG8_MMA(0, 1, At, B1); PG8_BAR;
;             PG8_LDA(At, 1, 1); PG8_STAGE(PG8_SA(1, 0), a3, voffA);
;             PG8_BAR; PG8_WAIT_L(0); PG8_MMA(1, 0, At, B0); PG8_BAR; PG8_SCHED;
;             PG8_STAGE(PG8_SB(1, 1), b3 + hstepB, voffB);
;             PG8_WAIT_V(6); PG8_BAR; PG8_MMA(1, 1, At, B1); PG8_BAR;
	s_waitcnt lgkmcnt(0)
	v_mfma_f32_16x16x32_bf16 v[116:119], v[210:213], v[176:179], v[116:119]
	v_mfma_f32_16x16x32_bf16 v[112:115], v[218:221], v[176:179], v[112:115]
	v_mfma_f32_16x16x32_bf16 v[96:99], v[218:221], v[184:187], v[96:99]
	v_mfma_f32_16x16x32_bf16 v[100:103], v[210:213], v[184:187], v[100:103]
	v_mfma_f32_16x16x32_bf16 v[84:87], v[210:213], v[192:195], v[84:87]
	v_mfma_f32_16x16x32_bf16 v[80:83], v[218:221], v[192:195], v[80:83]
	v_mfma_f32_16x16x32_bf16 v[64:67], v[218:221], v[202:205], v[64:67]
	v_mfma_f32_16x16x32_bf16 v[68:71], v[210:213], v[202:205], v[68:71]
	v_mfma_f32_16x16x32_bf16 v[116:119], v[214:217], v[180:183], v[116:119]
	v_mfma_f32_16x16x32_bf16 v[112:115], v[222:225], v[180:183], v[112:115]
	v_mfma_f32_16x16x32_bf16 v[96:99], v[222:225], v[188:191], v[96:99]
	v_mfma_f32_16x16x32_bf16 v[100:103], v[214:217], v[188:191], v[100:103]
	v_mfma_f32_16x16x32_bf16 v[84:87], v[214:217], v[198:201], v[84:87]
	v_mfma_f32_16x16x32_bf16 v[80:83], v[222:225], v[198:201], v[80:83]
	v_mfma_f32_16x16x32_bf16 v[64:67], v[222:225], v[206:209], v[64:67]
	v_mfma_f32_16x16x32_bf16 v[68:71], v[214:217], v[206:209], v[68:71]
	s_mov_b32 m0, s23
	v_lshl_add_u64 v[144:145], v[228:229], 0, s[46:47]
	s_barrier
	ds_read_b128 v[176:179], v154 offset:49152
	ds_read_b128 v[180:183], v154 offset:50176
	ds_read_b128 v[184:187], v154 offset:51200
	ds_read_b128 v[188:191], v154 offset:52224
	ds_read_b128 v[192:195], v154 offset:53248
	ds_read_b128 v[198:201], v154 offset:54272
	ds_read_b128 v[202:205], v154 offset:55296
	ds_read_b128 v[206:209], v154 offset:56320
	global_load_lds_dwordx4 v[144:145], off
	v_lshl_add_u64 v[144:145], v[230:231], 0, s[46:47]
	s_mov_b32 m0, s24
	s_nop 0
	global_load_lds_dwordx4 v[144:145], off
	s_barrier
	s_waitcnt lgkmcnt(0)
	v_mfma_f32_16x16x32_bf16 v[60:63], v[160:163], v[176:179], v[60:63]
	v_mfma_f32_16x16x32_bf16 v[56:59], v[168:171], v[176:179], v[56:59]
	v_mfma_f32_16x16x32_bf16 v[40:43], v[168:171], v[184:187], v[40:43]
	v_mfma_f32_16x16x32_bf16 v[44:47], v[160:163], v[184:187], v[44:47]
	v_mfma_f32_16x16x32_bf16 v[28:31], v[160:163], v[192:195], v[28:31]
	v_mfma_f32_16x16x32_bf16 v[24:27], v[168:171], v[192:195], v[24:27]
	v_mfma_f32_16x16x32_bf16 v[8:11], v[168:171], v[202:205], v[8:11]
	v_mfma_f32_16x16x32_bf16 v[12:15], v[160:163], v[202:205], v[12:15]
	v_mfma_f32_16x16x32_bf16 v[60:63], v[164:167], v[180:183], v[60:63]
	v_mfma_f32_16x16x32_bf16 v[56:59], v[172:175], v[180:183], v[56:59]
	v_mfma_f32_16x16x32_bf16 v[40:43], v[172:175], v[188:191], v[40:43]
	v_mfma_f32_16x16x32_bf16 v[44:47], v[164:167], v[188:191], v[44:47]
	v_mfma_f32_16x16x32_bf16 v[28:31], v[164:167], v[198:201], v[28:31]
	v_mfma_f32_16x16x32_bf16 v[24:27], v[172:175], v[198:201], v[24:27]
	v_mfma_f32_16x16x32_bf16 v[8:11], v[172:175], v[206:209], v[8:11]
	v_mfma_f32_16x16x32_bf16 v[12:15], v[164:167], v[206:209], v[12:15]
	s_barrier
	s_add_i32 s16, s50, s18
	v_lshl_add_u64 v[144:145], v[232:233], 0, s[46:47]
	s_mov_b32 m0, s16
	s_nop 0
	global_load_lds_dwordx4 v[144:145], off
	v_lshl_add_u64 v[144:145], v[234:235], 0, s[46:47]
	s_add_i32 m0, s16, 0x2000
	s_nop 0
	global_load_lds_dwordx4 v[144:145], off
	s_waitcnt vmcnt(6)
	s_barrier
	v_mfma_f32_16x16x32_bf16 v[52:55], v[210:213], v[176:179], v[52:55]
	v_mfma_f32_16x16x32_bf16 v[48:51], v[218:221], v[176:179], v[48:51]
	v_mfma_f32_16x16x32_bf16 v[32:35], v[218:221], v[184:187], v[32:35]
	v_mfma_f32_16x16x32_bf16 v[36:39], v[210:213], v[184:187], v[36:39]
	v_mfma_f32_16x16x32_bf16 v[20:23], v[210:213], v[192:195], v[20:23]
	v_mfma_f32_16x16x32_bf16 v[16:19], v[218:221], v[192:195], v[16:19]
	v_mfma_f32_16x16x32_bf16 v[0:3], v[218:221], v[202:205], v[0:3]
	v_mfma_f32_16x16x32_bf16 v[4:7], v[210:213], v[202:205], v[4:7]
	v_mfma_f32_16x16x32_bf16 v[52:55], v[214:217], v[180:183], v[52:55]
	v_mfma_f32_16x16x32_bf16 v[48:51], v[222:225], v[180:183], v[48:51]
	v_mfma_f32_16x16x32_bf16 v[32:35], v[222:225], v[188:191], v[32:35]
	v_mfma_f32_16x16x32_bf16 v[36:39], v[214:217], v[188:191], v[36:39]
	v_mfma_f32_16x16x32_bf16 v[20:23], v[214:217], v[198:201], v[20:23]
	v_mfma_f32_16x16x32_bf16 v[16:19], v[222:225], v[198:201], v[16:19]
	v_mfma_f32_16x16x32_bf16 v[0:3], v[222:225], v[206:209], v[0:3]
	v_mfma_f32_16x16x32_bf16 v[4:7], v[214:217], v[206:209], v[4:7]
	s_add_u32 s14, s14, 0x100
	s_addc_u32 s15, s15, 0
	s_add_u32 s64, s64, 0x100
	s_addc_u32 s65, s65, 0
	s_cmp_ge_i32 s76, s25
	s_mov_b32 s16, s76
	s_barrier
	s_cbranch_scc0 .LBB0_800

; #define PG8_STAGE(bufoff, gbase, voff) do { _Pragma("unroll") for (int _i = 0; _i < 2; ++_i) \
;         __builtin_amdgcn_global_load_lds((const unsigned*)((const char*)(gbase) + (voff)[_i]), (LAS unsigned*)(lds + (bufoff) + ldsw + _i * 8192), 16, 0, 0); } while (0)
; #define PG8_LDA(dst, b, h) do { _Pragma("unroll") for (int m = 0; m < 4; ++m) _Pragma("unroll") for (int k = 0; k < 2; ++k) dst[m][k] = *(const LAS bf16x8*)(lds + PG8_SA(b, h) + aoff + m * 2048 + k * 1024); } while (0)
; #define PG8_LDB(dst, b, h) do { _Pragma("unroll") for (int n = 0; n < 2; ++n) _Pragma("unroll") for (int k = 0; k < 2; ++k) dst[n][k] = *(const LAS bf16x8*)(lds + PG8_SB(b, h) + boff + n * 2048 + k * 1024); } while (0)
; #define PG8_MMA(ai, bj, At, Bt) do { __builtin_amdgcn_s_setprio(1); _Pragma("unroll") for (int m = 0; m < 4; ++m) _Pragma("unroll") for (int n = 0; n < 2; ++n) _Pragma("unroll") for (int k = 0; k < 2; ++k) \
;         acc[ai][bj][m][n] = __builtin_amdgcn_mfma_f32_16x16x32_bf16(Bt[n][k], At[m][k], acc[ai][bj][m][n], 0, 0, 0); __builtin_amdgcn_s_setprio(0); } while (0)
; #define PG8_WAIT_L(n) asm volatile("s_waitcnt lgkmcnt(" #n ")" ::: "memory")
; #define PG8_BAR __builtin_amdgcn_s_barrier()
; #define PG8_SCHED __builtin_amdgcn_sched_barrier(0)
; template <class Epi>
; DEVI void gemm_phase(LAS unsigned char* lds, const bf16_t* gA, const bf16_t* gBt, const int lda, const int ldb, const int K, const StaticOrder S_, const Epi E) {
;     ...
;         for (int t = 0; t < nt; t += 2) {
;             const bool last = (t == nt - 2);
;             const char* a1 = cA + (size_t)(t + 1) * kstep;
;             const char* a2 = last ? nA : cA + (size_t)(t + 2) * kstep; const char* b2 = last ? nB : cB + (size_t)(t + 2) * kstep;
;             const char* a3 = a2 + kstep; const char* b3 = b2 + kstep;
;             PG8_LDB(B0, 0, 0); PG8_SCHED; PG8_LDA(At, 0, 0); PG8_STAGE(PG8_SA(1, 1), a1 + hstepA, voffA);
;             PG8_WAIT_L(8); PG8_BAR; PG8_WAIT_L(0); PG8_MMA(0, 0, At, B0); PG8_BAR; PG8_SCHED;
;             PG8_LDB(B1, 0, 1); PG8_STAGE(PG8_SB(0, 0), b2, voffB);
;             PG8_BAR; PG8_WAIT_L(0); PG8_MMA(0, 1, At, B1); PG8_BAR;
;             PG8_LDA(At, 0, 1); PG8_STAGE(PG8_SA(0, 0), a2, voffA);
;             PG8_BAR; PG8_WAIT_L(0); PG8_MMA(1, 0, At, B0); PG8_BAR; PG8_SCHED;
.LBB0_1301:
	ds_read_b128 v[128:131], v201
	ds_read_b128 v[132:135], v201 offset:1024
	ds_read_b128 v[136:139], v201 offset:2048
	ds_read_b128 v[140:143], v201 offset:3072
	s_add_i32 s72, s16, 2
	s_add_u32 s40, s14, 0x80
	s_addc_u32 s17, s15, 0
	s_cmp_eq_u32 s19, s16
	s_cselect_b32 s16, s12, s40
	s_cselect_b32 s17, s13, s17
	s_cselect_b32 s41, s43, s71
	s_cselect_b32 s40, s42, s70
	v_lshl_add_u64 v[164:165], s[14:15], 0, v[174:175]
	s_add_i32 m0, s82, 0xc000
	ds_read_b128 v[144:147], v202
	ds_read_b128 v[148:151], v202 offset:1024
	ds_read_b128 v[152:155], v202 offset:2048
	ds_read_b128 v[156:159], v202 offset:3072
	ds_read_b128 v[160:163], v202 offset:4096
	ds_read_b128 v[180:183], v202 offset:5120
	ds_read_b128 v[184:187], v202 offset:6144
	ds_read_b128 v[188:191], v202 offset:7168
	global_load_lds_dwordx4 v[164:165], off
	v_lshl_add_u64 v[164:165], s[14:15], 0, v[176:177]
	s_add_i32 m0, s82, 0xe000
	s_nop 0
	global_load_lds_dwordx4 v[164:165], off
	s_waitcnt lgkmcnt(8)
	s_barrier
	s_waitcnt lgkmcnt(0)
	v_mfma_f32_16x16x32_bf16 v[124:127], v[128:131], v[144:147], v[124:127]
	v_mfma_f32_16x16x32_bf16 v[120:123], v[136:139], v[144:147], v[120:123]
	v_mfma_f32_16x16x32_bf16 v[104:107], v[136:139], v[152:155], v[104:107]
	v_mfma_f32_16x16x32_bf16 v[108:111], v[128:131], v[152:155], v[108:111]
	v_mfma_f32_16x16x32_bf16 v[92:95], v[128:131], v[160:163], v[92:95]
	v_mfma_f32_16x16x32_bf16 v[88:91], v[136:139], v[160:163], v[88:91]
	v_mfma_f32_16x16x32_bf16 v[72:75], v[136:139], v[184:187], v[72:75]
	v_mfma_f32_16x16x32_bf16 v[76:79], v[128:131], v[184:187], v[76:79]
	v_mfma_f32_16x16x32_bf16 v[124:127], v[132:135], v[148:151], v[124:127]
	v_mfma_f32_16x16x32_bf16 v[120:123], v[140:143], v[148:151], v[120:123]
	v_mfma_f32_16x16x32_bf16 v[104:107], v[140:143], v[156:159], v[104:107]
	v_mfma_f32_16x16x32_bf16 v[108:111], v[132:135], v[156:159], v[108:111]
	v_mfma_f32_16x16x32_bf16 v[92:95], v[132:135], v[180:183], v[92:95]
	v_mfma_f32_16x16x32_bf16 v[88:91], v[140:143], v[180:183], v[88:91]
	v_mfma_f32_16x16x32_bf16 v[72:75], v[140:143], v[188:191], v[72:75]
	v_mfma_f32_16x16x32_bf16 v[76:79], v[132:135], v[188:191], v[76:79]
	s_barrier
	s_add_i32 s73, s29, s20
	v_lshl_add_u64 v[164:165], s[40:41], 0, v[168:169]
	s_mov_b32 m0, s73
	ds_read_b128 v[192:195], v203
	ds_read_b128 v[206:209], v203 offset:1024
	ds_read_b128 v[210:213], v203 offset:2048
	ds_read_b128 v[214:217], v203 offset:3072
	global_load_lds_dwordx4 v[164:165], off
	v_lshl_add_u64 v[218:219], s[40:41], 0, v[172:173]
	s_add_i32 m0, s73, 0x2000
	s_nop 0
	global_load_lds_dwordx4 v[218:219], off
	s_barrier
	s_waitcnt lgkmcnt(0)
	v_mfma_f32_16x16x32_bf16 v[116:119], v[192:195], v[144:147], v[116:119]
	v_mfma_f32_16x16x32_bf16 v[112:115], v[210:213], v[144:147], v[112:115]
	v_mfma_f32_16x16x32_bf16 v[96:99], v[210:213], v[152:155], v[96:99]
	v_mfma_f32_16x16x32_bf16 v[100:103], v[192:195], v[152:155], v[100:103]
	v_mfma_f32_16x16x32_bf16 v[84:87], v[192:195], v[160:163], v[84:87]
	v_mfma_f32_16x16x32_bf16 v[80:83], v[210:213], v[160:163], v[80:83]
	v_mfma_f32_16x16x32_bf16 v[64:67], v[210:213], v[184:187], v[64:67]
	v_mfma_f32_16x16x32_bf16 v[68:71], v[192:195], v[184:187], v[68:71]
	v_mfma_f32_16x16x32_bf16 v[116:119], v[206:209], v[148:151], v[116:119]
	v_mfma_f32_16x16x32_bf16 v[112:115], v[214:217], v[148:151], v[112:115]
	v_mfma_f32_16x16x32_bf16 v[96:99], v[214:217], v[156:159], v[96:99]
	v_mfma_f32_16x16x32_bf16 v[100:103], v[206:209], v[156:159], v[100:103]
	v_mfma_f32_16x16x32_bf16 v[84:87], v[206:209], v[180:183], v[84:87]
	v_mfma_f32_16x16x32_bf16 v[80:83], v[214:217], v[180:183], v[80:83]
	v_mfma_f32_16x16x32_bf16 v[64:67], v[214:217], v[188:191], v[64:67]
	v_mfma_f32_16x16x32_bf16 v[68:71], v[206:209], v[188:191], v[68:71]
	s_mov_b32 m0, s82
	v_lshl_add_u64 v[220:221], s[16:17], 0, v[166:167]
	s_barrier
	ds_read_b128 v[144:147], v202 offset:16384
	ds_read_b128 v[148:151], v202 offset:17408
	ds_read_b128 v[152:155], v202 offset:18432
	ds_read_b128 v[156:159], v202 offset:19456
	ds_read_b128 v[160:163], v202 offset:20480
	ds_read_b128 v[180:183], v202 offset:21504
	ds_read_b128 v[184:187], v202 offset:22528
	ds_read_b128 v[188:191], v202 offset:23552
	global_load_lds_dwordx4 v[220:221], off
	v_lshl_add_u64 v[222:223], s[16:17], 0, v[170:171]
	s_mov_b32 m0, s22
	s_nop 0
	global_load_lds_dwordx4 v[222:223], off
	s_barrier
	s_waitcnt lgkmcnt(0)
	v_mfma_f32_16x16x32_bf16 v[60:63], v[128:131], v[144:147], v[60:63]
	v_mfma_f32_16x16x32_bf16 v[56:59], v[136:139], v[144:147], v[56:59]
	v_mfma_f32_16x16x32_bf16 v[40:43], v[136:139], v[152:155], v[40:43]
	v_mfma_f32_16x16x32_bf16 v[44:47], v[128:131], v[152:155], v[44:47]
	v_mfma_f32_16x16x32_bf16 v[28:31], v[128:131], v[160:163], v[28:31]
	v_mfma_f32_16x16x32_bf16 v[24:27], v[136:139], v[160:163], v[24:27]
	v_mfma_f32_16x16x32_bf16 v[8:11], v[136:139], v[184:187], v[8:11]
	v_mfma_f32_16x16x32_bf16 v[12:15], v[128:131], v[184:187], v[12:15]
	v_mfma_f32_16x16x32_bf16 v[60:63], v[132:135], v[148:151], v[60:63]
	v_mfma_f32_16x16x32_bf16 v[56:59], v[140:143], v[148:151], v[56:59]
	v_mfma_f32_16x16x32_bf16 v[40:43], v[140:143], v[156:159], v[40:43]
	v_mfma_f32_16x16x32_bf16 v[44:47], v[132:135], v[156:159], v[44:47]
	v_mfma_f32_16x16x32_bf16 v[28:31], v[132:135], v[180:183], v[28:31]
	v_mfma_f32_16x16x32_bf16 v[24:27], v[140:143], v[180:183], v[24:27]
	v_mfma_f32_16x16x32_bf16 v[8:11], v[140:143], v[188:191], v[8:11]
	v_mfma_f32_16x16x32_bf16 v[12:15], v[132:135], v[188:191], v[12:15]
	s_barrier
; #define PG8_STAGE(bufoff, gbase, voff) do { _Pragma("unroll") for (int _i = 0; _i < 2; ++_i) \
;         __builtin_amdgcn_global_load_lds((const unsigned*)((const char*)(gbase) + (voff)[_i]), (LAS unsigned*)(lds + (bufoff) + ldsw + _i * 8192), 16, 0, 0); } while (0)
; #define PG8_LDA(dst, b, h) do { _Pragma("unroll") for (int m = 0; m < 4; ++m) _Pragma("unroll") for (int k = 0; k < 2; ++k) dst[m][k] = *(const LAS bf16x8*)(lds + PG8_SA(b, h) + aoff + m * 2048 + k * 1024); } while (0)
; #define PG8_LDB(dst, b, h) do { _Pragma("unroll") for (int n = 0; n < 2; ++n) _Pragma("unroll") for (int k = 0; k < 2; ++k) dst[n][k] = *(const LAS bf16x8*)(lds + PG8_SB(b, h) + boff + n * 2048 + k * 1024); } while (0)
; #define PG8_MMA(ai, bj, At, Bt) do { __builtin_amdgcn_s_setprio(1); _Pragma("unroll") for (int m = 0; m < 4; ++m) _Pragma("unroll") for (int n = 0; n < 2; ++n) _Pragma("unroll") for (int k = 0; k < 2; ++k) \
;         acc[ai][bj][m][n] = __builtin_amdgcn_mfma_f32_16x16x32_bf16(Bt[n][k], At[m][k], acc[ai][bj][m][n], 0, 0, 0); __builtin_amdgcn_s_setprio(0); } while (0)
; #define PG8_WAIT_V(n) asm volatile("s_waitcnt vmcnt(" #n ")" ::: "memory")
; #define PG8_WAIT_L(n) asm volatile("s_waitcnt lgkmcnt(" #n ")" ::: "memory")
; #define PG8_BAR __builtin_amdgcn_s_barrier()
; #define PG8_SCHED __builtin_amdgcn_sched_barrier(0)
; template <class Epi>
; DEVI void gemm_phase(LAS unsigned char* lds, const bf16_t* gA, const bf16_t* gBt, const int lda, const int ldb, const int K, const StaticOrder S_, const Epi E) {
;     ...
;             PG8_STAGE(PG8_SB(0, 1), b2 + hstepB, voffB);
;             PG8_WAIT_V(6); PG8_BAR; PG8_MMA(1, 1, At, B1); PG8_BAR;
;             PG8_LDB(B0, 1, 0); PG8_SCHED; PG8_LDA(At, 1, 0); PG8_STAGE(PG8_SA(0, 1), a2 + hstepA, voffA);
;             PG8_WAIT_L(8); PG8_BAR; PG8_WAIT_L(0); PG8_MMA(0, 0, At, B0); PG8_BAR; PG8_SCHED;
;             PG8_LDB(B1, 1, 1); PG8_STAGE(PG8_SB(1, 0), b3, voffB);
;             PG8_BAR; PG8_WAIT_L(0); PG8_MMA(0, 1, At, B1); PG8_BAR;
;             PG8_LDA(At, 1, 1); PG8_STAGE(PG8_SA(1, 0), a3, voffA);
;             PG8_BAR; PG8_WAIT_L(0); PG8_MMA(1, 0, At, B0); PG8_BAR; PG8_SCHED;
;             PG8_STAGE(PG8_SB(1, 1), b3 + hstepB, voffB);
	s_add_u32 s40, s40, s2
	s_addc_u32 s41, s41, s3
	s_add_i32 s73, s50, s20
	v_lshl_add_u64 v[224:225], s[40:41], 0, v[168:169]
	s_mov_b32 m0, s73
	v_lshl_add_u64 v[226:227], s[40:41], 0, v[172:173]
	global_load_lds_dwordx4 v[224:225], off
	s_add_i32 m0, s73, 0x2000
	s_nop 0
	global_load_lds_dwordx4 v[226:227], off
	s_waitcnt vmcnt(6)
	s_barrier
	v_mfma_f32_16x16x32_bf16 v[52:55], v[192:195], v[144:147], v[52:55]
	v_mfma_f32_16x16x32_bf16 v[48:51], v[210:213], v[144:147], v[48:51]
	v_mfma_f32_16x16x32_bf16 v[32:35], v[210:213], v[152:155], v[32:35]
	v_mfma_f32_16x16x32_bf16 v[36:39], v[192:195], v[152:155], v[36:39]
	v_mfma_f32_16x16x32_bf16 v[20:23], v[192:195], v[160:163], v[20:23]
	v_mfma_f32_16x16x32_bf16 v[16:19], v[210:213], v[160:163], v[16:19]
	v_mfma_f32_16x16x32_bf16 v[0:3], v[210:213], v[184:187], v[0:3]
	v_mfma_f32_16x16x32_bf16 v[4:7], v[192:195], v[184:187], v[4:7]
	v_mfma_f32_16x16x32_bf16 v[52:55], v[206:209], v[148:151], v[52:55]
	v_mfma_f32_16x16x32_bf16 v[48:51], v[214:217], v[148:151], v[48:51]
	v_mfma_f32_16x16x32_bf16 v[32:35], v[214:217], v[156:159], v[32:35]
	v_mfma_f32_16x16x32_bf16 v[36:39], v[206:209], v[156:159], v[36:39]
	v_mfma_f32_16x16x32_bf16 v[20:23], v[206:209], v[180:183], v[20:23]
	v_mfma_f32_16x16x32_bf16 v[16:19], v[214:217], v[180:183], v[16:19]
	v_mfma_f32_16x16x32_bf16 v[0:3], v[214:217], v[188:191], v[0:3]
	v_mfma_f32_16x16x32_bf16 v[4:7], v[206:209], v[188:191], v[4:7]
	s_add_i32 s40, 0, 0x18000
	v_add_u32_e32 v140, s40, v199
	s_barrier
	ds_read_b128 v[128:131], v140
	ds_read_b128 v[132:135], v140 offset:1024
	ds_read_b128 v[136:139], v140 offset:2048
	ds_read_b128 v[140:143], v140 offset:3072
	s_add_u32 s16, s16, s0
	s_addc_u32 s17, s17, s1
	s_mov_b32 m0, s23
	v_lshl_add_u64 v[192:193], s[16:17], 0, v[166:167]
	ds_read_b128 v[144:147], v202 offset:32768
	ds_read_b128 v[148:151], v202 offset:33792
	ds_read_b128 v[152:155], v202 offset:34816
	ds_read_b128 v[156:159], v202 offset:35840
	ds_read_b128 v[160:163], v202 offset:36864
	ds_read_b128 v[180:183], v202 offset:37888
	ds_read_b128 v[184:187], v202 offset:38912
	ds_read_b128 v[188:191], v202 offset:39936
	global_load_lds_dwordx4 v[192:193], off
	v_lshl_add_u64 v[192:193], s[16:17], 0, v[170:171]
	s_mov_b32 m0, s24
	s_nop 0
	global_load_lds_dwordx4 v[192:193], off
	s_waitcnt lgkmcnt(8)
	s_barrier
	s_waitcnt lgkmcnt(0)
	v_mfma_f32_16x16x32_bf16 v[124:127], v[128:131], v[144:147], v[124:127]
	v_mfma_f32_16x16x32_bf16 v[120:123], v[136:139], v[144:147], v[120:123]
	v_mfma_f32_16x16x32_bf16 v[104:107], v[136:139], v[152:155], v[104:107]
	v_mfma_f32_16x16x32_bf16 v[108:111], v[128:131], v[152:155], v[108:111]
	v_mfma_f32_16x16x32_bf16 v[92:95], v[128:131], v[160:163], v[92:95]
	v_mfma_f32_16x16x32_bf16 v[88:91], v[136:139], v[160:163], v[88:91]
	v_mfma_f32_16x16x32_bf16 v[72:75], v[136:139], v[184:187], v[72:75]
	v_mfma_f32_16x16x32_bf16 v[76:79], v[128:131], v[184:187], v[76:79]
	v_mfma_f32_16x16x32_bf16 v[124:127], v[132:135], v[148:151], v[124:127]
	v_mfma_f32_16x16x32_bf16 v[120:123], v[140:143], v[148:151], v[120:123]
	v_mfma_f32_16x16x32_bf16 v[104:107], v[140:143], v[156:159], v[104:107]
	v_mfma_f32_16x16x32_bf16 v[108:111], v[132:135], v[156:159], v[108:111]
	v_mfma_f32_16x16x32_bf16 v[92:95], v[132:135], v[180:183], v[92:95]
	v_mfma_f32_16x16x32_bf16 v[88:91], v[140:143], v[180:183], v[88:91]
	v_mfma_f32_16x16x32_bf16 v[72:75], v[140:143], v[188:191], v[72:75]
	v_mfma_f32_16x16x32_bf16 v[76:79], v[132:135], v[188:191], v[76:79]
	s_barrier
	s_add_i32 s16, 0, 0x1c000
	s_add_i32 s17, s40, s20
	v_add_u32_e32 v205, s16, v199
	v_lshl_add_u64 v[164:165], v[164:165], 0, s[8:9]
	s_mov_b32 m0, s17
	ds_read_b128 v[192:195], v205
	ds_read_b128 v[206:209], v205 offset:1024
	ds_read_b128 v[210:213], v205 offset:2048
	ds_read_b128 v[214:217], v205 offset:3072
	global_load_lds_dwordx4 v[164:165], off
	v_lshl_add_u64 v[164:165], v[218:219], 0, s[8:9]
	s_add_i32 m0, s17, 0x2000
	s_nop 0
	global_load_lds_dwordx4 v[164:165], off
	s_barrier
; #define PG8_STAGE(bufoff, gbase, voff) do { _Pragma("unroll") for (int _i = 0; _i < 2; ++_i) \
;         __builtin_amdgcn_global_load_lds((const unsigned*)((const char*)(gbase) + (voff)[_i]), (LAS unsigned*)(lds + (bufoff) + ldsw + _i * 8192), 16, 0, 0); } while (0)
; #define PG8_LDA(dst, b, h) do { _Pragma("unroll") for (int m = 0; m < 4; ++m) _Pragma("unroll") for (int k = 0; k < 2; ++k) dst[m][k] = *(const LAS bf16x8*)(lds + PG8_SA(b, h) + aoff + m * 2048 + k * 1024); } while (0)
; #define PG8_MMA(ai, bj, At, Bt) do { __builtin_amdgcn_s_setprio(1); _Pragma("unroll") for (int m = 0; m < 4; ++m) _Pragma("unroll") for (int n = 0; n < 2; ++n) _Pragma("unroll") for (int k = 0; k < 2; ++k) \
;         acc[ai][bj][m][n] = __builtin_amdgcn_mfma_f32_16x16x32_bf16(Bt[n][k], At[m][k], acc[ai][bj][m][n], 0, 0, 0); __builtin_amdgcn_s_setprio(0); } while (0)
; #define PG8_WAIT_V(n) asm volatile("s_waitcnt vmcnt(" #n ")" ::: "memory")
; #define PG8_WAIT_L(n) asm volatile("s_waitcnt lgkmcnt(" #n ")" ::: "memory")
; #define PG8_BAR __builtin_amdgcn_s_barrier()
; #define PG8_SCHED __builtin_amdgcn_sched_barrier(0)
; template <class Epi>
; DEVI void gemm_phase(LAS unsigned char* lds, const bf16_t* gA, const bf16_t* gBt, const int lda, const int ldb, const int K, const StaticOrder S_, const Epi E) {
;     ...
;             PG8_BAR; PG8_WAIT_L(0); PG8_MMA(0, 1, At, B1); PG8_BAR;
;             PG8_LDA(At, 1, 1); PG8_STAGE(PG8_SA(1, 0), a3, voffA);
;             PG8_BAR; PG8_WAIT_L(0); PG8_MMA(1, 0, At, B0); PG8_BAR; PG8_SCHED;
;             PG8_STAGE(PG8_SB(1, 1), b3 + hstepB, voffB);
;             PG8_WAIT_V(6); PG8_BAR; PG8_MMA(1, 1, At, B1); PG8_BAR;
	s_waitcnt lgkmcnt(0)
	v_mfma_f32_16x16x32_bf16 v[116:119], v[192:195], v[144:147], v[116:119]
	v_mfma_f32_16x16x32_bf16 v[112:115], v[210:213], v[144:147], v[112:115]
	v_mfma_f32_16x16x32_bf16 v[96:99], v[210:213], v[152:155], v[96:99]
	v_mfma_f32_16x16x32_bf16 v[100:103], v[192:195], v[152:155], v[100:103]
	v_mfma_f32_16x16x32_bf16 v[84:87], v[192:195], v[160:163], v[84:87]
	v_mfma_f32_16x16x32_bf16 v[80:83], v[210:213], v[160:163], v[80:83]
	v_mfma_f32_16x16x32_bf16 v[64:67], v[210:213], v[184:187], v[64:67]
	v_mfma_f32_16x16x32_bf16 v[68:71], v[192:195], v[184:187], v[68:71]
	v_mfma_f32_16x16x32_bf16 v[116:119], v[206:209], v[148:151], v[116:119]
	v_mfma_f32_16x16x32_bf16 v[112:115], v[214:217], v[148:151], v[112:115]
	v_mfma_f32_16x16x32_bf16 v[96:99], v[214:217], v[156:159], v[96:99]
	v_mfma_f32_16x16x32_bf16 v[100:103], v[206:209], v[156:159], v[100:103]
	v_mfma_f32_16x16x32_bf16 v[84:87], v[206:209], v[180:183], v[84:87]
	v_mfma_f32_16x16x32_bf16 v[80:83], v[214:217], v[180:183], v[80:83]
	v_mfma_f32_16x16x32_bf16 v[64:67], v[214:217], v[188:191], v[64:67]
	v_mfma_f32_16x16x32_bf16 v[68:71], v[206:209], v[188:191], v[68:71]
	s_mov_b32 m0, s26
	v_lshl_add_u64 v[164:165], v[220:221], 0, s[8:9]
	s_barrier
	ds_read_b128 v[144:147], v202 offset:49152
	ds_read_b128 v[148:151], v202 offset:50176
	ds_read_b128 v[152:155], v202 offset:51200
	ds_read_b128 v[156:159], v202 offset:52224
	ds_read_b128 v[160:163], v202 offset:53248
	ds_read_b128 v[180:183], v202 offset:54272
	ds_read_b128 v[184:187], v202 offset:55296
	ds_read_b128 v[188:191], v202 offset:56320
	global_load_lds_dwordx4 v[164:165], off
	v_lshl_add_u64 v[164:165], v[222:223], 0, s[8:9]
	s_mov_b32 m0, s27
	s_nop 0
	global_load_lds_dwordx4 v[164:165], off
	s_barrier
	s_waitcnt lgkmcnt(0)
	v_mfma_f32_16x16x32_bf16 v[60:63], v[128:131], v[144:147], v[60:63]
	v_mfma_f32_16x16x32_bf16 v[56:59], v[136:139], v[144:147], v[56:59]
	v_mfma_f32_16x16x32_bf16 v[40:43], v[136:139], v[152:155], v[40:43]
	v_mfma_f32_16x16x32_bf16 v[44:47], v[128:131], v[152:155], v[44:47]
	v_mfma_f32_16x16x32_bf16 v[28:31], v[128:131], v[160:163], v[28:31]
	v_mfma_f32_16x16x32_bf16 v[24:27], v[136:139], v[160:163], v[24:27]
	v_mfma_f32_16x16x32_bf16 v[8:11], v[136:139], v[184:187], v[8:11]
	v_mfma_f32_16x16x32_bf16 v[12:15], v[128:131], v[184:187], v[12:15]
	v_mfma_f32_16x16x32_bf16 v[60:63], v[132:135], v[148:151], v[60:63]
	v_mfma_f32_16x16x32_bf16 v[56:59], v[140:143], v[148:151], v[56:59]
	v_mfma_f32_16x16x32_bf16 v[40:43], v[140:143], v[156:159], v[40:43]
	v_mfma_f32_16x16x32_bf16 v[44:47], v[132:135], v[156:159], v[44:47]
	v_mfma_f32_16x16x32_bf16 v[28:31], v[132:135], v[180:183], v[28:31]
	v_mfma_f32_16x16x32_bf16 v[24:27], v[140:143], v[180:183], v[24:27]
	v_mfma_f32_16x16x32_bf16 v[8:11], v[140:143], v[188:191], v[8:11]
	v_mfma_f32_16x16x32_bf16 v[12:15], v[132:135], v[188:191], v[12:15]
	s_barrier
	s_add_i32 s16, s16, s20
	v_lshl_add_u64 v[128:129], v[224:225], 0, s[8:9]
	s_mov_b32 m0, s16
	s_nop 0
	global_load_lds_dwordx4 v[128:129], off
	v_lshl_add_u64 v[128:129], v[226:227], 0, s[8:9]
	s_add_i32 m0, s16, 0x2000
	s_nop 0
	global_load_lds_dwordx4 v[128:129], off
	s_waitcnt vmcnt(6)
	s_barrier
	v_mfma_f32_16x16x32_bf16 v[52:55], v[192:195], v[144:147], v[52:55]
	v_mfma_f32_16x16x32_bf16 v[48:51], v[210:213], v[144:147], v[48:51]
	v_mfma_f32_16x16x32_bf16 v[32:35], v[210:213], v[152:155], v[32:35]
	v_mfma_f32_16x16x32_bf16 v[36:39], v[192:195], v[152:155], v[36:39]
	v_mfma_f32_16x16x32_bf16 v[20:23], v[192:195], v[160:163], v[20:23]
	v_mfma_f32_16x16x32_bf16 v[16:19], v[210:213], v[160:163], v[16:19]
	v_mfma_f32_16x16x32_bf16 v[0:3], v[210:213], v[184:187], v[0:3]
	v_mfma_f32_16x16x32_bf16 v[4:7], v[192:195], v[184:187], v[4:7]
	v_mfma_f32_16x16x32_bf16 v[52:55], v[206:209], v[148:151], v[52:55]
	v_mfma_f32_16x16x32_bf16 v[48:51], v[214:217], v[148:151], v[48:51]
	v_mfma_f32_16x16x32_bf16 v[32:35], v[214:217], v[156:159], v[32:35]
	v_mfma_f32_16x16x32_bf16 v[36:39], v[206:209], v[156:159], v[36:39]
	v_mfma_f32_16x16x32_bf16 v[20:23], v[206:209], v[180:183], v[20:23]
	v_mfma_f32_16x16x32_bf16 v[16:19], v[214:217], v[180:183], v[16:19]
	v_mfma_f32_16x16x32_bf16 v[0:3], v[214:217], v[188:191], v[0:3]
	v_mfma_f32_16x16x32_bf16 v[4:7], v[206:209], v[188:191], v[4:7]
	s_add_u32 s14, s14, 0x100
	s_addc_u32 s15, s15, 0
	s_add_u32 s70, s70, 0x100
	s_addc_u32 s71, s71, 0
	s_cmp_ge_i32 s72, s25
	s_mov_b32 s16, s72
	s_barrier
	s_cbranch_scc0 .LBB0_1301

; #define PG8_STAGE(bufoff, gbase, voff) do { _Pragma("unroll") for (int _i = 0; _i < 2; ++_i) \
;         __builtin_amdgcn_global_load_lds((const unsigned*)((const char*)(gbase) + (voff)[_i]), (LAS unsigned*)(lds + (bufoff) + ldsw + _i * 8192), 16, 0, 0); } while (0)
; #define PG8_LDA(dst, b, h) do { _Pragma("unroll") for (int m = 0; m < 4; ++m) _Pragma("unroll") for (int k = 0; k < 2; ++k) dst[m][k] = *(const LAS bf16x8*)(lds + PG8_SA(b, h) + aoff + m * 2048 + k * 1024); } while (0)
; #define PG8_LDB(dst, b, h) do { _Pragma("unroll") for (int n = 0; n < 2; ++n) _Pragma("unroll") for (int k = 0; k < 2; ++k) dst[n][k] = *(const LAS bf16x8*)(lds + PG8_SB(b, h) + boff + n * 2048 + k * 1024); } while (0)
; #define PG8_MMA(ai, bj, At, Bt) do { __builtin_amdgcn_s_setprio(1); _Pragma("unroll") for (int m = 0; m < 4; ++m) _Pragma("unroll") for (int n = 0; n < 2; ++n) _Pragma("unroll") for (int k = 0; k < 2; ++k) \
;         acc[ai][bj][m][n] = __builtin_amdgcn_mfma_f32_16x16x32_bf16(Bt[n][k], At[m][k], acc[ai][bj][m][n], 0, 0, 0); __builtin_amdgcn_s_setprio(0); } while (0)
; #define PG8_WAIT_L(n) asm volatile("s_waitcnt lgkmcnt(" #n ")" ::: "memory")
; #define PG8_BAR __builtin_amdgcn_s_barrier()
; #define PG8_SCHED __builtin_amdgcn_sched_barrier(0)
; template <class Epi>
; DEVI void gemm_phase(LAS unsigned char* lds, const bf16_t* gA, const bf16_t* gBt, const int lda, const int ldb, const int K, const StaticOrder S_, const Epi E) {
;     ...
;         for (int t = 0; t < nt; t += 2) {
;             const bool last = (t == nt - 2);
;             const char* a1 = cA + (size_t)(t + 1) * kstep;
;             const char* a2 = last ? nA : cA + (size_t)(t + 2) * kstep; const char* b2 = last ? nB : cB + (size_t)(t + 2) * kstep;
;             const char* a3 = a2 + kstep; const char* b3 = b2 + kstep;
;             PG8_LDB(B0, 0, 0); PG8_SCHED; PG8_LDA(At, 0, 0); PG8_STAGE(PG8_SA(1, 1), a1 + hstepA, voffA);
;             PG8_WAIT_L(8); PG8_BAR; PG8_WAIT_L(0); PG8_MMA(0, 0, At, B0); PG8_BAR; PG8_SCHED;
;             PG8_LDB(B1, 0, 1); PG8_STAGE(PG8_SB(0, 0), b2, voffB);
;             PG8_BAR; PG8_WAIT_L(0); PG8_MMA(0, 1, At, B1); PG8_BAR;
;             PG8_LDA(At, 0, 1); PG8_STAGE(PG8_SA(0, 0), a2, voffA);
;             PG8_BAR; PG8_WAIT_L(0); PG8_MMA(1, 0, At, B0); PG8_BAR; PG8_SCHED;
.LBB0_1445:
	ds_read_b128 v[158:161], v151
	ds_read_b128 v[162:165], v151 offset:1024
	ds_read_b128 v[166:169], v151 offset:2048
	ds_read_b128 v[170:173], v151 offset:3072
	s_add_i32 s79, s16, 2
	s_add_u32 s70, s14, 0x80
	s_addc_u32 s17, s15, 0
	s_cmp_eq_u32 s26, s16
	s_cselect_b32 s16, s40, s70
	s_cselect_b32 s17, s41, s17
	s_cselect_b32 s71, s67, s78
	s_cselect_b32 s70, s66, s77
	v_lshl_add_u64 v[144:145], s[14:15], 0, v[138:139]
	s_add_i32 m0, s19, 0xc000
	ds_read_b128 v[174:177], v152
	ds_read_b128 v[178:181], v152 offset:1024
	ds_read_b128 v[182:185], v152 offset:2048
	ds_read_b128 v[186:189], v152 offset:3072
	ds_read_b128 v[190:193], v152 offset:4096
	ds_read_b128 v[198:201], v152 offset:5120
	ds_read_b128 v[202:205], v152 offset:6144
	ds_read_b128 v[206:209], v152 offset:7168
	global_load_lds_dwordx4 v[144:145], off
	v_lshl_add_u64 v[144:145], s[14:15], 0, v[140:141]
	s_add_i32 m0, s19, 0xe000
	s_nop 0
	global_load_lds_dwordx4 v[144:145], off
	s_waitcnt lgkmcnt(8)
	s_barrier
	s_waitcnt lgkmcnt(0)
	v_mfma_f32_16x16x32_bf16 v[120:123], v[158:161], v[174:177], v[120:123]
	v_mfma_f32_16x16x32_bf16 v[116:119], v[166:169], v[174:177], v[116:119]
	v_mfma_f32_16x16x32_bf16 v[100:103], v[166:169], v[182:185], v[100:103]
	v_mfma_f32_16x16x32_bf16 v[108:111], v[158:161], v[182:185], v[108:111]
	v_mfma_f32_16x16x32_bf16 v[92:95], v[158:161], v[190:193], v[92:95]
	v_mfma_f32_16x16x32_bf16 v[84:87], v[166:169], v[190:193], v[84:87]
	v_mfma_f32_16x16x32_bf16 v[68:71], v[166:169], v[202:205], v[68:71]
	v_mfma_f32_16x16x32_bf16 v[76:79], v[158:161], v[202:205], v[76:79]
	v_mfma_f32_16x16x32_bf16 v[120:123], v[162:165], v[178:181], v[120:123]
	v_mfma_f32_16x16x32_bf16 v[116:119], v[170:173], v[178:181], v[116:119]
	v_mfma_f32_16x16x32_bf16 v[100:103], v[170:173], v[186:189], v[100:103]
	v_mfma_f32_16x16x32_bf16 v[108:111], v[162:165], v[186:189], v[108:111]
	v_mfma_f32_16x16x32_bf16 v[92:95], v[162:165], v[198:201], v[92:95]
	v_mfma_f32_16x16x32_bf16 v[84:87], v[170:173], v[198:201], v[84:87]
	v_mfma_f32_16x16x32_bf16 v[68:71], v[170:173], v[206:209], v[68:71]
	v_mfma_f32_16x16x32_bf16 v[76:79], v[162:165], v[206:209], v[76:79]
	s_barrier
	s_add_i32 s80, s34, s18
	v_lshl_add_u64 v[144:145], s[70:71], 0, v[130:131]
	s_mov_b32 m0, s80
	ds_read_b128 v[210:213], v153
	ds_read_b128 v[214:217], v153 offset:1024
	ds_read_b128 v[218:221], v153 offset:2048
	ds_read_b128 v[222:225], v153 offset:3072
	global_load_lds_dwordx4 v[144:145], off
	v_lshl_add_u64 v[194:195], s[70:71], 0, v[134:135]
	s_add_i32 m0, s80, 0x2000
	s_nop 0
	global_load_lds_dwordx4 v[194:195], off
	s_barrier
	s_waitcnt lgkmcnt(0)
	v_mfma_f32_16x16x32_bf16 v[124:127], v[210:213], v[174:177], v[124:127]
	v_mfma_f32_16x16x32_bf16 v[112:115], v[218:221], v[174:177], v[112:115]
	v_mfma_f32_16x16x32_bf16 v[96:99], v[218:221], v[182:185], v[96:99]
	v_mfma_f32_16x16x32_bf16 v[104:107], v[210:213], v[182:185], v[104:107]
	v_mfma_f32_16x16x32_bf16 v[88:91], v[210:213], v[190:193], v[88:91]
	v_mfma_f32_16x16x32_bf16 v[80:83], v[218:221], v[190:193], v[80:83]
	v_mfma_f32_16x16x32_bf16 v[64:67], v[218:221], v[202:205], v[64:67]
	v_mfma_f32_16x16x32_bf16 v[72:75], v[210:213], v[202:205], v[72:75]
	v_mfma_f32_16x16x32_bf16 v[124:127], v[214:217], v[178:181], v[124:127]
	v_mfma_f32_16x16x32_bf16 v[112:115], v[222:225], v[178:181], v[112:115]
	v_mfma_f32_16x16x32_bf16 v[96:99], v[222:225], v[186:189], v[96:99]
	v_mfma_f32_16x16x32_bf16 v[104:107], v[214:217], v[186:189], v[104:107]
	v_mfma_f32_16x16x32_bf16 v[88:91], v[214:217], v[198:201], v[88:91]
	v_mfma_f32_16x16x32_bf16 v[80:83], v[222:225], v[198:201], v[80:83]
	v_mfma_f32_16x16x32_bf16 v[64:67], v[222:225], v[206:209], v[64:67]
	v_mfma_f32_16x16x32_bf16 v[72:75], v[214:217], v[206:209], v[72:75]
	s_mov_b32 m0, s19
	v_lshl_add_u64 v[226:227], s[16:17], 0, v[128:129]
	s_barrier
	ds_read_b128 v[174:177], v152 offset:16384
	ds_read_b128 v[178:181], v152 offset:17408
	ds_read_b128 v[182:185], v152 offset:18432
	ds_read_b128 v[186:189], v152 offset:19456
	ds_read_b128 v[190:193], v152 offset:20480
	ds_read_b128 v[198:201], v152 offset:21504
	ds_read_b128 v[202:205], v152 offset:22528
	ds_read_b128 v[206:209], v152 offset:23552
	global_load_lds_dwordx4 v[226:227], off
	v_lshl_add_u64 v[228:229], s[16:17], 0, v[132:133]
	s_mov_b32 m0, s20
	s_nop 0
	global_load_lds_dwordx4 v[228:229], off
	s_barrier
	s_waitcnt lgkmcnt(0)
	v_mfma_f32_16x16x32_bf16 v[60:63], v[158:161], v[174:177], v[60:63]
	v_mfma_f32_16x16x32_bf16 v[56:59], v[166:169], v[174:177], v[56:59]
	v_mfma_f32_16x16x32_bf16 v[40:43], v[166:169], v[182:185], v[40:43]
	v_mfma_f32_16x16x32_bf16 v[44:47], v[158:161], v[182:185], v[44:47]
	v_mfma_f32_16x16x32_bf16 v[28:31], v[158:161], v[190:193], v[28:31]
	v_mfma_f32_16x16x32_bf16 v[24:27], v[166:169], v[190:193], v[24:27]
	v_mfma_f32_16x16x32_bf16 v[8:11], v[166:169], v[202:205], v[8:11]
	v_mfma_f32_16x16x32_bf16 v[12:15], v[158:161], v[202:205], v[12:15]
	v_mfma_f32_16x16x32_bf16 v[60:63], v[162:165], v[178:181], v[60:63]
	v_mfma_f32_16x16x32_bf16 v[56:59], v[170:173], v[178:181], v[56:59]
	v_mfma_f32_16x16x32_bf16 v[40:43], v[170:173], v[186:189], v[40:43]
	v_mfma_f32_16x16x32_bf16 v[44:47], v[162:165], v[186:189], v[44:47]
	v_mfma_f32_16x16x32_bf16 v[28:31], v[162:165], v[198:201], v[28:31]
	v_mfma_f32_16x16x32_bf16 v[24:27], v[170:173], v[198:201], v[24:27]
	v_mfma_f32_16x16x32_bf16 v[8:11], v[170:173], v[206:209], v[8:11]
	v_mfma_f32_16x16x32_bf16 v[12:15], v[162:165], v[206:209], v[12:15]
	s_barrier
; #define PG8_STAGE(bufoff, gbase, voff) do { _Pragma("unroll") for (int _i = 0; _i < 2; ++_i) \
;         __builtin_amdgcn_global_load_lds((const unsigned*)((const char*)(gbase) + (voff)[_i]), (LAS unsigned*)(lds + (bufoff) + ldsw + _i * 8192), 16, 0, 0); } while (0)
; #define PG8_LDA(dst, b, h) do { _Pragma("unroll") for (int m = 0; m < 4; ++m) _Pragma("unroll") for (int k = 0; k < 2; ++k) dst[m][k] = *(const LAS bf16x8*)(lds + PG8_SA(b, h) + aoff + m * 2048 + k * 1024); } while (0)
; #define PG8_LDB(dst, b, h) do { _Pragma("unroll") for (int n = 0; n < 2; ++n) _Pragma("unroll") for (int k = 0; k < 2; ++k) dst[n][k] = *(const LAS bf16x8*)(lds + PG8_SB(b, h) + boff + n * 2048 + k * 1024); } while (0)
; #define PG8_MMA(ai, bj, At, Bt) do { __builtin_amdgcn_s_setprio(1); _Pragma("unroll") for (int m = 0; m < 4; ++m) _Pragma("unroll") for (int n = 0; n < 2; ++n) _Pragma("unroll") for (int k = 0; k < 2; ++k) \
;         acc[ai][bj][m][n] = __builtin_amdgcn_mfma_f32_16x16x32_bf16(Bt[n][k], At[m][k], acc[ai][bj][m][n], 0, 0, 0); __builtin_amdgcn_s_setprio(0); } while (0)
; #define PG8_WAIT_V(n) asm volatile("s_waitcnt vmcnt(" #n ")" ::: "memory")
; #define PG8_WAIT_L(n) asm volatile("s_waitcnt lgkmcnt(" #n ")" ::: "memory")
; #define PG8_BAR __builtin_amdgcn_s_barrier()
; #define PG8_SCHED __builtin_amdgcn_sched_barrier(0)
; template <class Epi>
; DEVI void gemm_phase(LAS unsigned char* lds, const bf16_t* gA, const bf16_t* gBt, const int lda, const int ldb, const int K, const StaticOrder S_, const Epi E) {
;     ...
;             PG8_STAGE(PG8_SB(0, 1), b2 + hstepB, voffB);
;             PG8_WAIT_V(6); PG8_BAR; PG8_MMA(1, 1, At, B1); PG8_BAR;
;             PG8_LDB(B0, 1, 0); PG8_SCHED; PG8_LDA(At, 1, 0); PG8_STAGE(PG8_SA(0, 1), a2 + hstepA, voffA);
;             PG8_WAIT_L(8); PG8_BAR; PG8_WAIT_L(0); PG8_MMA(0, 0, At, B0); PG8_BAR; PG8_SCHED;
;             PG8_LDB(B1, 1, 1); PG8_STAGE(PG8_SB(1, 0), b3, voffB);
;             PG8_BAR; PG8_WAIT_L(0); PG8_MMA(0, 1, At, B1); PG8_BAR;
;             PG8_LDA(At, 1, 1); PG8_STAGE(PG8_SA(1, 0), a3, voffA);
;             PG8_BAR; PG8_WAIT_L(0); PG8_MMA(1, 0, At, B0); PG8_BAR; PG8_SCHED;
;             PG8_STAGE(PG8_SB(1, 1), b3 + hstepB, voffB);
	s_add_u32 s70, s70, s2
	s_addc_u32 s71, s71, s3
	s_add_i32 s80, s35, s18
	v_lshl_add_u64 v[230:231], s[70:71], 0, v[130:131]
	s_mov_b32 m0, s80
	v_lshl_add_u64 v[232:233], s[70:71], 0, v[134:135]
	global_load_lds_dwordx4 v[230:231], off
	s_add_i32 m0, s80, 0x2000
	s_nop 0
	global_load_lds_dwordx4 v[232:233], off
	s_waitcnt vmcnt(6)
	s_barrier
	v_mfma_f32_16x16x32_bf16 v[52:55], v[210:213], v[174:177], v[52:55]
	v_mfma_f32_16x16x32_bf16 v[48:51], v[218:221], v[174:177], v[48:51]
	v_mfma_f32_16x16x32_bf16 v[32:35], v[218:221], v[182:185], v[32:35]
	v_mfma_f32_16x16x32_bf16 v[36:39], v[210:213], v[182:185], v[36:39]
	v_mfma_f32_16x16x32_bf16 v[20:23], v[210:213], v[190:193], v[20:23]
	v_mfma_f32_16x16x32_bf16 v[16:19], v[218:221], v[190:193], v[16:19]
	v_mfma_f32_16x16x32_bf16 v[0:3], v[218:221], v[202:205], v[0:3]
	v_mfma_f32_16x16x32_bf16 v[4:7], v[210:213], v[202:205], v[4:7]
	v_mfma_f32_16x16x32_bf16 v[52:55], v[214:217], v[178:181], v[52:55]
	v_mfma_f32_16x16x32_bf16 v[48:51], v[222:225], v[178:181], v[48:51]
	v_mfma_f32_16x16x32_bf16 v[32:35], v[222:225], v[186:189], v[32:35]
	v_mfma_f32_16x16x32_bf16 v[36:39], v[214:217], v[186:189], v[36:39]
	v_mfma_f32_16x16x32_bf16 v[20:23], v[214:217], v[198:201], v[20:23]
	v_mfma_f32_16x16x32_bf16 v[16:19], v[222:225], v[198:201], v[16:19]
	v_mfma_f32_16x16x32_bf16 v[0:3], v[222:225], v[206:209], v[0:3]
	v_mfma_f32_16x16x32_bf16 v[4:7], v[214:217], v[206:209], v[4:7]
	s_barrier
	ds_read_b128 v[158:161], v154
	ds_read_b128 v[162:165], v154 offset:1024
	ds_read_b128 v[166:169], v154 offset:2048
	ds_read_b128 v[170:173], v154 offset:3072
	s_add_u32 s16, s16, s0
	s_addc_u32 s17, s17, s1
	s_mov_b32 m0, s21
	v_lshl_add_u64 v[210:211], s[16:17], 0, v[128:129]
	ds_read_b128 v[174:177], v152 offset:32768
	ds_read_b128 v[178:181], v152 offset:33792
	ds_read_b128 v[182:185], v152 offset:34816
	ds_read_b128 v[186:189], v152 offset:35840
	ds_read_b128 v[190:193], v152 offset:36864
	ds_read_b128 v[198:201], v152 offset:37888
	ds_read_b128 v[202:205], v152 offset:38912
	ds_read_b128 v[206:209], v152 offset:39936
	global_load_lds_dwordx4 v[210:211], off
	v_lshl_add_u64 v[210:211], s[16:17], 0, v[132:133]
	s_mov_b32 m0, s22
	s_nop 0
	global_load_lds_dwordx4 v[210:211], off
	s_waitcnt lgkmcnt(8)
	s_barrier
	s_waitcnt lgkmcnt(0)
	v_mfma_f32_16x16x32_bf16 v[120:123], v[158:161], v[174:177], v[120:123]
	v_mfma_f32_16x16x32_bf16 v[116:119], v[166:169], v[174:177], v[116:119]
	v_mfma_f32_16x16x32_bf16 v[100:103], v[166:169], v[182:185], v[100:103]
	v_mfma_f32_16x16x32_bf16 v[108:111], v[158:161], v[182:185], v[108:111]
	v_mfma_f32_16x16x32_bf16 v[92:95], v[158:161], v[190:193], v[92:95]
	v_mfma_f32_16x16x32_bf16 v[84:87], v[166:169], v[190:193], v[84:87]
	v_mfma_f32_16x16x32_bf16 v[68:71], v[166:169], v[202:205], v[68:71]
	v_mfma_f32_16x16x32_bf16 v[76:79], v[158:161], v[202:205], v[76:79]
	v_mfma_f32_16x16x32_bf16 v[120:123], v[162:165], v[178:181], v[120:123]
	v_mfma_f32_16x16x32_bf16 v[116:119], v[170:173], v[178:181], v[116:119]
	v_mfma_f32_16x16x32_bf16 v[100:103], v[170:173], v[186:189], v[100:103]
	v_mfma_f32_16x16x32_bf16 v[108:111], v[162:165], v[186:189], v[108:111]
	v_mfma_f32_16x16x32_bf16 v[92:95], v[162:165], v[198:201], v[92:95]
	v_mfma_f32_16x16x32_bf16 v[84:87], v[170:173], v[198:201], v[84:87]
	v_mfma_f32_16x16x32_bf16 v[68:71], v[170:173], v[206:209], v[68:71]
	v_mfma_f32_16x16x32_bf16 v[76:79], v[162:165], v[206:209], v[76:79]
	s_barrier
	s_add_i32 s16, s49, s18
	v_lshl_add_u64 v[144:145], v[144:145], 0, s[64:65]
	s_mov_b32 m0, s16
	ds_read_b128 v[210:213], v155
	ds_read_b128 v[214:217], v155 offset:1024
	ds_read_b128 v[218:221], v155 offset:2048
	ds_read_b128 v[222:225], v155 offset:3072
	global_load_lds_dwordx4 v[144:145], off
	v_lshl_add_u64 v[144:145], v[194:195], 0, s[64:65]
	s_add_i32 m0, s16, 0x2000
	s_nop 0
	global_load_lds_dwordx4 v[144:145], off
	s_barrier
; #define PG8_STAGE(bufoff, gbase, voff) do { _Pragma("unroll") for (int _i = 0; _i < 2; ++_i) \
;         __builtin_amdgcn_global_load_lds((const unsigned*)((const char*)(gbase) + (voff)[_i]), (LAS unsigned*)(lds + (bufoff) + ldsw + _i * 8192), 16, 0, 0); } while (0)
; #define PG8_LDA(dst, b, h) do { _Pragma("unroll") for (int m = 0; m < 4; ++m) _Pragma("unroll") for (int k = 0; k < 2; ++k) dst[m][k] = *(const LAS bf16x8*)(lds + PG8_SA(b, h) + aoff + m * 2048 + k * 1024); } while (0)
; #define PG8_MMA(ai, bj, At, Bt) do { __builtin_amdgcn_s_setprio(1); _Pragma("unroll") for (int m = 0; m < 4; ++m) _Pragma("unroll") for (int n = 0; n < 2; ++n) _Pragma("unroll") for (int k = 0; k < 2; ++k) \
;         acc[ai][bj][m][n] = __builtin_amdgcn_mfma_f32_16x16x32_bf16(Bt[n][k], At[m][k], acc[ai][bj][m][n], 0, 0, 0); __builtin_amdgcn_s_setprio(0); } while (0)
; #define PG8_WAIT_V(n) asm volatile("s_waitcnt vmcnt(" #n ")" ::: "memory")
; #define PG8_WAIT_L(n) asm volatile("s_waitcnt lgkmcnt(" #n ")" ::: "memory")
; #define PG8_BAR __builtin_amdgcn_s_barrier()
; #define PG8_SCHED __builtin_amdgcn_sched_barrier(0)
; template <class Epi>
; DEVI void gemm_phase(LAS unsigned char* lds, const bf16_t* gA, const bf16_t* gBt, const int lda, const int ldb, const int K, const StaticOrder S_, const Epi E) {
;     ...
;             PG8_BAR; PG8_WAIT_L(0); PG8_MMA(0, 1, At, B1); PG8_BAR;
;             PG8_LDA(At, 1, 1); PG8_STAGE(PG8_SA(1, 0), a3, voffA);
;             PG8_BAR; PG8_WAIT_L(0); PG8_MMA(1, 0, At, B0); PG8_BAR; PG8_SCHED;
;             PG8_STAGE(PG8_SB(1, 1), b3 + hstepB, voffB);
;             PG8_WAIT_V(6); PG8_BAR; PG8_MMA(1, 1, At, B1); PG8_BAR;
	s_waitcnt lgkmcnt(0)
	v_mfma_f32_16x16x32_bf16 v[124:127], v[210:213], v[174:177], v[124:127]
	v_mfma_f32_16x16x32_bf16 v[112:115], v[218:221], v[174:177], v[112:115]
	v_mfma_f32_16x16x32_bf16 v[96:99], v[218:221], v[182:185], v[96:99]
	v_mfma_f32_16x16x32_bf16 v[104:107], v[210:213], v[182:185], v[104:107]
	v_mfma_f32_16x16x32_bf16 v[88:91], v[210:213], v[190:193], v[88:91]
	v_mfma_f32_16x16x32_bf16 v[80:83], v[218:221], v[190:193], v[80:83]
	v_mfma_f32_16x16x32_bf16 v[64:67], v[218:221], v[202:205], v[64:67]
	v_mfma_f32_16x16x32_bf16 v[72:75], v[210:213], v[202:205], v[72:75]
	v_mfma_f32_16x16x32_bf16 v[124:127], v[214:217], v[178:181], v[124:127]
	v_mfma_f32_16x16x32_bf16 v[112:115], v[222:225], v[178:181], v[112:115]
	v_mfma_f32_16x16x32_bf16 v[96:99], v[222:225], v[186:189], v[96:99]
	v_mfma_f32_16x16x32_bf16 v[104:107], v[214:217], v[186:189], v[104:107]
	v_mfma_f32_16x16x32_bf16 v[88:91], v[214:217], v[198:201], v[88:91]
	v_mfma_f32_16x16x32_bf16 v[80:83], v[222:225], v[198:201], v[80:83]
	v_mfma_f32_16x16x32_bf16 v[64:67], v[222:225], v[206:209], v[64:67]
	v_mfma_f32_16x16x32_bf16 v[72:75], v[214:217], v[206:209], v[72:75]
	s_mov_b32 m0, s23
	v_lshl_add_u64 v[144:145], v[226:227], 0, s[64:65]
	s_barrier
	ds_read_b128 v[174:177], v152 offset:49152
	ds_read_b128 v[178:181], v152 offset:50176
	ds_read_b128 v[182:185], v152 offset:51200
	ds_read_b128 v[186:189], v152 offset:52224
	ds_read_b128 v[190:193], v152 offset:53248
	ds_read_b128 v[198:201], v152 offset:54272
	ds_read_b128 v[202:205], v152 offset:55296
	ds_read_b128 v[206:209], v152 offset:56320
	global_load_lds_dwordx4 v[144:145], off
	v_lshl_add_u64 v[144:145], v[228:229], 0, s[64:65]
	s_mov_b32 m0, s24
	s_nop 0
	global_load_lds_dwordx4 v[144:145], off
	s_barrier
	s_waitcnt lgkmcnt(0)
	v_mfma_f32_16x16x32_bf16 v[60:63], v[158:161], v[174:177], v[60:63]
	v_mfma_f32_16x16x32_bf16 v[56:59], v[166:169], v[174:177], v[56:59]
	v_mfma_f32_16x16x32_bf16 v[40:43], v[166:169], v[182:185], v[40:43]
	v_mfma_f32_16x16x32_bf16 v[44:47], v[158:161], v[182:185], v[44:47]
	v_mfma_f32_16x16x32_bf16 v[28:31], v[158:161], v[190:193], v[28:31]
	v_mfma_f32_16x16x32_bf16 v[24:27], v[166:169], v[190:193], v[24:27]
	v_mfma_f32_16x16x32_bf16 v[8:11], v[166:169], v[202:205], v[8:11]
	v_mfma_f32_16x16x32_bf16 v[12:15], v[158:161], v[202:205], v[12:15]
	v_mfma_f32_16x16x32_bf16 v[60:63], v[162:165], v[178:181], v[60:63]
	v_mfma_f32_16x16x32_bf16 v[56:59], v[170:173], v[178:181], v[56:59]
	v_mfma_f32_16x16x32_bf16 v[40:43], v[170:173], v[186:189], v[40:43]
	v_mfma_f32_16x16x32_bf16 v[44:47], v[162:165], v[186:189], v[44:47]
	v_mfma_f32_16x16x32_bf16 v[28:31], v[162:165], v[198:201], v[28:31]
	v_mfma_f32_16x16x32_bf16 v[24:27], v[170:173], v[198:201], v[24:27]
	v_mfma_f32_16x16x32_bf16 v[8:11], v[170:173], v[206:209], v[8:11]
	v_mfma_f32_16x16x32_bf16 v[12:15], v[162:165], v[206:209], v[12:15]
	s_barrier
	s_add_i32 s16, s31, s18
	v_lshl_add_u64 v[144:145], v[230:231], 0, s[64:65]
	s_mov_b32 m0, s16
	s_nop 0
	global_load_lds_dwordx4 v[144:145], off
	v_lshl_add_u64 v[144:145], v[232:233], 0, s[64:65]
	s_add_i32 m0, s16, 0x2000
	s_nop 0
	global_load_lds_dwordx4 v[144:145], off
	s_waitcnt vmcnt(6)
	s_barrier
	v_mfma_f32_16x16x32_bf16 v[52:55], v[210:213], v[174:177], v[52:55]
	v_mfma_f32_16x16x32_bf16 v[48:51], v[218:221], v[174:177], v[48:51]
	v_mfma_f32_16x16x32_bf16 v[32:35], v[218:221], v[182:185], v[32:35]
	v_mfma_f32_16x16x32_bf16 v[36:39], v[210:213], v[182:185], v[36:39]
	v_mfma_f32_16x16x32_bf16 v[20:23], v[210:213], v[190:193], v[20:23]
	v_mfma_f32_16x16x32_bf16 v[16:19], v[218:221], v[190:193], v[16:19]
	v_mfma_f32_16x16x32_bf16 v[0:3], v[218:221], v[202:205], v[0:3]
	v_mfma_f32_16x16x32_bf16 v[4:7], v[210:213], v[202:205], v[4:7]
	v_mfma_f32_16x16x32_bf16 v[52:55], v[214:217], v[178:181], v[52:55]
	v_mfma_f32_16x16x32_bf16 v[48:51], v[222:225], v[178:181], v[48:51]
	v_mfma_f32_16x16x32_bf16 v[32:35], v[222:225], v[186:189], v[32:35]
	v_mfma_f32_16x16x32_bf16 v[36:39], v[214:217], v[186:189], v[36:39]
	v_mfma_f32_16x16x32_bf16 v[20:23], v[214:217], v[198:201], v[20:23]
	v_mfma_f32_16x16x32_bf16 v[16:19], v[222:225], v[198:201], v[16:19]
	v_mfma_f32_16x16x32_bf16 v[0:3], v[222:225], v[206:209], v[0:3]
	v_mfma_f32_16x16x32_bf16 v[4:7], v[214:217], v[206:209], v[4:7]
	s_add_u32 s14, s14, 0x100
	s_addc_u32 s15, s15, 0
	s_add_u32 s77, s77, 0x100
	s_addc_u32 s78, s78, 0
	s_cmp_ge_i32 s79, s25
	s_mov_b32 s16, s79
	s_barrier
	s_cbranch_scc0 .LBB0_1445

; #define PG8_STAGE(bufoff, gbase, voff) do { _Pragma("unroll") for (int _i = 0; _i < 2; ++_i) \
;         __builtin_amdgcn_global_load_lds((const unsigned*)((const char*)(gbase) + (voff)[_i]), (LAS unsigned*)(lds + (bufoff) + ldsw + _i * 8192), 16, 0, 0); } while (0)
; #define PG8_LDA(dst, b, h) do { _Pragma("unroll") for (int m = 0; m < 4; ++m) _Pragma("unroll") for (int k = 0; k < 2; ++k) dst[m][k] = *(const LAS bf16x8*)(lds + PG8_SA(b, h) + aoff + m * 2048 + k * 1024); } while (0)
; #define PG8_LDB(dst, b, h) do { _Pragma("unroll") for (int n = 0; n < 2; ++n) _Pragma("unroll") for (int k = 0; k < 2; ++k) dst[n][k] = *(const LAS bf16x8*)(lds + PG8_SB(b, h) + boff + n * 2048 + k * 1024); } while (0)
; #define PG8_MMA(ai, bj, At, Bt) do { __builtin_amdgcn_s_setprio(1); _Pragma("unroll") for (int m = 0; m < 4; ++m) _Pragma("unroll") for (int n = 0; n < 2; ++n) _Pragma("unroll") for (int k = 0; k < 2; ++k) \
;         acc[ai][bj][m][n] = __builtin_amdgcn_mfma_f32_16x16x32_bf16(Bt[n][k], At[m][k], acc[ai][bj][m][n], 0, 0, 0); __builtin_amdgcn_s_setprio(0); } while (0)
; #define PG8_WAIT_L(n) asm volatile("s_waitcnt lgkmcnt(" #n ")" ::: "memory")
; #define PG8_BAR __builtin_amdgcn_s_barrier()
; #define PG8_SCHED __builtin_amdgcn_sched_barrier(0)
; template <class Epi>
; DEVI void gemm_phase(LAS unsigned char* lds, const bf16_t* gA, const bf16_t* gBt, const int lda, const int ldb, const int K, const StaticOrder S_, const Epi E) {
;     ...
;         for (int t = 0; t < nt; t += 2) {
;             const bool last = (t == nt - 2);
;             const char* a1 = cA + (size_t)(t + 1) * kstep;
;             const char* a2 = last ? nA : cA + (size_t)(t + 2) * kstep; const char* b2 = last ? nB : cB + (size_t)(t + 2) * kstep;
;             const char* a3 = a2 + kstep; const char* b3 = b2 + kstep;
;             PG8_LDB(B0, 0, 0); PG8_SCHED; PG8_LDA(At, 0, 0); PG8_STAGE(PG8_SA(1, 1), a1 + hstepA, voffA);
;             PG8_WAIT_L(8); PG8_BAR; PG8_WAIT_L(0); PG8_MMA(0, 0, At, B0); PG8_BAR; PG8_SCHED;
;             PG8_LDB(B1, 0, 1); PG8_STAGE(PG8_SB(0, 0), b2, voffB);
;             PG8_BAR; PG8_WAIT_L(0); PG8_MMA(0, 1, At, B1); PG8_BAR;
;             PG8_LDA(At, 0, 1); PG8_STAGE(PG8_SA(0, 0), a2, voffA);
;             PG8_BAR; PG8_WAIT_L(0); PG8_MMA(1, 0, At, B0); PG8_BAR; PG8_SCHED;
.LBB0_1574:
	ds_read_b128 v[128:131], v201
	ds_read_b128 v[132:135], v201 offset:1024
	ds_read_b128 v[136:139], v201 offset:2048
	ds_read_b128 v[140:143], v201 offset:3072
	s_add_i32 s75, s16, 2
	s_add_u32 s40, s14, 0x80
	s_addc_u32 s17, s15, 0
	s_cmp_eq_u32 s19, s16
	s_cselect_b32 s16, s12, s40
	s_cselect_b32 s17, s13, s17
	s_cselect_b32 s41, s43, s71
	s_cselect_b32 s40, s42, s70
	v_lshl_add_u64 v[164:165], s[14:15], 0, v[174:175]
	s_add_i32 m0, s74, 0xc000
	ds_read_b128 v[144:147], v202
	ds_read_b128 v[148:151], v202 offset:1024
	ds_read_b128 v[152:155], v202 offset:2048
	ds_read_b128 v[156:159], v202 offset:3072
	ds_read_b128 v[160:163], v202 offset:4096
	ds_read_b128 v[180:183], v202 offset:5120
	ds_read_b128 v[184:187], v202 offset:6144
	ds_read_b128 v[188:191], v202 offset:7168
	global_load_lds_dwordx4 v[164:165], off
	v_lshl_add_u64 v[164:165], s[14:15], 0, v[176:177]
	s_add_i32 m0, s74, 0xe000
	s_nop 0
	global_load_lds_dwordx4 v[164:165], off
	s_waitcnt lgkmcnt(8)
	s_barrier
	s_waitcnt lgkmcnt(0)
	v_mfma_f32_16x16x32_bf16 v[124:127], v[128:131], v[144:147], v[124:127]
	v_mfma_f32_16x16x32_bf16 v[120:123], v[136:139], v[144:147], v[120:123]
	v_mfma_f32_16x16x32_bf16 v[104:107], v[136:139], v[152:155], v[104:107]
	v_mfma_f32_16x16x32_bf16 v[108:111], v[128:131], v[152:155], v[108:111]
	v_mfma_f32_16x16x32_bf16 v[92:95], v[128:131], v[160:163], v[92:95]
	v_mfma_f32_16x16x32_bf16 v[88:91], v[136:139], v[160:163], v[88:91]
	v_mfma_f32_16x16x32_bf16 v[72:75], v[136:139], v[184:187], v[72:75]
	v_mfma_f32_16x16x32_bf16 v[76:79], v[128:131], v[184:187], v[76:79]
	v_mfma_f32_16x16x32_bf16 v[124:127], v[132:135], v[148:151], v[124:127]
	v_mfma_f32_16x16x32_bf16 v[120:123], v[140:143], v[148:151], v[120:123]
	v_mfma_f32_16x16x32_bf16 v[104:107], v[140:143], v[156:159], v[104:107]
	v_mfma_f32_16x16x32_bf16 v[108:111], v[132:135], v[156:159], v[108:111]
	v_mfma_f32_16x16x32_bf16 v[92:95], v[132:135], v[180:183], v[92:95]
	v_mfma_f32_16x16x32_bf16 v[88:91], v[140:143], v[180:183], v[88:91]
	v_mfma_f32_16x16x32_bf16 v[72:75], v[140:143], v[188:191], v[72:75]
	v_mfma_f32_16x16x32_bf16 v[76:79], v[132:135], v[188:191], v[76:79]
	s_barrier
	s_add_i32 s76, s29, s20
	v_lshl_add_u64 v[164:165], s[40:41], 0, v[168:169]
	s_mov_b32 m0, s76
	ds_read_b128 v[192:195], v203
	ds_read_b128 v[206:209], v203 offset:1024
	ds_read_b128 v[210:213], v203 offset:2048
	ds_read_b128 v[214:217], v203 offset:3072
	global_load_lds_dwordx4 v[164:165], off
	v_lshl_add_u64 v[218:219], s[40:41], 0, v[172:173]
	s_add_i32 m0, s76, 0x2000
	s_nop 0
	global_load_lds_dwordx4 v[218:219], off
	s_barrier
	s_waitcnt lgkmcnt(0)
	v_mfma_f32_16x16x32_bf16 v[116:119], v[192:195], v[144:147], v[116:119]
	v_mfma_f32_16x16x32_bf16 v[112:115], v[210:213], v[144:147], v[112:115]
	v_mfma_f32_16x16x32_bf16 v[96:99], v[210:213], v[152:155], v[96:99]
	v_mfma_f32_16x16x32_bf16 v[100:103], v[192:195], v[152:155], v[100:103]
	v_mfma_f32_16x16x32_bf16 v[84:87], v[192:195], v[160:163], v[84:87]
	v_mfma_f32_16x16x32_bf16 v[80:83], v[210:213], v[160:163], v[80:83]
	v_mfma_f32_16x16x32_bf16 v[64:67], v[210:213], v[184:187], v[64:67]
	v_mfma_f32_16x16x32_bf16 v[68:71], v[192:195], v[184:187], v[68:71]
	v_mfma_f32_16x16x32_bf16 v[116:119], v[206:209], v[148:151], v[116:119]
	v_mfma_f32_16x16x32_bf16 v[112:115], v[214:217], v[148:151], v[112:115]
	v_mfma_f32_16x16x32_bf16 v[96:99], v[214:217], v[156:159], v[96:99]
	v_mfma_f32_16x16x32_bf16 v[100:103], v[206:209], v[156:159], v[100:103]
	v_mfma_f32_16x16x32_bf16 v[84:87], v[206:209], v[180:183], v[84:87]
	v_mfma_f32_16x16x32_bf16 v[80:83], v[214:217], v[180:183], v[80:83]
	v_mfma_f32_16x16x32_bf16 v[64:67], v[214:217], v[188:191], v[64:67]
	v_mfma_f32_16x16x32_bf16 v[68:71], v[206:209], v[188:191], v[68:71]
	s_mov_b32 m0, s74
	v_lshl_add_u64 v[220:221], s[16:17], 0, v[166:167]
	s_barrier
	ds_read_b128 v[144:147], v202 offset:16384
	ds_read_b128 v[148:151], v202 offset:17408
	ds_read_b128 v[152:155], v202 offset:18432
	ds_read_b128 v[156:159], v202 offset:19456
	ds_read_b128 v[160:163], v202 offset:20480
	ds_read_b128 v[180:183], v202 offset:21504
	ds_read_b128 v[184:187], v202 offset:22528
	ds_read_b128 v[188:191], v202 offset:23552
	global_load_lds_dwordx4 v[220:221], off
	v_lshl_add_u64 v[222:223], s[16:17], 0, v[170:171]
	s_mov_b32 m0, s22
	s_nop 0
	global_load_lds_dwordx4 v[222:223], off
	s_barrier
	s_waitcnt lgkmcnt(0)
	v_mfma_f32_16x16x32_bf16 v[60:63], v[128:131], v[144:147], v[60:63]
	v_mfma_f32_16x16x32_bf16 v[56:59], v[136:139], v[144:147], v[56:59]
	v_mfma_f32_16x16x32_bf16 v[40:43], v[136:139], v[152:155], v[40:43]
	v_mfma_f32_16x16x32_bf16 v[44:47], v[128:131], v[152:155], v[44:47]
	v_mfma_f32_16x16x32_bf16 v[28:31], v[128:131], v[160:163], v[28:31]
	v_mfma_f32_16x16x32_bf16 v[24:27], v[136:139], v[160:163], v[24:27]
	v_mfma_f32_16x16x32_bf16 v[8:11], v[136:139], v[184:187], v[8:11]
	v_mfma_f32_16x16x32_bf16 v[12:15], v[128:131], v[184:187], v[12:15]
	v_mfma_f32_16x16x32_bf16 v[60:63], v[132:135], v[148:151], v[60:63]
	v_mfma_f32_16x16x32_bf16 v[56:59], v[140:143], v[148:151], v[56:59]
	v_mfma_f32_16x16x32_bf16 v[40:43], v[140:143], v[156:159], v[40:43]
	v_mfma_f32_16x16x32_bf16 v[44:47], v[132:135], v[156:159], v[44:47]
	v_mfma_f32_16x16x32_bf16 v[28:31], v[132:135], v[180:183], v[28:31]
	v_mfma_f32_16x16x32_bf16 v[24:27], v[140:143], v[180:183], v[24:27]
	v_mfma_f32_16x16x32_bf16 v[8:11], v[140:143], v[188:191], v[8:11]
	v_mfma_f32_16x16x32_bf16 v[12:15], v[132:135], v[188:191], v[12:15]
	s_barrier
; #define PG8_STAGE(bufoff, gbase, voff) do { _Pragma("unroll") for (int _i = 0; _i < 2; ++_i) \
;         __builtin_amdgcn_global_load_lds((const unsigned*)((const char*)(gbase) + (voff)[_i]), (LAS unsigned*)(lds + (bufoff) + ldsw + _i * 8192), 16, 0, 0); } while (0)
; #define PG8_LDA(dst, b, h) do { _Pragma("unroll") for (int m = 0; m < 4; ++m) _Pragma("unroll") for (int k = 0; k < 2; ++k) dst[m][k] = *(const LAS bf16x8*)(lds + PG8_SA(b, h) + aoff + m * 2048 + k * 1024); } while (0)
; #define PG8_LDB(dst, b, h) do { _Pragma("unroll") for (int n = 0; n < 2; ++n) _Pragma("unroll") for (int k = 0; k < 2; ++k) dst[n][k] = *(const LAS bf16x8*)(lds + PG8_SB(b, h) + boff + n * 2048 + k * 1024); } while (0)
; #define PG8_MMA(ai, bj, At, Bt) do { __builtin_amdgcn_s_setprio(1); _Pragma("unroll") for (int m = 0; m < 4; ++m) _Pragma("unroll") for (int n = 0; n < 2; ++n) _Pragma("unroll") for (int k = 0; k < 2; ++k) \
;         acc[ai][bj][m][n] = __builtin_amdgcn_mfma_f32_16x16x32_bf16(Bt[n][k], At[m][k], acc[ai][bj][m][n], 0, 0, 0); __builtin_amdgcn_s_setprio(0); } while (0)
; #define PG8_WAIT_V(n) asm volatile("s_waitcnt vmcnt(" #n ")" ::: "memory")
; #define PG8_WAIT_L(n) asm volatile("s_waitcnt lgkmcnt(" #n ")" ::: "memory")
; #define PG8_BAR __builtin_amdgcn_s_barrier()
; #define PG8_SCHED __builtin_amdgcn_sched_barrier(0)
; template <class Epi>
; DEVI void gemm_phase(LAS unsigned char* lds, const bf16_t* gA, const bf16_t* gBt, const int lda, const int ldb, const int K, const StaticOrder S_, const Epi E) {
;     ...
;             PG8_STAGE(PG8_SB(0, 1), b2 + hstepB, voffB);
;             PG8_WAIT_V(6); PG8_BAR; PG8_MMA(1, 1, At, B1); PG8_BAR;
;             PG8_LDB(B0, 1, 0); PG8_SCHED; PG8_LDA(At, 1, 0); PG8_STAGE(PG8_SA(0, 1), a2 + hstepA, voffA);
;             PG8_WAIT_L(8); PG8_BAR; PG8_WAIT_L(0); PG8_MMA(0, 0, At, B0); PG8_BAR; PG8_SCHED;
;             PG8_LDB(B1, 1, 1); PG8_STAGE(PG8_SB(1, 0), b3, voffB);
;             PG8_BAR; PG8_WAIT_L(0); PG8_MMA(0, 1, At, B1); PG8_BAR;
;             PG8_LDA(At, 1, 1); PG8_STAGE(PG8_SA(1, 0), a3, voffA);
;             PG8_BAR; PG8_WAIT_L(0); PG8_MMA(1, 0, At, B0); PG8_BAR; PG8_SCHED;
;             PG8_STAGE(PG8_SB(1, 1), b3 + hstepB, voffB);
	s_add_u32 s40, s40, s2
	s_addc_u32 s41, s41, s3
	s_add_i32 s76, s50, s20
	v_lshl_add_u64 v[224:225], s[40:41], 0, v[168:169]
	s_mov_b32 m0, s76
	v_lshl_add_u64 v[226:227], s[40:41], 0, v[172:173]
	global_load_lds_dwordx4 v[224:225], off
	s_add_i32 m0, s76, 0x2000
	s_nop 0
	global_load_lds_dwordx4 v[226:227], off
	s_waitcnt vmcnt(6)
	s_barrier
	v_mfma_f32_16x16x32_bf16 v[52:55], v[192:195], v[144:147], v[52:55]
	v_mfma_f32_16x16x32_bf16 v[48:51], v[210:213], v[144:147], v[48:51]
	v_mfma_f32_16x16x32_bf16 v[32:35], v[210:213], v[152:155], v[32:35]
	v_mfma_f32_16x16x32_bf16 v[36:39], v[192:195], v[152:155], v[36:39]
	v_mfma_f32_16x16x32_bf16 v[20:23], v[192:195], v[160:163], v[20:23]
	v_mfma_f32_16x16x32_bf16 v[16:19], v[210:213], v[160:163], v[16:19]
	v_mfma_f32_16x16x32_bf16 v[0:3], v[210:213], v[184:187], v[0:3]
	v_mfma_f32_16x16x32_bf16 v[4:7], v[192:195], v[184:187], v[4:7]
	v_mfma_f32_16x16x32_bf16 v[52:55], v[206:209], v[148:151], v[52:55]
	v_mfma_f32_16x16x32_bf16 v[48:51], v[214:217], v[148:151], v[48:51]
	v_mfma_f32_16x16x32_bf16 v[32:35], v[214:217], v[156:159], v[32:35]
	v_mfma_f32_16x16x32_bf16 v[36:39], v[206:209], v[156:159], v[36:39]
	v_mfma_f32_16x16x32_bf16 v[20:23], v[206:209], v[180:183], v[20:23]
	v_mfma_f32_16x16x32_bf16 v[16:19], v[214:217], v[180:183], v[16:19]
	v_mfma_f32_16x16x32_bf16 v[0:3], v[214:217], v[188:191], v[0:3]
	v_mfma_f32_16x16x32_bf16 v[4:7], v[206:209], v[188:191], v[4:7]
	s_add_i32 s40, 0, 0x18000
	v_add_u32_e32 v140, s40, v199
	s_barrier
	ds_read_b128 v[128:131], v140
	ds_read_b128 v[132:135], v140 offset:1024
	ds_read_b128 v[136:139], v140 offset:2048
	ds_read_b128 v[140:143], v140 offset:3072
	s_add_u32 s16, s16, s0
	s_addc_u32 s17, s17, s1
	s_mov_b32 m0, s23
	v_lshl_add_u64 v[192:193], s[16:17], 0, v[166:167]
	ds_read_b128 v[144:147], v202 offset:32768
	ds_read_b128 v[148:151], v202 offset:33792
	ds_read_b128 v[152:155], v202 offset:34816
	ds_read_b128 v[156:159], v202 offset:35840
	ds_read_b128 v[160:163], v202 offset:36864
	ds_read_b128 v[180:183], v202 offset:37888
	ds_read_b128 v[184:187], v202 offset:38912
	ds_read_b128 v[188:191], v202 offset:39936
	global_load_lds_dwordx4 v[192:193], off
	v_lshl_add_u64 v[192:193], s[16:17], 0, v[170:171]
	s_mov_b32 m0, s24
	s_nop 0
	global_load_lds_dwordx4 v[192:193], off
	s_waitcnt lgkmcnt(8)
	s_barrier
	s_waitcnt lgkmcnt(0)
	v_mfma_f32_16x16x32_bf16 v[124:127], v[128:131], v[144:147], v[124:127]
	v_mfma_f32_16x16x32_bf16 v[120:123], v[136:139], v[144:147], v[120:123]
	v_mfma_f32_16x16x32_bf16 v[104:107], v[136:139], v[152:155], v[104:107]
	v_mfma_f32_16x16x32_bf16 v[108:111], v[128:131], v[152:155], v[108:111]
	v_mfma_f32_16x16x32_bf16 v[92:95], v[128:131], v[160:163], v[92:95]
	v_mfma_f32_16x16x32_bf16 v[88:91], v[136:139], v[160:163], v[88:91]
	v_mfma_f32_16x16x32_bf16 v[72:75], v[136:139], v[184:187], v[72:75]
	v_mfma_f32_16x16x32_bf16 v[76:79], v[128:131], v[184:187], v[76:79]
	v_mfma_f32_16x16x32_bf16 v[124:127], v[132:135], v[148:151], v[124:127]
	v_mfma_f32_16x16x32_bf16 v[120:123], v[140:143], v[148:151], v[120:123]
	v_mfma_f32_16x16x32_bf16 v[104:107], v[140:143], v[156:159], v[104:107]
	v_mfma_f32_16x16x32_bf16 v[108:111], v[132:135], v[156:159], v[108:111]
	v_mfma_f32_16x16x32_bf16 v[92:95], v[132:135], v[180:183], v[92:95]
	v_mfma_f32_16x16x32_bf16 v[88:91], v[140:143], v[180:183], v[88:91]
	v_mfma_f32_16x16x32_bf16 v[72:75], v[140:143], v[188:191], v[72:75]
	v_mfma_f32_16x16x32_bf16 v[76:79], v[132:135], v[188:191], v[76:79]
	s_barrier
	s_add_i32 s16, 0, 0x1c000
	s_add_i32 s17, s40, s20
	v_add_u32_e32 v205, s16, v199
	v_lshl_add_u64 v[164:165], v[164:165], 0, s[8:9]
	s_mov_b32 m0, s17
	ds_read_b128 v[192:195], v205
	ds_read_b128 v[206:209], v205 offset:1024
	ds_read_b128 v[210:213], v205 offset:2048
	ds_read_b128 v[214:217], v205 offset:3072
	global_load_lds_dwordx4 v[164:165], off
	v_lshl_add_u64 v[164:165], v[218:219], 0, s[8:9]
	s_add_i32 m0, s17, 0x2000
	s_nop 0
	global_load_lds_dwordx4 v[164:165], off
	s_barrier
; #define PG8_STAGE(bufoff, gbase, voff) do { _Pragma("unroll") for (int _i = 0; _i < 2; ++_i) \
;         __builtin_amdgcn_global_load_lds((const unsigned*)((const char*)(gbase) + (voff)[_i]), (LAS unsigned*)(lds + (bufoff) + ldsw + _i * 8192), 16, 0, 0); } while (0)
; #define PG8_LDA(dst, b, h) do { _Pragma("unroll") for (int m = 0; m < 4; ++m) _Pragma("unroll") for (int k = 0; k < 2; ++k) dst[m][k] = *(const LAS bf16x8*)(lds + PG8_SA(b, h) + aoff + m * 2048 + k * 1024); } while (0)
; #define PG8_MMA(ai, bj, At, Bt) do { __builtin_amdgcn_s_setprio(1); _Pragma("unroll") for (int m = 0; m < 4; ++m) _Pragma("unroll") for (int n = 0; n < 2; ++n) _Pragma("unroll") for (int k = 0; k < 2; ++k) \
;         acc[ai][bj][m][n] = __builtin_amdgcn_mfma_f32_16x16x32_bf16(Bt[n][k], At[m][k], acc[ai][bj][m][n], 0, 0, 0); __builtin_amdgcn_s_setprio(0); } while (0)
; #define PG8_WAIT_V(n) asm volatile("s_waitcnt vmcnt(" #n ")" ::: "memory")
; #define PG8_WAIT_L(n) asm volatile("s_waitcnt lgkmcnt(" #n ")" ::: "memory")
; #define PG8_BAR __builtin_amdgcn_s_barrier()
; #define PG8_SCHED __builtin_amdgcn_sched_barrier(0)
; template <class Epi>
; DEVI void gemm_phase(LAS unsigned char* lds, const bf16_t* gA, const bf16_t* gBt, const int lda, const int ldb, const int K, const StaticOrder S_, const Epi E) {
;     ...
;             PG8_BAR; PG8_WAIT_L(0); PG8_MMA(0, 1, At, B1); PG8_BAR;
;             PG8_LDA(At, 1, 1); PG8_STAGE(PG8_SA(1, 0), a3, voffA);
;             PG8_BAR; PG8_WAIT_L(0); PG8_MMA(1, 0, At, B0); PG8_BAR; PG8_SCHED;
;             PG8_STAGE(PG8_SB(1, 1), b3 + hstepB, voffB);
;             PG8_WAIT_V(6); PG8_BAR; PG8_MMA(1, 1, At, B1); PG8_BAR;
	s_waitcnt lgkmcnt(0)
	v_mfma_f32_16x16x32_bf16 v[116:119], v[192:195], v[144:147], v[116:119]
	v_mfma_f32_16x16x32_bf16 v[112:115], v[210:213], v[144:147], v[112:115]
	v_mfma_f32_16x16x32_bf16 v[96:99], v[210:213], v[152:155], v[96:99]
	v_mfma_f32_16x16x32_bf16 v[100:103], v[192:195], v[152:155], v[100:103]
	v_mfma_f32_16x16x32_bf16 v[84:87], v[192:195], v[160:163], v[84:87]
	v_mfma_f32_16x16x32_bf16 v[80:83], v[210:213], v[160:163], v[80:83]
	v_mfma_f32_16x16x32_bf16 v[64:67], v[210:213], v[184:187], v[64:67]
	v_mfma_f32_16x16x32_bf16 v[68:71], v[192:195], v[184:187], v[68:71]
	v_mfma_f32_16x16x32_bf16 v[116:119], v[206:209], v[148:151], v[116:119]
	v_mfma_f32_16x16x32_bf16 v[112:115], v[214:217], v[148:151], v[112:115]
	v_mfma_f32_16x16x32_bf16 v[96:99], v[214:217], v[156:159], v[96:99]
	v_mfma_f32_16x16x32_bf16 v[100:103], v[206:209], v[156:159], v[100:103]
	v_mfma_f32_16x16x32_bf16 v[84:87], v[206:209], v[180:183], v[84:87]
	v_mfma_f32_16x16x32_bf16 v[80:83], v[214:217], v[180:183], v[80:83]
	v_mfma_f32_16x16x32_bf16 v[64:67], v[214:217], v[188:191], v[64:67]
	v_mfma_f32_16x16x32_bf16 v[68:71], v[206:209], v[188:191], v[68:71]
	s_mov_b32 m0, s26
	v_lshl_add_u64 v[164:165], v[220:221], 0, s[8:9]
	s_barrier
	ds_read_b128 v[144:147], v202 offset:49152
	ds_read_b128 v[148:151], v202 offset:50176
	ds_read_b128 v[152:155], v202 offset:51200
	ds_read_b128 v[156:159], v202 offset:52224
	ds_read_b128 v[160:163], v202 offset:53248
	ds_read_b128 v[180:183], v202 offset:54272
	ds_read_b128 v[184:187], v202 offset:55296
	ds_read_b128 v[188:191], v202 offset:56320
	global_load_lds_dwordx4 v[164:165], off
	v_lshl_add_u64 v[164:165], v[222:223], 0, s[8:9]
	s_mov_b32 m0, s27
	s_nop 0
	global_load_lds_dwordx4 v[164:165], off
	s_barrier
	s_waitcnt lgkmcnt(0)
	v_mfma_f32_16x16x32_bf16 v[60:63], v[128:131], v[144:147], v[60:63]
	v_mfma_f32_16x16x32_bf16 v[56:59], v[136:139], v[144:147], v[56:59]
	v_mfma_f32_16x16x32_bf16 v[40:43], v[136:139], v[152:155], v[40:43]
	v_mfma_f32_16x16x32_bf16 v[44:47], v[128:131], v[152:155], v[44:47]
	v_mfma_f32_16x16x32_bf16 v[28:31], v[128:131], v[160:163], v[28:31]
	v_mfma_f32_16x16x32_bf16 v[24:27], v[136:139], v[160:163], v[24:27]
	v_mfma_f32_16x16x32_bf16 v[8:11], v[136:139], v[184:187], v[8:11]
	v_mfma_f32_16x16x32_bf16 v[12:15], v[128:131], v[184:187], v[12:15]
	v_mfma_f32_16x16x32_bf16 v[60:63], v[132:135], v[148:151], v[60:63]
	v_mfma_f32_16x16x32_bf16 v[56:59], v[140:143], v[148:151], v[56:59]
	v_mfma_f32_16x16x32_bf16 v[40:43], v[140:143], v[156:159], v[40:43]
	v_mfma_f32_16x16x32_bf16 v[44:47], v[132:135], v[156:159], v[44:47]
	v_mfma_f32_16x16x32_bf16 v[28:31], v[132:135], v[180:183], v[28:31]
	v_mfma_f32_16x16x32_bf16 v[24:27], v[140:143], v[180:183], v[24:27]
	v_mfma_f32_16x16x32_bf16 v[8:11], v[140:143], v[188:191], v[8:11]
	v_mfma_f32_16x16x32_bf16 v[12:15], v[132:135], v[188:191], v[12:15]
	s_barrier
	s_add_i32 s16, s16, s20
	v_lshl_add_u64 v[128:129], v[224:225], 0, s[8:9]
	s_mov_b32 m0, s16
	s_nop 0
	global_load_lds_dwordx4 v[128:129], off
	v_lshl_add_u64 v[128:129], v[226:227], 0, s[8:9]
	s_add_i32 m0, s16, 0x2000
	s_nop 0
	global_load_lds_dwordx4 v[128:129], off
	s_waitcnt vmcnt(6)
	s_barrier
	v_mfma_f32_16x16x32_bf16 v[52:55], v[192:195], v[144:147], v[52:55]
	v_mfma_f32_16x16x32_bf16 v[48:51], v[210:213], v[144:147], v[48:51]
	v_mfma_f32_16x16x32_bf16 v[32:35], v[210:213], v[152:155], v[32:35]
	v_mfma_f32_16x16x32_bf16 v[36:39], v[192:195], v[152:155], v[36:39]
	v_mfma_f32_16x16x32_bf16 v[20:23], v[192:195], v[160:163], v[20:23]
	v_mfma_f32_16x16x32_bf16 v[16:19], v[210:213], v[160:163], v[16:19]
	v_mfma_f32_16x16x32_bf16 v[0:3], v[210:213], v[184:187], v[0:3]
	v_mfma_f32_16x16x32_bf16 v[4:7], v[192:195], v[184:187], v[4:7]
	v_mfma_f32_16x16x32_bf16 v[52:55], v[206:209], v[148:151], v[52:55]
	v_mfma_f32_16x16x32_bf16 v[48:51], v[214:217], v[148:151], v[48:51]
	v_mfma_f32_16x16x32_bf16 v[32:35], v[214:217], v[156:159], v[32:35]
	v_mfma_f32_16x16x32_bf16 v[36:39], v[206:209], v[156:159], v[36:39]
	v_mfma_f32_16x16x32_bf16 v[20:23], v[206:209], v[180:183], v[20:23]
	v_mfma_f32_16x16x32_bf16 v[16:19], v[214:217], v[180:183], v[16:19]
	v_mfma_f32_16x16x32_bf16 v[0:3], v[214:217], v[188:191], v[0:3]
	v_mfma_f32_16x16x32_bf16 v[4:7], v[206:209], v[188:191], v[4:7]
	s_add_u32 s14, s14, 0x100
	s_addc_u32 s15, s15, 0
	s_add_u32 s70, s70, 0x100
	s_addc_u32 s71, s71, 0
	s_cmp_ge_i32 s75, s25
	s_mov_b32 s16, s75
	s_barrier
	s_cbranch_scc0 .LBB0_1574
	v_readlane_b32 s76, v238, 50
	v_readlane_b32 s77, v238, 51
	v_readlane_b32 s78, v238, 52
	v_readlane_b32 s79, v238, 53
	v_readlane_b32 s80, v238, 54
	v_readlane_b32 s81, v238, 55
	v_readlane_b32 s82, v238, 56
	v_readlane_b32 s83, v238, 57

; #define PG8_STAGE(bufoff, gbase, voff) do { _Pragma("unroll") for (int _i = 0; _i < 2; ++_i) \
;         __builtin_amdgcn_global_load_lds((const unsigned*)((const char*)(gbase) + (voff)[_i]), (LAS unsigned*)(lds + (bufoff) + ldsw + _i * 8192), 16, 0, 0); } while (0)
; #define PG8_LDA(dst, b, h) do { _Pragma("unroll") for (int m = 0; m < 4; ++m) _Pragma("unroll") for (int k = 0; k < 2; ++k) dst[m][k] = *(const LAS bf16x8*)(lds + PG8_SA(b, h) + aoff + m * 2048 + k * 1024); } while (0)
; #define PG8_LDB(dst, b, h) do { _Pragma("unroll") for (int n = 0; n < 2; ++n) _Pragma("unroll") for (int k = 0; k < 2; ++k) dst[n][k] = *(const LAS bf16x8*)(lds + PG8_SB(b, h) + boff + n * 2048 + k * 1024); } while (0)
; #define PG8_MMA(ai, bj, At, Bt) do { __builtin_amdgcn_s_setprio(1); _Pragma("unroll") for (int m = 0; m < 4; ++m) _Pragma("unroll") for (int n = 0; n < 2; ++n) _Pragma("unroll") for (int k = 0; k < 2; ++k) \
;         acc[ai][bj][m][n] = __builtin_amdgcn_mfma_f32_16x16x32_bf16(Bt[n][k], At[m][k], acc[ai][bj][m][n], 0, 0, 0); __builtin_amdgcn_s_setprio(0); } while (0)
; #define PG8_WAIT_L(n) asm volatile("s_waitcnt lgkmcnt(" #n ")" ::: "memory")
; #define PG8_BAR __builtin_amdgcn_s_barrier()
; #define PG8_SCHED __builtin_amdgcn_sched_barrier(0)
; template <class Epi>
; DEVI void gemm_phase(LAS unsigned char* lds, const bf16_t* gA, const bf16_t* gBt, const int lda, const int ldb, const int K, const StaticOrder S_, const Epi E) {
;     ...
;         for (int t = 0; t < nt; t += 2) {
;             const bool last = (t == nt - 2);
;             const char* a1 = cA + (size_t)(t + 1) * kstep;
;             const char* a2 = last ? nA : cA + (size_t)(t + 2) * kstep; const char* b2 = last ? nB : cB + (size_t)(t + 2) * kstep;
;             const char* a3 = a2 + kstep; const char* b3 = b2 + kstep;
;             PG8_LDB(B0, 0, 0); PG8_SCHED; PG8_LDA(At, 0, 0); PG8_STAGE(PG8_SA(1, 1), a1 + hstepA, voffA);
;             PG8_WAIT_L(8); PG8_BAR; PG8_WAIT_L(0); PG8_MMA(0, 0, At, B0); PG8_BAR; PG8_SCHED;
;             PG8_LDB(B1, 0, 1); PG8_STAGE(PG8_SB(0, 0), b2, voffB);
;             PG8_BAR; PG8_WAIT_L(0); PG8_MMA(0, 1, At, B1); PG8_BAR;
;             PG8_LDA(At, 0, 1); PG8_STAGE(PG8_SA(0, 0), a2, voffA);
;             PG8_BAR; PG8_WAIT_L(0); PG8_MMA(1, 0, At, B0); PG8_BAR; PG8_SCHED;
.LBB0_1848:
	ds_read_b128 v[128:131], v201
	ds_read_b128 v[132:135], v201 offset:1024
	ds_read_b128 v[136:139], v201 offset:2048
	ds_read_b128 v[140:143], v201 offset:3072
	s_add_i32 s64, s16, 2
	s_add_u32 s38, s14, 0x80
	s_addc_u32 s17, s15, 0
	s_cmp_eq_u32 s19, s16
	s_cselect_b32 s16, s12, s38
	s_cselect_b32 s17, s13, s17
	s_cselect_b32 s39, s41, s57
	s_cselect_b32 s38, s40, s56
	v_lshl_add_u64 v[164:165], s[14:15], 0, v[174:175]
	s_add_i32 m0, s61, 0xc000
	ds_read_b128 v[144:147], v202
	ds_read_b128 v[148:151], v202 offset:1024
	ds_read_b128 v[152:155], v202 offset:2048
	ds_read_b128 v[156:159], v202 offset:3072
	ds_read_b128 v[160:163], v202 offset:4096
	ds_read_b128 v[180:183], v202 offset:5120
	ds_read_b128 v[184:187], v202 offset:6144
	ds_read_b128 v[188:191], v202 offset:7168
	global_load_lds_dwordx4 v[164:165], off
	v_lshl_add_u64 v[164:165], s[14:15], 0, v[176:177]
	s_add_i32 m0, s61, 0xe000
	s_nop 0
	global_load_lds_dwordx4 v[164:165], off
	s_waitcnt lgkmcnt(8)
	s_barrier
	s_waitcnt lgkmcnt(0)
	v_mfma_f32_16x16x32_bf16 v[124:127], v[128:131], v[144:147], v[124:127]
	v_mfma_f32_16x16x32_bf16 v[120:123], v[136:139], v[144:147], v[120:123]
	v_mfma_f32_16x16x32_bf16 v[104:107], v[136:139], v[152:155], v[104:107]
	v_mfma_f32_16x16x32_bf16 v[108:111], v[128:131], v[152:155], v[108:111]
	v_mfma_f32_16x16x32_bf16 v[92:95], v[128:131], v[160:163], v[92:95]
	v_mfma_f32_16x16x32_bf16 v[88:91], v[136:139], v[160:163], v[88:91]
	v_mfma_f32_16x16x32_bf16 v[72:75], v[136:139], v[184:187], v[72:75]
	v_mfma_f32_16x16x32_bf16 v[76:79], v[128:131], v[184:187], v[76:79]
	v_mfma_f32_16x16x32_bf16 v[124:127], v[132:135], v[148:151], v[124:127]
	v_mfma_f32_16x16x32_bf16 v[120:123], v[140:143], v[148:151], v[120:123]
	v_mfma_f32_16x16x32_bf16 v[104:107], v[140:143], v[156:159], v[104:107]
	v_mfma_f32_16x16x32_bf16 v[108:111], v[132:135], v[156:159], v[108:111]
	v_mfma_f32_16x16x32_bf16 v[92:95], v[132:135], v[180:183], v[92:95]
	v_mfma_f32_16x16x32_bf16 v[88:91], v[140:143], v[180:183], v[88:91]
	v_mfma_f32_16x16x32_bf16 v[72:75], v[140:143], v[188:191], v[72:75]
	v_mfma_f32_16x16x32_bf16 v[76:79], v[132:135], v[188:191], v[76:79]
	s_barrier
	s_add_i32 s65, s29, s20
	v_lshl_add_u64 v[164:165], s[38:39], 0, v[168:169]
	s_mov_b32 m0, s65
	ds_read_b128 v[192:195], v203
	ds_read_b128 v[206:209], v203 offset:1024
	ds_read_b128 v[210:213], v203 offset:2048
	ds_read_b128 v[214:217], v203 offset:3072
	global_load_lds_dwordx4 v[164:165], off
	v_lshl_add_u64 v[218:219], s[38:39], 0, v[172:173]
	s_add_i32 m0, s65, 0x2000
	s_nop 0
	global_load_lds_dwordx4 v[218:219], off
	s_barrier
	s_waitcnt lgkmcnt(0)
	v_mfma_f32_16x16x32_bf16 v[116:119], v[192:195], v[144:147], v[116:119]
	v_mfma_f32_16x16x32_bf16 v[112:115], v[210:213], v[144:147], v[112:115]
	v_mfma_f32_16x16x32_bf16 v[96:99], v[210:213], v[152:155], v[96:99]
	v_mfma_f32_16x16x32_bf16 v[100:103], v[192:195], v[152:155], v[100:103]
	v_mfma_f32_16x16x32_bf16 v[84:87], v[192:195], v[160:163], v[84:87]
	v_mfma_f32_16x16x32_bf16 v[80:83], v[210:213], v[160:163], v[80:83]
	v_mfma_f32_16x16x32_bf16 v[64:67], v[210:213], v[184:187], v[64:67]
	v_mfma_f32_16x16x32_bf16 v[68:71], v[192:195], v[184:187], v[68:71]
	v_mfma_f32_16x16x32_bf16 v[116:119], v[206:209], v[148:151], v[116:119]
	v_mfma_f32_16x16x32_bf16 v[112:115], v[214:217], v[148:151], v[112:115]
	v_mfma_f32_16x16x32_bf16 v[96:99], v[214:217], v[156:159], v[96:99]
	v_mfma_f32_16x16x32_bf16 v[100:103], v[206:209], v[156:159], v[100:103]
	v_mfma_f32_16x16x32_bf16 v[84:87], v[206:209], v[180:183], v[84:87]
	v_mfma_f32_16x16x32_bf16 v[80:83], v[214:217], v[180:183], v[80:83]
	v_mfma_f32_16x16x32_bf16 v[64:67], v[214:217], v[188:191], v[64:67]
	v_mfma_f32_16x16x32_bf16 v[68:71], v[206:209], v[188:191], v[68:71]
	s_mov_b32 m0, s61
	v_lshl_add_u64 v[220:221], s[16:17], 0, v[166:167]
	s_barrier
	ds_read_b128 v[144:147], v202 offset:16384
	ds_read_b128 v[148:151], v202 offset:17408
	ds_read_b128 v[152:155], v202 offset:18432
	ds_read_b128 v[156:159], v202 offset:19456
	ds_read_b128 v[160:163], v202 offset:20480
	ds_read_b128 v[180:183], v202 offset:21504
	ds_read_b128 v[184:187], v202 offset:22528
	ds_read_b128 v[188:191], v202 offset:23552
	global_load_lds_dwordx4 v[220:221], off
	v_lshl_add_u64 v[222:223], s[16:17], 0, v[170:171]
	s_mov_b32 m0, s22
	s_nop 0
	global_load_lds_dwordx4 v[222:223], off
	s_barrier
	s_waitcnt lgkmcnt(0)
	v_mfma_f32_16x16x32_bf16 v[60:63], v[128:131], v[144:147], v[60:63]
	v_mfma_f32_16x16x32_bf16 v[56:59], v[136:139], v[144:147], v[56:59]
	v_mfma_f32_16x16x32_bf16 v[40:43], v[136:139], v[152:155], v[40:43]
	v_mfma_f32_16x16x32_bf16 v[44:47], v[128:131], v[152:155], v[44:47]
	v_mfma_f32_16x16x32_bf16 v[28:31], v[128:131], v[160:163], v[28:31]
	v_mfma_f32_16x16x32_bf16 v[24:27], v[136:139], v[160:163], v[24:27]
	v_mfma_f32_16x16x32_bf16 v[8:11], v[136:139], v[184:187], v[8:11]
	v_mfma_f32_16x16x32_bf16 v[12:15], v[128:131], v[184:187], v[12:15]
	v_mfma_f32_16x16x32_bf16 v[60:63], v[132:135], v[148:151], v[60:63]
	v_mfma_f32_16x16x32_bf16 v[56:59], v[140:143], v[148:151], v[56:59]
	v_mfma_f32_16x16x32_bf16 v[40:43], v[140:143], v[156:159], v[40:43]
	v_mfma_f32_16x16x32_bf16 v[44:47], v[132:135], v[156:159], v[44:47]
	v_mfma_f32_16x16x32_bf16 v[28:31], v[132:135], v[180:183], v[28:31]
	v_mfma_f32_16x16x32_bf16 v[24:27], v[140:143], v[180:183], v[24:27]
	v_mfma_f32_16x16x32_bf16 v[8:11], v[140:143], v[188:191], v[8:11]
	v_mfma_f32_16x16x32_bf16 v[12:15], v[132:135], v[188:191], v[12:15]
	s_barrier
; #define PG8_STAGE(bufoff, gbase, voff) do { _Pragma("unroll") for (int _i = 0; _i < 2; ++_i) \
;         __builtin_amdgcn_global_load_lds((const unsigned*)((const char*)(gbase) + (voff)[_i]), (LAS unsigned*)(lds + (bufoff) + ldsw + _i * 8192), 16, 0, 0); } while (0)
; #define PG8_LDA(dst, b, h) do { _Pragma("unroll") for (int m = 0; m < 4; ++m) _Pragma("unroll") for (int k = 0; k < 2; ++k) dst[m][k] = *(const LAS bf16x8*)(lds + PG8_SA(b, h) + aoff + m * 2048 + k * 1024); } while (0)
; #define PG8_LDB(dst, b, h) do { _Pragma("unroll") for (int n = 0; n < 2; ++n) _Pragma("unroll") for (int k = 0; k < 2; ++k) dst[n][k] = *(const LAS bf16x8*)(lds + PG8_SB(b, h) + boff + n * 2048 + k * 1024); } while (0)
; #define PG8_MMA(ai, bj, At, Bt) do { __builtin_amdgcn_s_setprio(1); _Pragma("unroll") for (int m = 0; m < 4; ++m) _Pragma("unroll") for (int n = 0; n < 2; ++n) _Pragma("unroll") for (int k = 0; k < 2; ++k) \
;         acc[ai][bj][m][n] = __builtin_amdgcn_mfma_f32_16x16x32_bf16(Bt[n][k], At[m][k], acc[ai][bj][m][n], 0, 0, 0); __builtin_amdgcn_s_setprio(0); } while (0)
; #define PG8_WAIT_V(n) asm volatile("s_waitcnt vmcnt(" #n ")" ::: "memory")
; #define PG8_WAIT_L(n) asm volatile("s_waitcnt lgkmcnt(" #n ")" ::: "memory")
; #define PG8_BAR __builtin_amdgcn_s_barrier()
; #define PG8_SCHED __builtin_amdgcn_sched_barrier(0)
; template <class Epi>
; DEVI void gemm_phase(LAS unsigned char* lds, const bf16_t* gA, const bf16_t* gBt, const int lda, const int ldb, const int K, const StaticOrder S_, const Epi E) {
;     ...
;             PG8_STAGE(PG8_SB(0, 1), b2 + hstepB, voffB);
;             PG8_WAIT_V(6); PG8_BAR; PG8_MMA(1, 1, At, B1); PG8_BAR;
;             PG8_LDB(B0, 1, 0); PG8_SCHED; PG8_LDA(At, 1, 0); PG8_STAGE(PG8_SA(0, 1), a2 + hstepA, voffA);
;             PG8_WAIT_L(8); PG8_BAR; PG8_WAIT_L(0); PG8_MMA(0, 0, At, B0); PG8_BAR; PG8_SCHED;
;             PG8_LDB(B1, 1, 1); PG8_STAGE(PG8_SB(1, 0), b3, voffB);
;             PG8_BAR; PG8_WAIT_L(0); PG8_MMA(0, 1, At, B1); PG8_BAR;
;             PG8_LDA(At, 1, 1); PG8_STAGE(PG8_SA(1, 0), a3, voffA);
;             PG8_BAR; PG8_WAIT_L(0); PG8_MMA(1, 0, At, B0); PG8_BAR; PG8_SCHED;
;             PG8_STAGE(PG8_SB(1, 1), b3 + hstepB, voffB);
	s_add_u32 s38, s38, s2
	s_addc_u32 s39, s39, s3
	s_add_i32 s65, s50, s20
	v_lshl_add_u64 v[224:225], s[38:39], 0, v[168:169]
	s_mov_b32 m0, s65
	v_lshl_add_u64 v[226:227], s[38:39], 0, v[172:173]
	global_load_lds_dwordx4 v[224:225], off
	s_add_i32 m0, s65, 0x2000
	s_nop 0
	global_load_lds_dwordx4 v[226:227], off
	s_waitcnt vmcnt(6)
	s_barrier
	v_mfma_f32_16x16x32_bf16 v[52:55], v[192:195], v[144:147], v[52:55]
	v_mfma_f32_16x16x32_bf16 v[48:51], v[210:213], v[144:147], v[48:51]
	v_mfma_f32_16x16x32_bf16 v[32:35], v[210:213], v[152:155], v[32:35]
	v_mfma_f32_16x16x32_bf16 v[36:39], v[192:195], v[152:155], v[36:39]
	v_mfma_f32_16x16x32_bf16 v[20:23], v[192:195], v[160:163], v[20:23]
	v_mfma_f32_16x16x32_bf16 v[16:19], v[210:213], v[160:163], v[16:19]
	v_mfma_f32_16x16x32_bf16 v[0:3], v[210:213], v[184:187], v[0:3]
	v_mfma_f32_16x16x32_bf16 v[4:7], v[192:195], v[184:187], v[4:7]
	v_mfma_f32_16x16x32_bf16 v[52:55], v[206:209], v[148:151], v[52:55]
	v_mfma_f32_16x16x32_bf16 v[48:51], v[214:217], v[148:151], v[48:51]
	v_mfma_f32_16x16x32_bf16 v[32:35], v[214:217], v[156:159], v[32:35]
	v_mfma_f32_16x16x32_bf16 v[36:39], v[206:209], v[156:159], v[36:39]
	v_mfma_f32_16x16x32_bf16 v[20:23], v[206:209], v[180:183], v[20:23]
	v_mfma_f32_16x16x32_bf16 v[16:19], v[214:217], v[180:183], v[16:19]
	v_mfma_f32_16x16x32_bf16 v[0:3], v[214:217], v[188:191], v[0:3]
	v_mfma_f32_16x16x32_bf16 v[4:7], v[206:209], v[188:191], v[4:7]
	s_add_i32 s38, 0, 0x18000
	v_add_u32_e32 v140, s38, v199
	s_barrier
	ds_read_b128 v[128:131], v140
	ds_read_b128 v[132:135], v140 offset:1024
	ds_read_b128 v[136:139], v140 offset:2048
	ds_read_b128 v[140:143], v140 offset:3072
	s_add_u32 s16, s16, s0
	s_addc_u32 s17, s17, s1
	s_mov_b32 m0, s23
	v_lshl_add_u64 v[192:193], s[16:17], 0, v[166:167]
	ds_read_b128 v[144:147], v202 offset:32768
	ds_read_b128 v[148:151], v202 offset:33792
	ds_read_b128 v[152:155], v202 offset:34816
	ds_read_b128 v[156:159], v202 offset:35840
	ds_read_b128 v[160:163], v202 offset:36864
	ds_read_b128 v[180:183], v202 offset:37888
	ds_read_b128 v[184:187], v202 offset:38912
	ds_read_b128 v[188:191], v202 offset:39936
	global_load_lds_dwordx4 v[192:193], off
	v_lshl_add_u64 v[192:193], s[16:17], 0, v[170:171]
	s_mov_b32 m0, s24
	s_nop 0
	global_load_lds_dwordx4 v[192:193], off
	s_waitcnt lgkmcnt(8)
	s_barrier
	s_waitcnt lgkmcnt(0)
	v_mfma_f32_16x16x32_bf16 v[124:127], v[128:131], v[144:147], v[124:127]
	v_mfma_f32_16x16x32_bf16 v[120:123], v[136:139], v[144:147], v[120:123]
	v_mfma_f32_16x16x32_bf16 v[104:107], v[136:139], v[152:155], v[104:107]
	v_mfma_f32_16x16x32_bf16 v[108:111], v[128:131], v[152:155], v[108:111]
	v_mfma_f32_16x16x32_bf16 v[92:95], v[128:131], v[160:163], v[92:95]
	v_mfma_f32_16x16x32_bf16 v[88:91], v[136:139], v[160:163], v[88:91]
	v_mfma_f32_16x16x32_bf16 v[72:75], v[136:139], v[184:187], v[72:75]
	v_mfma_f32_16x16x32_bf16 v[76:79], v[128:131], v[184:187], v[76:79]
	v_mfma_f32_16x16x32_bf16 v[124:127], v[132:135], v[148:151], v[124:127]
	v_mfma_f32_16x16x32_bf16 v[120:123], v[140:143], v[148:151], v[120:123]
	v_mfma_f32_16x16x32_bf16 v[104:107], v[140:143], v[156:159], v[104:107]
	v_mfma_f32_16x16x32_bf16 v[108:111], v[132:135], v[156:159], v[108:111]
	v_mfma_f32_16x16x32_bf16 v[92:95], v[132:135], v[180:183], v[92:95]
	v_mfma_f32_16x16x32_bf16 v[88:91], v[140:143], v[180:183], v[88:91]
	v_mfma_f32_16x16x32_bf16 v[72:75], v[140:143], v[188:191], v[72:75]
	v_mfma_f32_16x16x32_bf16 v[76:79], v[132:135], v[188:191], v[76:79]
	s_barrier
	s_add_i32 s16, 0, 0x1c000
	s_add_i32 s17, s38, s20
	v_add_u32_e32 v205, s16, v199
	v_lshl_add_u64 v[164:165], v[164:165], 0, s[8:9]
	s_mov_b32 m0, s17
	ds_read_b128 v[192:195], v205
	ds_read_b128 v[206:209], v205 offset:1024
	ds_read_b128 v[210:213], v205 offset:2048
	ds_read_b128 v[214:217], v205 offset:3072
	global_load_lds_dwordx4 v[164:165], off
	v_lshl_add_u64 v[164:165], v[218:219], 0, s[8:9]
	s_add_i32 m0, s17, 0x2000
	s_nop 0
	global_load_lds_dwordx4 v[164:165], off
	s_barrier
; #define PG8_STAGE(bufoff, gbase, voff) do { _Pragma("unroll") for (int _i = 0; _i < 2; ++_i) \
;         __builtin_amdgcn_global_load_lds((const unsigned*)((const char*)(gbase) + (voff)[_i]), (LAS unsigned*)(lds + (bufoff) + ldsw + _i * 8192), 16, 0, 0); } while (0)
; #define PG8_LDA(dst, b, h) do { _Pragma("unroll") for (int m = 0; m < 4; ++m) _Pragma("unroll") for (int k = 0; k < 2; ++k) dst[m][k] = *(const LAS bf16x8*)(lds + PG8_SA(b, h) + aoff + m * 2048 + k * 1024); } while (0)
; #define PG8_MMA(ai, bj, At, Bt) do { __builtin_amdgcn_s_setprio(1); _Pragma("unroll") for (int m = 0; m < 4; ++m) _Pragma("unroll") for (int n = 0; n < 2; ++n) _Pragma("unroll") for (int k = 0; k < 2; ++k) \
;         acc[ai][bj][m][n] = __builtin_amdgcn_mfma_f32_16x16x32_bf16(Bt[n][k], At[m][k], acc[ai][bj][m][n], 0, 0, 0); __builtin_amdgcn_s_setprio(0); } while (0)
; #define PG8_WAIT_V(n) asm volatile("s_waitcnt vmcnt(" #n ")" ::: "memory")
; #define PG8_WAIT_L(n) asm volatile("s_waitcnt lgkmcnt(" #n ")" ::: "memory")
; #define PG8_BAR __builtin_amdgcn_s_barrier()
; #define PG8_SCHED __builtin_amdgcn_sched_barrier(0)
; template <class Epi>
; DEVI void gemm_phase(LAS unsigned char* lds, const bf16_t* gA, const bf16_t* gBt, const int lda, const int ldb, const int K, const StaticOrder S_, const Epi E) {
;     ...
;             PG8_BAR; PG8_WAIT_L(0); PG8_MMA(0, 1, At, B1); PG8_BAR;
;             PG8_LDA(At, 1, 1); PG8_STAGE(PG8_SA(1, 0), a3, voffA);
;             PG8_BAR; PG8_WAIT_L(0); PG8_MMA(1, 0, At, B0); PG8_BAR; PG8_SCHED;
;             PG8_STAGE(PG8_SB(1, 1), b3 + hstepB, voffB);
;             PG8_WAIT_V(6); PG8_BAR; PG8_MMA(1, 1, At, B1); PG8_BAR;
	s_waitcnt lgkmcnt(0)
	v_mfma_f32_16x16x32_bf16 v[116:119], v[192:195], v[144:147], v[116:119]
	v_mfma_f32_16x16x32_bf16 v[112:115], v[210:213], v[144:147], v[112:115]
	v_mfma_f32_16x16x32_bf16 v[96:99], v[210:213], v[152:155], v[96:99]
	v_mfma_f32_16x16x32_bf16 v[100:103], v[192:195], v[152:155], v[100:103]
	v_mfma_f32_16x16x32_bf16 v[84:87], v[192:195], v[160:163], v[84:87]
	v_mfma_f32_16x16x32_bf16 v[80:83], v[210:213], v[160:163], v[80:83]
	v_mfma_f32_16x16x32_bf16 v[64:67], v[210:213], v[184:187], v[64:67]
	v_mfma_f32_16x16x32_bf16 v[68:71], v[192:195], v[184:187], v[68:71]
	v_mfma_f32_16x16x32_bf16 v[116:119], v[206:209], v[148:151], v[116:119]
	v_mfma_f32_16x16x32_bf16 v[112:115], v[214:217], v[148:151], v[112:115]
	v_mfma_f32_16x16x32_bf16 v[96:99], v[214:217], v[156:159], v[96:99]
	v_mfma_f32_16x16x32_bf16 v[100:103], v[206:209], v[156:159], v[100:103]
	v_mfma_f32_16x16x32_bf16 v[84:87], v[206:209], v[180:183], v[84:87]
	v_mfma_f32_16x16x32_bf16 v[80:83], v[214:217], v[180:183], v[80:83]
	v_mfma_f32_16x16x32_bf16 v[64:67], v[214:217], v[188:191], v[64:67]
	v_mfma_f32_16x16x32_bf16 v[68:71], v[206:209], v[188:191], v[68:71]
	s_mov_b32 m0, s26
	v_lshl_add_u64 v[164:165], v[220:221], 0, s[8:9]
	s_barrier
	ds_read_b128 v[144:147], v202 offset:49152
	ds_read_b128 v[148:151], v202 offset:50176
	ds_read_b128 v[152:155], v202 offset:51200
	ds_read_b128 v[156:159], v202 offset:52224
	ds_read_b128 v[160:163], v202 offset:53248
	ds_read_b128 v[180:183], v202 offset:54272
	ds_read_b128 v[184:187], v202 offset:55296
	ds_read_b128 v[188:191], v202 offset:56320
	global_load_lds_dwordx4 v[164:165], off
	v_lshl_add_u64 v[164:165], v[222:223], 0, s[8:9]
	s_mov_b32 m0, s27
	s_nop 0
	global_load_lds_dwordx4 v[164:165], off
	s_barrier
	s_waitcnt lgkmcnt(0)
	v_mfma_f32_16x16x32_bf16 v[60:63], v[128:131], v[144:147], v[60:63]
	v_mfma_f32_16x16x32_bf16 v[56:59], v[136:139], v[144:147], v[56:59]
	v_mfma_f32_16x16x32_bf16 v[40:43], v[136:139], v[152:155], v[40:43]
	v_mfma_f32_16x16x32_bf16 v[44:47], v[128:131], v[152:155], v[44:47]
	v_mfma_f32_16x16x32_bf16 v[28:31], v[128:131], v[160:163], v[28:31]
	v_mfma_f32_16x16x32_bf16 v[24:27], v[136:139], v[160:163], v[24:27]
	v_mfma_f32_16x16x32_bf16 v[8:11], v[136:139], v[184:187], v[8:11]
	v_mfma_f32_16x16x32_bf16 v[12:15], v[128:131], v[184:187], v[12:15]
	v_mfma_f32_16x16x32_bf16 v[60:63], v[132:135], v[148:151], v[60:63]
	v_mfma_f32_16x16x32_bf16 v[56:59], v[140:143], v[148:151], v[56:59]
	v_mfma_f32_16x16x32_bf16 v[40:43], v[140:143], v[156:159], v[40:43]
	v_mfma_f32_16x16x32_bf16 v[44:47], v[132:135], v[156:159], v[44:47]
	v_mfma_f32_16x16x32_bf16 v[28:31], v[132:135], v[180:183], v[28:31]
	v_mfma_f32_16x16x32_bf16 v[24:27], v[140:143], v[180:183], v[24:27]
	v_mfma_f32_16x16x32_bf16 v[8:11], v[140:143], v[188:191], v[8:11]
	v_mfma_f32_16x16x32_bf16 v[12:15], v[132:135], v[188:191], v[12:15]
	s_barrier
	s_add_i32 s16, s16, s20
	v_lshl_add_u64 v[128:129], v[224:225], 0, s[8:9]
	s_mov_b32 m0, s16
	s_nop 0
	global_load_lds_dwordx4 v[128:129], off
	v_lshl_add_u64 v[128:129], v[226:227], 0, s[8:9]
	s_add_i32 m0, s16, 0x2000
	s_nop 0
	global_load_lds_dwordx4 v[128:129], off
	s_waitcnt vmcnt(6)
	s_barrier
	v_mfma_f32_16x16x32_bf16 v[52:55], v[192:195], v[144:147], v[52:55]
	v_mfma_f32_16x16x32_bf16 v[48:51], v[210:213], v[144:147], v[48:51]
	v_mfma_f32_16x16x32_bf16 v[32:35], v[210:213], v[152:155], v[32:35]
	v_mfma_f32_16x16x32_bf16 v[36:39], v[192:195], v[152:155], v[36:39]
	v_mfma_f32_16x16x32_bf16 v[20:23], v[192:195], v[160:163], v[20:23]
	v_mfma_f32_16x16x32_bf16 v[16:19], v[210:213], v[160:163], v[16:19]
	v_mfma_f32_16x16x32_bf16 v[0:3], v[210:213], v[184:187], v[0:3]
	v_mfma_f32_16x16x32_bf16 v[4:7], v[192:195], v[184:187], v[4:7]
	v_mfma_f32_16x16x32_bf16 v[52:55], v[206:209], v[148:151], v[52:55]
	v_mfma_f32_16x16x32_bf16 v[48:51], v[214:217], v[148:151], v[48:51]
	v_mfma_f32_16x16x32_bf16 v[32:35], v[214:217], v[156:159], v[32:35]
	v_mfma_f32_16x16x32_bf16 v[36:39], v[206:209], v[156:159], v[36:39]
	v_mfma_f32_16x16x32_bf16 v[20:23], v[206:209], v[180:183], v[20:23]
	v_mfma_f32_16x16x32_bf16 v[16:19], v[214:217], v[180:183], v[16:19]
	v_mfma_f32_16x16x32_bf16 v[0:3], v[214:217], v[188:191], v[0:3]
	v_mfma_f32_16x16x32_bf16 v[4:7], v[206:209], v[188:191], v[4:7]
	s_add_u32 s14, s14, 0x100
	s_addc_u32 s15, s15, 0
	s_add_u32 s56, s56, 0x100
	s_addc_u32 s57, s57, 0
	s_cmp_ge_i32 s64, s25
	s_mov_b32 s16, s64
	s_barrier
	s_cbranch_scc0 .LBB0_1848
	v_readlane_b32 s64, v241, 0
	v_readlane_b32 s66, v241, 2
	v_readlane_b32 s65, v241, 1
	v_readlane_b32 s67, v241, 3

; #define PG8_STAGE(bufoff, gbase, voff) do { _Pragma("unroll") for (int _i = 0; _i < 2; ++_i) \
;         __builtin_amdgcn_global_load_lds((const unsigned*)((const char*)(gbase) + (voff)[_i]), (LAS unsigned*)(lds + (bufoff) + ldsw + _i * 8192), 16, 0, 0); } while (0)
; #define PG8_LDA(dst, b, h) do { _Pragma("unroll") for (int m = 0; m < 4; ++m) _Pragma("unroll") for (int k = 0; k < 2; ++k) dst[m][k] = *(const LAS bf16x8*)(lds + PG8_SA(b, h) + aoff + m * 2048 + k * 1024); } while (0)
; #define PG8_LDB(dst, b, h) do { _Pragma("unroll") for (int n = 0; n < 2; ++n) _Pragma("unroll") for (int k = 0; k < 2; ++k) dst[n][k] = *(const LAS bf16x8*)(lds + PG8_SB(b, h) + boff + n * 2048 + k * 1024); } while (0)
; #define PG8_MMA(ai, bj, At, Bt) do { __builtin_amdgcn_s_setprio(1); _Pragma("unroll") for (int m = 0; m < 4; ++m) _Pragma("unroll") for (int n = 0; n < 2; ++n) _Pragma("unroll") for (int k = 0; k < 2; ++k) \
;         acc[ai][bj][m][n] = __builtin_amdgcn_mfma_f32_16x16x32_bf16(Bt[n][k], At[m][k], acc[ai][bj][m][n], 0, 0, 0); __builtin_amdgcn_s_setprio(0); } while (0)
; #define PG8_WAIT_L(n) asm volatile("s_waitcnt lgkmcnt(" #n ")" ::: "memory")
; #define PG8_BAR __builtin_amdgcn_s_barrier()
; #define PG8_SCHED __builtin_amdgcn_sched_barrier(0)
; template <class Epi>
; DEVI void gemm_phase(LAS unsigned char* lds, const bf16_t* gA, const bf16_t* gBt, const int lda, const int ldb, const int K, const StaticOrder S_, const Epi E) {
;     ...
;         for (int t = 0; t < nt; t += 2) {
;             const bool last = (t == nt - 2);
;             const char* a1 = cA + (size_t)(t + 1) * kstep;
;             const char* a2 = last ? nA : cA + (size_t)(t + 2) * kstep; const char* b2 = last ? nB : cB + (size_t)(t + 2) * kstep;
;             const char* a3 = a2 + kstep; const char* b3 = b2 + kstep;
;             PG8_LDB(B0, 0, 0); PG8_SCHED; PG8_LDA(At, 0, 0); PG8_STAGE(PG8_SA(1, 1), a1 + hstepA, voffA);
;             PG8_WAIT_L(8); PG8_BAR; PG8_WAIT_L(0); PG8_MMA(0, 0, At, B0); PG8_BAR; PG8_SCHED;
;             PG8_LDB(B1, 0, 1); PG8_STAGE(PG8_SB(0, 0), b2, voffB);
;             PG8_BAR; PG8_WAIT_L(0); PG8_MMA(0, 1, At, B1); PG8_BAR;
;             PG8_LDA(At, 0, 1); PG8_STAGE(PG8_SA(0, 0), a2, voffA);
;             PG8_BAR; PG8_WAIT_L(0); PG8_MMA(1, 0, At, B0); PG8_BAR; PG8_SCHED;
.LBB0_1980:
	ds_read_b128 v[160:163], v153
	ds_read_b128 v[164:167], v153 offset:1024
	ds_read_b128 v[168:171], v153 offset:2048
	ds_read_b128 v[172:175], v153 offset:3072
	s_add_i32 s70, s16, 2
	s_add_u32 s38, s14, 0x80
	s_addc_u32 s17, s15, 0
	s_cmp_eq_u32 s26, s16
	s_cselect_b32 s16, s54, s38
	s_cselect_b32 s17, s55, s17
	s_cselect_b32 s39, s57, s61
	s_cselect_b32 s38, s56, s60
	v_lshl_add_u64 v[144:145], s[14:15], 0, v[138:139]
	s_add_i32 m0, s19, 0xc000
	ds_read_b128 v[176:179], v154
	ds_read_b128 v[180:183], v154 offset:1024
	ds_read_b128 v[184:187], v154 offset:2048
	ds_read_b128 v[188:191], v154 offset:3072
	ds_read_b128 v[192:195], v154 offset:4096
	ds_read_b128 v[198:201], v154 offset:5120
	ds_read_b128 v[202:205], v154 offset:6144
	ds_read_b128 v[206:209], v154 offset:7168
	global_load_lds_dwordx4 v[144:145], off
	v_lshl_add_u64 v[144:145], s[14:15], 0, v[140:141]
	s_add_i32 m0, s19, 0xe000
	s_nop 0
	global_load_lds_dwordx4 v[144:145], off
	s_waitcnt lgkmcnt(8)
	s_barrier
	s_waitcnt lgkmcnt(0)
	v_mfma_f32_16x16x32_bf16 v[124:127], v[160:163], v[176:179], v[124:127]
	v_mfma_f32_16x16x32_bf16 v[120:123], v[168:171], v[176:179], v[120:123]
	v_mfma_f32_16x16x32_bf16 v[104:107], v[168:171], v[184:187], v[104:107]
	v_mfma_f32_16x16x32_bf16 v[108:111], v[160:163], v[184:187], v[108:111]
	v_mfma_f32_16x16x32_bf16 v[92:95], v[160:163], v[192:195], v[92:95]
	v_mfma_f32_16x16x32_bf16 v[88:91], v[168:171], v[192:195], v[88:91]
	v_mfma_f32_16x16x32_bf16 v[72:75], v[168:171], v[202:205], v[72:75]
	v_mfma_f32_16x16x32_bf16 v[76:79], v[160:163], v[202:205], v[76:79]
	v_mfma_f32_16x16x32_bf16 v[124:127], v[164:167], v[180:183], v[124:127]
	v_mfma_f32_16x16x32_bf16 v[120:123], v[172:175], v[180:183], v[120:123]
	v_mfma_f32_16x16x32_bf16 v[104:107], v[172:175], v[188:191], v[104:107]
	v_mfma_f32_16x16x32_bf16 v[108:111], v[164:167], v[188:191], v[108:111]
	v_mfma_f32_16x16x32_bf16 v[92:95], v[164:167], v[198:201], v[92:95]
	v_mfma_f32_16x16x32_bf16 v[88:91], v[172:175], v[198:201], v[88:91]
	v_mfma_f32_16x16x32_bf16 v[72:75], v[172:175], v[206:209], v[72:75]
	v_mfma_f32_16x16x32_bf16 v[76:79], v[164:167], v[206:209], v[76:79]
	s_barrier
	s_add_i32 s71, s31, s18
	v_lshl_add_u64 v[144:145], s[38:39], 0, v[130:131]
	s_mov_b32 m0, s71
	ds_read_b128 v[210:213], v155
	ds_read_b128 v[214:217], v155 offset:1024
	ds_read_b128 v[218:221], v155 offset:2048
	ds_read_b128 v[222:225], v155 offset:3072
	global_load_lds_dwordx4 v[144:145], off
	v_lshl_add_u64 v[226:227], s[38:39], 0, v[134:135]
	s_add_i32 m0, s71, 0x2000
	s_nop 0
	global_load_lds_dwordx4 v[226:227], off
	s_barrier
	s_waitcnt lgkmcnt(0)
	v_mfma_f32_16x16x32_bf16 v[116:119], v[210:213], v[176:179], v[116:119]
	v_mfma_f32_16x16x32_bf16 v[112:115], v[218:221], v[176:179], v[112:115]
	v_mfma_f32_16x16x32_bf16 v[96:99], v[218:221], v[184:187], v[96:99]
	v_mfma_f32_16x16x32_bf16 v[100:103], v[210:213], v[184:187], v[100:103]
	v_mfma_f32_16x16x32_bf16 v[84:87], v[210:213], v[192:195], v[84:87]
	v_mfma_f32_16x16x32_bf16 v[80:83], v[218:221], v[192:195], v[80:83]
	v_mfma_f32_16x16x32_bf16 v[64:67], v[218:221], v[202:205], v[64:67]
	v_mfma_f32_16x16x32_bf16 v[68:71], v[210:213], v[202:205], v[68:71]
	v_mfma_f32_16x16x32_bf16 v[116:119], v[214:217], v[180:183], v[116:119]
	v_mfma_f32_16x16x32_bf16 v[112:115], v[222:225], v[180:183], v[112:115]
	v_mfma_f32_16x16x32_bf16 v[96:99], v[222:225], v[188:191], v[96:99]
	v_mfma_f32_16x16x32_bf16 v[100:103], v[214:217], v[188:191], v[100:103]
	v_mfma_f32_16x16x32_bf16 v[84:87], v[214:217], v[198:201], v[84:87]
	v_mfma_f32_16x16x32_bf16 v[80:83], v[222:225], v[198:201], v[80:83]
	v_mfma_f32_16x16x32_bf16 v[64:67], v[222:225], v[206:209], v[64:67]
	v_mfma_f32_16x16x32_bf16 v[68:71], v[214:217], v[206:209], v[68:71]
	s_mov_b32 m0, s19
	v_lshl_add_u64 v[228:229], s[16:17], 0, v[128:129]
	s_barrier
	ds_read_b128 v[176:179], v154 offset:16384
	ds_read_b128 v[180:183], v154 offset:17408
	ds_read_b128 v[184:187], v154 offset:18432
	ds_read_b128 v[188:191], v154 offset:19456
	ds_read_b128 v[192:195], v154 offset:20480
	ds_read_b128 v[198:201], v154 offset:21504
	ds_read_b128 v[202:205], v154 offset:22528
	ds_read_b128 v[206:209], v154 offset:23552
	global_load_lds_dwordx4 v[228:229], off
	v_lshl_add_u64 v[230:231], s[16:17], 0, v[132:133]
	s_mov_b32 m0, s20
	s_nop 0
	global_load_lds_dwordx4 v[230:231], off
	s_barrier
	s_waitcnt lgkmcnt(0)
	v_mfma_f32_16x16x32_bf16 v[60:63], v[160:163], v[176:179], v[60:63]
	v_mfma_f32_16x16x32_bf16 v[56:59], v[168:171], v[176:179], v[56:59]
	v_mfma_f32_16x16x32_bf16 v[40:43], v[168:171], v[184:187], v[40:43]
	v_mfma_f32_16x16x32_bf16 v[44:47], v[160:163], v[184:187], v[44:47]
	v_mfma_f32_16x16x32_bf16 v[28:31], v[160:163], v[192:195], v[28:31]
	v_mfma_f32_16x16x32_bf16 v[24:27], v[168:171], v[192:195], v[24:27]
	v_mfma_f32_16x16x32_bf16 v[8:11], v[168:171], v[202:205], v[8:11]
	v_mfma_f32_16x16x32_bf16 v[12:15], v[160:163], v[202:205], v[12:15]
	v_mfma_f32_16x16x32_bf16 v[60:63], v[164:167], v[180:183], v[60:63]
	v_mfma_f32_16x16x32_bf16 v[56:59], v[172:175], v[180:183], v[56:59]
	v_mfma_f32_16x16x32_bf16 v[40:43], v[172:175], v[188:191], v[40:43]
	v_mfma_f32_16x16x32_bf16 v[44:47], v[164:167], v[188:191], v[44:47]
	v_mfma_f32_16x16x32_bf16 v[28:31], v[164:167], v[198:201], v[28:31]
	v_mfma_f32_16x16x32_bf16 v[24:27], v[172:175], v[198:201], v[24:27]
	v_mfma_f32_16x16x32_bf16 v[8:11], v[172:175], v[206:209], v[8:11]
	v_mfma_f32_16x16x32_bf16 v[12:15], v[164:167], v[206:209], v[12:15]
	s_barrier
; #define PG8_STAGE(bufoff, gbase, voff) do { _Pragma("unroll") for (int _i = 0; _i < 2; ++_i) \
;         __builtin_amdgcn_global_load_lds((const unsigned*)((const char*)(gbase) + (voff)[_i]), (LAS unsigned*)(lds + (bufoff) + ldsw + _i * 8192), 16, 0, 0); } while (0)
; #define PG8_LDA(dst, b, h) do { _Pragma("unroll") for (int m = 0; m < 4; ++m) _Pragma("unroll") for (int k = 0; k < 2; ++k) dst[m][k] = *(const LAS bf16x8*)(lds + PG8_SA(b, h) + aoff + m * 2048 + k * 1024); } while (0)
; #define PG8_LDB(dst, b, h) do { _Pragma("unroll") for (int n = 0; n < 2; ++n) _Pragma("unroll") for (int k = 0; k < 2; ++k) dst[n][k] = *(const LAS bf16x8*)(lds + PG8_SB(b, h) + boff + n * 2048 + k * 1024); } while (0)
; #define PG8_MMA(ai, bj, At, Bt) do { __builtin_amdgcn_s_setprio(1); _Pragma("unroll") for (int m = 0; m < 4; ++m) _Pragma("unroll") for (int n = 0; n < 2; ++n) _Pragma("unroll") for (int k = 0; k < 2; ++k) \
;         acc[ai][bj][m][n] = __builtin_amdgcn_mfma_f32_16x16x32_bf16(Bt[n][k], At[m][k], acc[ai][bj][m][n], 0, 0, 0); __builtin_amdgcn_s_setprio(0); } while (0)
; #define PG8_WAIT_V(n) asm volatile("s_waitcnt vmcnt(" #n ")" ::: "memory")
; #define PG8_WAIT_L(n) asm volatile("s_waitcnt lgkmcnt(" #n ")" ::: "memory")
; #define PG8_BAR __builtin_amdgcn_s_barrier()
; #define PG8_SCHED __builtin_amdgcn_sched_barrier(0)
; template <class Epi>
; DEVI void gemm_phase(LAS unsigned char* lds, const bf16_t* gA, const bf16_t* gBt, const int lda, const int ldb, const int K, const StaticOrder S_, const Epi E) {
;     ...
;             PG8_STAGE(PG8_SB(0, 1), b2 + hstepB, voffB);
;             PG8_WAIT_V(6); PG8_BAR; PG8_MMA(1, 1, At, B1); PG8_BAR;
;             PG8_LDB(B0, 1, 0); PG8_SCHED; PG8_LDA(At, 1, 0); PG8_STAGE(PG8_SA(0, 1), a2 + hstepA, voffA);
;             PG8_WAIT_L(8); PG8_BAR; PG8_WAIT_L(0); PG8_MMA(0, 0, At, B0); PG8_BAR; PG8_SCHED;
;             PG8_LDB(B1, 1, 1); PG8_STAGE(PG8_SB(1, 0), b3, voffB);
	s_add_u32 s38, s38, s2
	s_addc_u32 s39, s39, s3
	s_add_i32 s71, s48, s18
	v_lshl_add_u64 v[232:233], s[38:39], 0, v[130:131]
	s_mov_b32 m0, s71
	v_lshl_add_u64 v[234:235], s[38:39], 0, v[134:135]
	global_load_lds_dwordx4 v[232:233], off
	s_add_i32 m0, s71, 0x2000
	s_nop 0
	global_load_lds_dwordx4 v[234:235], off
	s_waitcnt vmcnt(6)
	s_barrier
	v_mfma_f32_16x16x32_bf16 v[52:55], v[210:213], v[176:179], v[52:55]
	v_mfma_f32_16x16x32_bf16 v[48:51], v[218:221], v[176:179], v[48:51]
	v_mfma_f32_16x16x32_bf16 v[32:35], v[218:221], v[184:187], v[32:35]
	v_mfma_f32_16x16x32_bf16 v[36:39], v[210:213], v[184:187], v[36:39]
	v_mfma_f32_16x16x32_bf16 v[20:23], v[210:213], v[192:195], v[20:23]
	v_mfma_f32_16x16x32_bf16 v[16:19], v[218:221], v[192:195], v[16:19]
	v_mfma_f32_16x16x32_bf16 v[0:3], v[218:221], v[202:205], v[0:3]
	v_mfma_f32_16x16x32_bf16 v[4:7], v[210:213], v[202:205], v[4:7]
	v_mfma_f32_16x16x32_bf16 v[52:55], v[214:217], v[180:183], v[52:55]
	v_mfma_f32_16x16x32_bf16 v[48:51], v[222:225], v[180:183], v[48:51]
	v_mfma_f32_16x16x32_bf16 v[32:35], v[222:225], v[188:191], v[32:35]
	v_mfma_f32_16x16x32_bf16 v[36:39], v[214:217], v[188:191], v[36:39]
	v_mfma_f32_16x16x32_bf16 v[20:23], v[214:217], v[198:201], v[20:23]
	v_mfma_f32_16x16x32_bf16 v[16:19], v[222:225], v[198:201], v[16:19]
	v_mfma_f32_16x16x32_bf16 v[0:3], v[222:225], v[206:209], v[0:3]
	v_mfma_f32_16x16x32_bf16 v[4:7], v[214:217], v[206:209], v[4:7]
	s_barrier
	ds_read_b128 v[160:163], v156
	ds_read_b128 v[164:167], v156 offset:1024
	ds_read_b128 v[168:171], v156 offset:2048
	ds_read_b128 v[172:175], v156 offset:3072
	s_add_u32 s16, s16, s0
	s_addc_u32 s17, s17, s1
	s_mov_b32 m0, s21
	v_lshl_add_u64 v[210:211], s[16:17], 0, v[128:129]
	ds_read_b128 v[176:179], v154 offset:32768
	ds_read_b128 v[180:183], v154 offset:33792
	ds_read_b128 v[184:187], v154 offset:34816
	ds_read_b128 v[188:191], v154 offset:35840
	ds_read_b128 v[192:195], v154 offset:36864
	ds_read_b128 v[198:201], v154 offset:37888
	ds_read_b128 v[202:205], v154 offset:38912
	ds_read_b128 v[206:209], v154 offset:39936
	global_load_lds_dwordx4 v[210:211], off
	v_lshl_add_u64 v[210:211], s[16:17], 0, v[132:133]
	s_mov_b32 m0, s22
	s_nop 0
	global_load_lds_dwordx4 v[210:211], off
	s_waitcnt lgkmcnt(8)
	s_barrier
	s_waitcnt lgkmcnt(0)
	v_mfma_f32_16x16x32_bf16 v[124:127], v[160:163], v[176:179], v[124:127]
	v_mfma_f32_16x16x32_bf16 v[120:123], v[168:171], v[176:179], v[120:123]
	v_mfma_f32_16x16x32_bf16 v[104:107], v[168:171], v[184:187], v[104:107]
	v_mfma_f32_16x16x32_bf16 v[108:111], v[160:163], v[184:187], v[108:111]
	v_mfma_f32_16x16x32_bf16 v[92:95], v[160:163], v[192:195], v[92:95]
	v_mfma_f32_16x16x32_bf16 v[88:91], v[168:171], v[192:195], v[88:91]
	v_mfma_f32_16x16x32_bf16 v[72:75], v[168:171], v[202:205], v[72:75]
	v_mfma_f32_16x16x32_bf16 v[76:79], v[160:163], v[202:205], v[76:79]
	v_mfma_f32_16x16x32_bf16 v[124:127], v[164:167], v[180:183], v[124:127]
	v_mfma_f32_16x16x32_bf16 v[120:123], v[172:175], v[180:183], v[120:123]
	v_mfma_f32_16x16x32_bf16 v[104:107], v[172:175], v[188:191], v[104:107]
	v_mfma_f32_16x16x32_bf16 v[108:111], v[164:167], v[188:191], v[108:111]
	v_mfma_f32_16x16x32_bf16 v[92:95], v[164:167], v[198:201], v[92:95]
	v_mfma_f32_16x16x32_bf16 v[88:91], v[172:175], v[198:201], v[88:91]
	v_mfma_f32_16x16x32_bf16 v[72:75], v[172:175], v[206:209], v[72:75]
	v_mfma_f32_16x16x32_bf16 v[76:79], v[164:167], v[206:209], v[76:79]
	s_barrier
	s_add_i32 s16, s49, s18
	v_lshl_add_u64 v[144:145], v[144:145], 0, s[52:53]
	s_mov_b32 m0, s16
	ds_read_b128 v[210:213], v157
	ds_read_b128 v[214:217], v157 offset:1024
	ds_read_b128 v[218:221], v157 offset:2048
	ds_read_b128 v[222:225], v157 offset:3072
	global_load_lds_dwordx4 v[144:145], off
	v_lshl_add_u64 v[144:145], v[226:227], 0, s[52:53]
	s_add_i32 m0, s16, 0x2000
	s_nop 0
	global_load_lds_dwordx4 v[144:145], off
	s_barrier
; #define PG8_STAGE(bufoff, gbase, voff) do { _Pragma("unroll") for (int _i = 0; _i < 2; ++_i) \
;         __builtin_amdgcn_global_load_lds((const unsigned*)((const char*)(gbase) + (voff)[_i]), (LAS unsigned*)(lds + (bufoff) + ldsw + _i * 8192), 16, 0, 0); } while (0)
; #define PG8_LDA(dst, b, h) do { _Pragma("unroll") for (int m = 0; m < 4; ++m) _Pragma("unroll") for (int k = 0; k < 2; ++k) dst[m][k] = *(const LAS bf16x8*)(lds + PG8_SA(b, h) + aoff + m * 2048 + k * 1024); } while (0)
; #define PG8_MMA(ai, bj, At, Bt) do { __builtin_amdgcn_s_setprio(1); _Pragma("unroll") for (int m = 0; m < 4; ++m) _Pragma("unroll") for (int n = 0; n < 2; ++n) _Pragma("unroll") for (int k = 0; k < 2; ++k) \
;         acc[ai][bj][m][n] = __builtin_amdgcn_mfma_f32_16x16x32_bf16(Bt[n][k], At[m][k], acc[ai][bj][m][n], 0, 0, 0); __builtin_amdgcn_s_setprio(0); } while (0)
; #define PG8_WAIT_V(n) asm volatile("s_waitcnt vmcnt(" #n ")" ::: "memory")
; #define PG8_WAIT_L(n) asm volatile("s_waitcnt lgkmcnt(" #n ")" ::: "memory")
; #define PG8_BAR __builtin_amdgcn_s_barrier()
; #define PG8_SCHED __builtin_amdgcn_sched_barrier(0)
; template <class Epi>
; DEVI void gemm_phase(LAS unsigned char* lds, const bf16_t* gA, const bf16_t* gBt, const int lda, const int ldb, const int K, const StaticOrder S_, const Epi E) {
;     ...
;             PG8_BAR; PG8_WAIT_L(0); PG8_MMA(0, 1, At, B1); PG8_BAR;
;             PG8_LDA(At, 1, 1); PG8_STAGE(PG8_SA(1, 0), a3, voffA);
;             PG8_BAR; PG8_WAIT_L(0); PG8_MMA(1, 0, At, B0); PG8_BAR; PG8_SCHED;
;             PG8_STAGE(PG8_SB(1, 1), b3 + hstepB, voffB);
;             PG8_WAIT_V(6); PG8_BAR; PG8_MMA(1, 1, At, B1); PG8_BAR;
	s_waitcnt lgkmcnt(0)
	v_mfma_f32_16x16x32_bf16 v[116:119], v[210:213], v[176:179], v[116:119]
	v_mfma_f32_16x16x32_bf16 v[112:115], v[218:221], v[176:179], v[112:115]
	v_mfma_f32_16x16x32_bf16 v[96:99], v[218:221], v[184:187], v[96:99]
	v_mfma_f32_16x16x32_bf16 v[100:103], v[210:213], v[184:187], v[100:103]
	v_mfma_f32_16x16x32_bf16 v[84:87], v[210:213], v[192:195], v[84:87]
	v_mfma_f32_16x16x32_bf16 v[80:83], v[218:221], v[192:195], v[80:83]
	v_mfma_f32_16x16x32_bf16 v[64:67], v[218:221], v[202:205], v[64:67]
	v_mfma_f32_16x16x32_bf16 v[68:71], v[210:213], v[202:205], v[68:71]
	v_mfma_f32_16x16x32_bf16 v[116:119], v[214:217], v[180:183], v[116:119]
	v_mfma_f32_16x16x32_bf16 v[112:115], v[222:225], v[180:183], v[112:115]
	v_mfma_f32_16x16x32_bf16 v[96:99], v[222:225], v[188:191], v[96:99]
	v_mfma_f32_16x16x32_bf16 v[100:103], v[214:217], v[188:191], v[100:103]
	v_mfma_f32_16x16x32_bf16 v[84:87], v[214:217], v[198:201], v[84:87]
	v_mfma_f32_16x16x32_bf16 v[80:83], v[222:225], v[198:201], v[80:83]
	v_mfma_f32_16x16x32_bf16 v[64:67], v[222:225], v[206:209], v[64:67]
	v_mfma_f32_16x16x32_bf16 v[68:71], v[214:217], v[206:209], v[68:71]
	s_mov_b32 m0, s23
	v_lshl_add_u64 v[144:145], v[228:229], 0, s[52:53]
	s_barrier
	ds_read_b128 v[176:179], v154 offset:49152
	ds_read_b128 v[180:183], v154 offset:50176
	ds_read_b128 v[184:187], v154 offset:51200
	ds_read_b128 v[188:191], v154 offset:52224
	ds_read_b128 v[192:195], v154 offset:53248
	ds_read_b128 v[198:201], v154 offset:54272
	ds_read_b128 v[202:205], v154 offset:55296
	ds_read_b128 v[206:209], v154 offset:56320
	global_load_lds_dwordx4 v[144:145], off
	v_lshl_add_u64 v[144:145], v[230:231], 0, s[52:53]
	s_mov_b32 m0, s24
	s_nop 0
	global_load_lds_dwordx4 v[144:145], off
	s_barrier
	s_waitcnt lgkmcnt(0)
	v_mfma_f32_16x16x32_bf16 v[60:63], v[160:163], v[176:179], v[60:63]
	v_mfma_f32_16x16x32_bf16 v[56:59], v[168:171], v[176:179], v[56:59]
	v_mfma_f32_16x16x32_bf16 v[40:43], v[168:171], v[184:187], v[40:43]
	v_mfma_f32_16x16x32_bf16 v[44:47], v[160:163], v[184:187], v[44:47]
	v_mfma_f32_16x16x32_bf16 v[28:31], v[160:163], v[192:195], v[28:31]
	v_mfma_f32_16x16x32_bf16 v[24:27], v[168:171], v[192:195], v[24:27]
	v_mfma_f32_16x16x32_bf16 v[8:11], v[168:171], v[202:205], v[8:11]
	v_mfma_f32_16x16x32_bf16 v[12:15], v[160:163], v[202:205], v[12:15]
	v_mfma_f32_16x16x32_bf16 v[60:63], v[164:167], v[180:183], v[60:63]
	v_mfma_f32_16x16x32_bf16 v[56:59], v[172:175], v[180:183], v[56:59]
	v_mfma_f32_16x16x32_bf16 v[40:43], v[172:175], v[188:191], v[40:43]
	v_mfma_f32_16x16x32_bf16 v[44:47], v[164:167], v[188:191], v[44:47]
	v_mfma_f32_16x16x32_bf16 v[28:31], v[164:167], v[198:201], v[28:31]
	v_mfma_f32_16x16x32_bf16 v[24:27], v[172:175], v[198:201], v[24:27]
	v_mfma_f32_16x16x32_bf16 v[8:11], v[172:175], v[206:209], v[8:11]
	v_mfma_f32_16x16x32_bf16 v[12:15], v[164:167], v[206:209], v[12:15]
	s_barrier
	s_add_i32 s16, s50, s18
	v_lshl_add_u64 v[144:145], v[232:233], 0, s[52:53]
	s_mov_b32 m0, s16
	s_nop 0
	global_load_lds_dwordx4 v[144:145], off
	v_lshl_add_u64 v[144:145], v[234:235], 0, s[52:53]
	s_add_i32 m0, s16, 0x2000
	s_nop 0
	global_load_lds_dwordx4 v[144:145], off
	s_waitcnt vmcnt(6)
	s_barrier
	v_mfma_f32_16x16x32_bf16 v[52:55], v[210:213], v[176:179], v[52:55]
	v_mfma_f32_16x16x32_bf16 v[48:51], v[218:221], v[176:179], v[48:51]
	v_mfma_f32_16x16x32_bf16 v[32:35], v[218:221], v[184:187], v[32:35]
	v_mfma_f32_16x16x32_bf16 v[36:39], v[210:213], v[184:187], v[36:39]
	v_mfma_f32_16x16x32_bf16 v[20:23], v[210:213], v[192:195], v[20:23]
	v_mfma_f32_16x16x32_bf16 v[16:19], v[218:221], v[192:195], v[16:19]
	v_mfma_f32_16x16x32_bf16 v[0:3], v[218:221], v[202:205], v[0:3]
	v_mfma_f32_16x16x32_bf16 v[4:7], v[210:213], v[202:205], v[4:7]
	v_mfma_f32_16x16x32_bf16 v[52:55], v[214:217], v[180:183], v[52:55]
	v_mfma_f32_16x16x32_bf16 v[48:51], v[222:225], v[180:183], v[48:51]
	v_mfma_f32_16x16x32_bf16 v[32:35], v[222:225], v[188:191], v[32:35]
	v_mfma_f32_16x16x32_bf16 v[36:39], v[214:217], v[188:191], v[36:39]
	v_mfma_f32_16x16x32_bf16 v[20:23], v[214:217], v[198:201], v[20:23]
	v_mfma_f32_16x16x32_bf16 v[16:19], v[222:225], v[198:201], v[16:19]
	v_mfma_f32_16x16x32_bf16 v[0:3], v[222:225], v[206:209], v[0:3]
	v_mfma_f32_16x16x32_bf16 v[4:7], v[214:217], v[206:209], v[4:7]
	s_add_u32 s14, s14, 0x100
	s_addc_u32 s15, s15, 0
	s_add_u32 s60, s60, 0x100
	s_addc_u32 s61, s61, 0
	s_cmp_ge_i32 s70, s25
	s_mov_b32 s16, s70
	s_barrier
	s_cbranch_scc0 .LBB0_1980

; #define PG8_STAGE(bufoff, gbase, voff) do { _Pragma("unroll") for (int _i = 0; _i < 2; ++_i) \
;         __builtin_amdgcn_global_load_lds((const unsigned*)((const char*)(gbase) + (voff)[_i]), (LAS unsigned*)(lds + (bufoff) + ldsw + _i * 8192), 16, 0, 0); } while (0)
; #define PG8_LDA(dst, b, h) do { _Pragma("unroll") for (int m = 0; m < 4; ++m) _Pragma("unroll") for (int k = 0; k < 2; ++k) dst[m][k] = *(const LAS bf16x8*)(lds + PG8_SA(b, h) + aoff + m * 2048 + k * 1024); } while (0)
; #define PG8_LDB(dst, b, h) do { _Pragma("unroll") for (int n = 0; n < 2; ++n) _Pragma("unroll") for (int k = 0; k < 2; ++k) dst[n][k] = *(const LAS bf16x8*)(lds + PG8_SB(b, h) + boff + n * 2048 + k * 1024); } while (0)
; #define PG8_MMA(ai, bj, At, Bt) do { __builtin_amdgcn_s_setprio(1); _Pragma("unroll") for (int m = 0; m < 4; ++m) _Pragma("unroll") for (int n = 0; n < 2; ++n) _Pragma("unroll") for (int k = 0; k < 2; ++k) \
;         acc[ai][bj][m][n] = __builtin_amdgcn_mfma_f32_16x16x32_bf16(Bt[n][k], At[m][k], acc[ai][bj][m][n], 0, 0, 0); __builtin_amdgcn_s_setprio(0); } while (0)
; #define PG8_WAIT_L(n) asm volatile("s_waitcnt lgkmcnt(" #n ")" ::: "memory")
; #define PG8_BAR __builtin_amdgcn_s_barrier()
; #define PG8_SCHED __builtin_amdgcn_sched_barrier(0)
; template <class Epi>
; DEVI void gemm_phase(LAS unsigned char* lds, const bf16_t* gA, const bf16_t* gBt, const int lda, const int ldb, const int K, const StaticOrder S_, const Epi E) {
;     ...
;         for (int t = 0; t < nt; t += 2) {
;             const bool last = (t == nt - 2);
;             const char* a1 = cA + (size_t)(t + 1) * kstep;
;             const char* a2 = last ? nA : cA + (size_t)(t + 2) * kstep; const char* b2 = last ? nB : cB + (size_t)(t + 2) * kstep;
;             const char* a3 = a2 + kstep; const char* b3 = b2 + kstep;
;             PG8_LDB(B0, 0, 0); PG8_SCHED; PG8_LDA(At, 0, 0); PG8_STAGE(PG8_SA(1, 1), a1 + hstepA, voffA);
;             PG8_WAIT_L(8); PG8_BAR; PG8_WAIT_L(0); PG8_MMA(0, 0, At, B0); PG8_BAR; PG8_SCHED;
;             PG8_LDB(B1, 0, 1); PG8_STAGE(PG8_SB(0, 0), b2, voffB);
;             PG8_BAR; PG8_WAIT_L(0); PG8_MMA(0, 1, At, B1); PG8_BAR;
;             PG8_LDA(At, 0, 1); PG8_STAGE(PG8_SA(0, 0), a2, voffA);
;             PG8_BAR; PG8_WAIT_L(0); PG8_MMA(1, 0, At, B0); PG8_BAR; PG8_SCHED;
.LBB0_2366:
	ds_read_b128 v[128:131], v201
	ds_read_b128 v[132:135], v201 offset:1024
	ds_read_b128 v[136:139], v201 offset:2048
	ds_read_b128 v[140:143], v201 offset:3072
	s_add_i32 s60, s16, 2
	s_add_u32 s38, s14, 0x80
	s_addc_u32 s17, s15, 0
	s_cmp_eq_u32 s19, s16
	s_cselect_b32 s16, s12, s38
	s_cselect_b32 s17, s13, s17
	s_cselect_b32 s39, s41, s49
	s_cselect_b32 s38, s40, s48
	v_lshl_add_u64 v[164:165], s[14:15], 0, v[174:175]
	s_add_i32 m0, s55, 0xc000
	ds_read_b128 v[144:147], v202
	ds_read_b128 v[148:151], v202 offset:1024
	ds_read_b128 v[152:155], v202 offset:2048
	ds_read_b128 v[156:159], v202 offset:3072
	ds_read_b128 v[160:163], v202 offset:4096
	ds_read_b128 v[180:183], v202 offset:5120
	ds_read_b128 v[184:187], v202 offset:6144
	ds_read_b128 v[188:191], v202 offset:7168
	global_load_lds_dwordx4 v[164:165], off
	v_lshl_add_u64 v[164:165], s[14:15], 0, v[176:177]
	s_add_i32 m0, s55, 0xe000
	s_nop 0
	global_load_lds_dwordx4 v[164:165], off
	s_waitcnt lgkmcnt(8)
	s_barrier
	s_waitcnt lgkmcnt(0)
	v_mfma_f32_16x16x32_bf16 v[124:127], v[128:131], v[144:147], v[124:127]
	v_mfma_f32_16x16x32_bf16 v[120:123], v[136:139], v[144:147], v[120:123]
	v_mfma_f32_16x16x32_bf16 v[104:107], v[136:139], v[152:155], v[104:107]
	v_mfma_f32_16x16x32_bf16 v[108:111], v[128:131], v[152:155], v[108:111]
	v_mfma_f32_16x16x32_bf16 v[92:95], v[128:131], v[160:163], v[92:95]
	v_mfma_f32_16x16x32_bf16 v[88:91], v[136:139], v[160:163], v[88:91]
	v_mfma_f32_16x16x32_bf16 v[72:75], v[136:139], v[184:187], v[72:75]
	v_mfma_f32_16x16x32_bf16 v[76:79], v[128:131], v[184:187], v[76:79]
	v_mfma_f32_16x16x32_bf16 v[124:127], v[132:135], v[148:151], v[124:127]
	v_mfma_f32_16x16x32_bf16 v[120:123], v[140:143], v[148:151], v[120:123]
	v_mfma_f32_16x16x32_bf16 v[104:107], v[140:143], v[156:159], v[104:107]
	v_mfma_f32_16x16x32_bf16 v[108:111], v[132:135], v[156:159], v[108:111]
	v_mfma_f32_16x16x32_bf16 v[92:95], v[132:135], v[180:183], v[92:95]
	v_mfma_f32_16x16x32_bf16 v[88:91], v[140:143], v[180:183], v[88:91]
	v_mfma_f32_16x16x32_bf16 v[72:75], v[140:143], v[188:191], v[72:75]
	v_mfma_f32_16x16x32_bf16 v[76:79], v[132:135], v[188:191], v[76:79]
	s_barrier
	s_add_i32 s61, s29, s20
	v_lshl_add_u64 v[164:165], s[38:39], 0, v[168:169]
	s_mov_b32 m0, s61
	ds_read_b128 v[192:195], v203
	ds_read_b128 v[206:209], v203 offset:1024
	ds_read_b128 v[210:213], v203 offset:2048
	ds_read_b128 v[214:217], v203 offset:3072
	global_load_lds_dwordx4 v[164:165], off
	v_lshl_add_u64 v[218:219], s[38:39], 0, v[172:173]
	s_add_i32 m0, s61, 0x2000
	s_nop 0
	global_load_lds_dwordx4 v[218:219], off
	s_barrier
	s_waitcnt lgkmcnt(0)
	v_mfma_f32_16x16x32_bf16 v[116:119], v[192:195], v[144:147], v[116:119]
	v_mfma_f32_16x16x32_bf16 v[112:115], v[210:213], v[144:147], v[112:115]
	v_mfma_f32_16x16x32_bf16 v[96:99], v[210:213], v[152:155], v[96:99]
	v_mfma_f32_16x16x32_bf16 v[100:103], v[192:195], v[152:155], v[100:103]
	v_mfma_f32_16x16x32_bf16 v[84:87], v[192:195], v[160:163], v[84:87]
	v_mfma_f32_16x16x32_bf16 v[80:83], v[210:213], v[160:163], v[80:83]
	v_mfma_f32_16x16x32_bf16 v[64:67], v[210:213], v[184:187], v[64:67]
	v_mfma_f32_16x16x32_bf16 v[68:71], v[192:195], v[184:187], v[68:71]
	v_mfma_f32_16x16x32_bf16 v[116:119], v[206:209], v[148:151], v[116:119]
	v_mfma_f32_16x16x32_bf16 v[112:115], v[214:217], v[148:151], v[112:115]
	v_mfma_f32_16x16x32_bf16 v[96:99], v[214:217], v[156:159], v[96:99]
	v_mfma_f32_16x16x32_bf16 v[100:103], v[206:209], v[156:159], v[100:103]
	v_mfma_f32_16x16x32_bf16 v[84:87], v[206:209], v[180:183], v[84:87]
	v_mfma_f32_16x16x32_bf16 v[80:83], v[214:217], v[180:183], v[80:83]
	v_mfma_f32_16x16x32_bf16 v[64:67], v[214:217], v[188:191], v[64:67]
	v_mfma_f32_16x16x32_bf16 v[68:71], v[206:209], v[188:191], v[68:71]
	s_mov_b32 m0, s55
	v_lshl_add_u64 v[220:221], s[16:17], 0, v[166:167]
	s_barrier
	ds_read_b128 v[144:147], v202 offset:16384
	ds_read_b128 v[148:151], v202 offset:17408
	ds_read_b128 v[152:155], v202 offset:18432
	ds_read_b128 v[156:159], v202 offset:19456
	ds_read_b128 v[160:163], v202 offset:20480
	ds_read_b128 v[180:183], v202 offset:21504
	ds_read_b128 v[184:187], v202 offset:22528
	ds_read_b128 v[188:191], v202 offset:23552
	global_load_lds_dwordx4 v[220:221], off
	v_lshl_add_u64 v[222:223], s[16:17], 0, v[170:171]
	s_mov_b32 m0, s22
	s_nop 0
	global_load_lds_dwordx4 v[222:223], off
	s_barrier
	s_waitcnt lgkmcnt(0)
	v_mfma_f32_16x16x32_bf16 v[60:63], v[128:131], v[144:147], v[60:63]
	v_mfma_f32_16x16x32_bf16 v[56:59], v[136:139], v[144:147], v[56:59]
	v_mfma_f32_16x16x32_bf16 v[40:43], v[136:139], v[152:155], v[40:43]
	v_mfma_f32_16x16x32_bf16 v[44:47], v[128:131], v[152:155], v[44:47]
	v_mfma_f32_16x16x32_bf16 v[28:31], v[128:131], v[160:163], v[28:31]
	v_mfma_f32_16x16x32_bf16 v[24:27], v[136:139], v[160:163], v[24:27]
	v_mfma_f32_16x16x32_bf16 v[8:11], v[136:139], v[184:187], v[8:11]
	v_mfma_f32_16x16x32_bf16 v[12:15], v[128:131], v[184:187], v[12:15]
	v_mfma_f32_16x16x32_bf16 v[60:63], v[132:135], v[148:151], v[60:63]
	v_mfma_f32_16x16x32_bf16 v[56:59], v[140:143], v[148:151], v[56:59]
	v_mfma_f32_16x16x32_bf16 v[40:43], v[140:143], v[156:159], v[40:43]
	v_mfma_f32_16x16x32_bf16 v[44:47], v[132:135], v[156:159], v[44:47]
	v_mfma_f32_16x16x32_bf16 v[28:31], v[132:135], v[180:183], v[28:31]
	v_mfma_f32_16x16x32_bf16 v[24:27], v[140:143], v[180:183], v[24:27]
	v_mfma_f32_16x16x32_bf16 v[8:11], v[140:143], v[188:191], v[8:11]
	v_mfma_f32_16x16x32_bf16 v[12:15], v[132:135], v[188:191], v[12:15]
	s_barrier
; #define PG8_STAGE(bufoff, gbase, voff) do { _Pragma("unroll") for (int _i = 0; _i < 2; ++_i) \
;         __builtin_amdgcn_global_load_lds((const unsigned*)((const char*)(gbase) + (voff)[_i]), (LAS unsigned*)(lds + (bufoff) + ldsw + _i * 8192), 16, 0, 0); } while (0)
; #define PG8_LDA(dst, b, h) do { _Pragma("unroll") for (int m = 0; m < 4; ++m) _Pragma("unroll") for (int k = 0; k < 2; ++k) dst[m][k] = *(const LAS bf16x8*)(lds + PG8_SA(b, h) + aoff + m * 2048 + k * 1024); } while (0)
; #define PG8_LDB(dst, b, h) do { _Pragma("unroll") for (int n = 0; n < 2; ++n) _Pragma("unroll") for (int k = 0; k < 2; ++k) dst[n][k] = *(const LAS bf16x8*)(lds + PG8_SB(b, h) + boff + n * 2048 + k * 1024); } while (0)
; #define PG8_MMA(ai, bj, At, Bt) do { __builtin_amdgcn_s_setprio(1); _Pragma("unroll") for (int m = 0; m < 4; ++m) _Pragma("unroll") for (int n = 0; n < 2; ++n) _Pragma("unroll") for (int k = 0; k < 2; ++k) \
;         acc[ai][bj][m][n] = __builtin_amdgcn_mfma_f32_16x16x32_bf16(Bt[n][k], At[m][k], acc[ai][bj][m][n], 0, 0, 0); __builtin_amdgcn_s_setprio(0); } while (0)
; #define PG8_WAIT_V(n) asm volatile("s_waitcnt vmcnt(" #n ")" ::: "memory")
; #define PG8_WAIT_L(n) asm volatile("s_waitcnt lgkmcnt(" #n ")" ::: "memory")
; #define PG8_BAR __builtin_amdgcn_s_barrier()
; #define PG8_SCHED __builtin_amdgcn_sched_barrier(0)
; template <class Epi>
; DEVI void gemm_phase(LAS unsigned char* lds, const bf16_t* gA, const bf16_t* gBt, const int lda, const int ldb, const int K, const StaticOrder S_, const Epi E) {
;     ...
;             PG8_STAGE(PG8_SB(0, 1), b2 + hstepB, voffB);
;             PG8_WAIT_V(6); PG8_BAR; PG8_MMA(1, 1, At, B1); PG8_BAR;
;             PG8_LDB(B0, 1, 0); PG8_SCHED; PG8_LDA(At, 1, 0); PG8_STAGE(PG8_SA(0, 1), a2 + hstepA, voffA);
;             PG8_WAIT_L(8); PG8_BAR; PG8_WAIT_L(0); PG8_MMA(0, 0, At, B0); PG8_BAR; PG8_SCHED;
;             PG8_LDB(B1, 1, 1); PG8_STAGE(PG8_SB(1, 0), b3, voffB);
	s_add_u32 s38, s38, s2
	s_addc_u32 s39, s39, s3
	s_add_i32 s61, s50, s20
	v_lshl_add_u64 v[224:225], s[38:39], 0, v[168:169]
	s_mov_b32 m0, s61
	v_lshl_add_u64 v[226:227], s[38:39], 0, v[172:173]
	global_load_lds_dwordx4 v[224:225], off
	s_add_i32 m0, s61, 0x2000
	s_nop 0
	global_load_lds_dwordx4 v[226:227], off
	s_waitcnt vmcnt(6)
	s_barrier
	v_mfma_f32_16x16x32_bf16 v[52:55], v[192:195], v[144:147], v[52:55]
	v_mfma_f32_16x16x32_bf16 v[48:51], v[210:213], v[144:147], v[48:51]
	v_mfma_f32_16x16x32_bf16 v[32:35], v[210:213], v[152:155], v[32:35]
	v_mfma_f32_16x16x32_bf16 v[36:39], v[192:195], v[152:155], v[36:39]
	v_mfma_f32_16x16x32_bf16 v[20:23], v[192:195], v[160:163], v[20:23]
	v_mfma_f32_16x16x32_bf16 v[16:19], v[210:213], v[160:163], v[16:19]
	v_mfma_f32_16x16x32_bf16 v[0:3], v[210:213], v[184:187], v[0:3]
	v_mfma_f32_16x16x32_bf16 v[4:7], v[192:195], v[184:187], v[4:7]
	v_mfma_f32_16x16x32_bf16 v[52:55], v[206:209], v[148:151], v[52:55]
	v_mfma_f32_16x16x32_bf16 v[48:51], v[214:217], v[148:151], v[48:51]
	v_mfma_f32_16x16x32_bf16 v[32:35], v[214:217], v[156:159], v[32:35]
	v_mfma_f32_16x16x32_bf16 v[36:39], v[206:209], v[156:159], v[36:39]
	v_mfma_f32_16x16x32_bf16 v[20:23], v[206:209], v[180:183], v[20:23]
	v_mfma_f32_16x16x32_bf16 v[16:19], v[214:217], v[180:183], v[16:19]
	v_mfma_f32_16x16x32_bf16 v[0:3], v[214:217], v[188:191], v[0:3]
	v_mfma_f32_16x16x32_bf16 v[4:7], v[206:209], v[188:191], v[4:7]
	s_add_i32 s38, 0, 0x18000
	v_add_u32_e32 v140, s38, v199
	s_barrier
	ds_read_b128 v[128:131], v140
	ds_read_b128 v[132:135], v140 offset:1024
	ds_read_b128 v[136:139], v140 offset:2048
	ds_read_b128 v[140:143], v140 offset:3072
	s_add_u32 s16, s16, s0
	s_addc_u32 s17, s17, s1
	s_mov_b32 m0, s23
	v_lshl_add_u64 v[192:193], s[16:17], 0, v[166:167]
	ds_read_b128 v[144:147], v202 offset:32768
	ds_read_b128 v[148:151], v202 offset:33792
	ds_read_b128 v[152:155], v202 offset:34816
	ds_read_b128 v[156:159], v202 offset:35840
	ds_read_b128 v[160:163], v202 offset:36864
	ds_read_b128 v[180:183], v202 offset:37888
	ds_read_b128 v[184:187], v202 offset:38912
	ds_read_b128 v[188:191], v202 offset:39936
	global_load_lds_dwordx4 v[192:193], off
	v_lshl_add_u64 v[192:193], s[16:17], 0, v[170:171]
	s_mov_b32 m0, s24
	s_nop 0
	global_load_lds_dwordx4 v[192:193], off
	s_waitcnt lgkmcnt(8)
	s_barrier
	s_waitcnt lgkmcnt(0)
	v_mfma_f32_16x16x32_bf16 v[124:127], v[128:131], v[144:147], v[124:127]
	v_mfma_f32_16x16x32_bf16 v[120:123], v[136:139], v[144:147], v[120:123]
	v_mfma_f32_16x16x32_bf16 v[104:107], v[136:139], v[152:155], v[104:107]
	v_mfma_f32_16x16x32_bf16 v[108:111], v[128:131], v[152:155], v[108:111]
	v_mfma_f32_16x16x32_bf16 v[92:95], v[128:131], v[160:163], v[92:95]
	v_mfma_f32_16x16x32_bf16 v[88:91], v[136:139], v[160:163], v[88:91]
	v_mfma_f32_16x16x32_bf16 v[72:75], v[136:139], v[184:187], v[72:75]
	v_mfma_f32_16x16x32_bf16 v[76:79], v[128:131], v[184:187], v[76:79]
	v_mfma_f32_16x16x32_bf16 v[124:127], v[132:135], v[148:151], v[124:127]
	v_mfma_f32_16x16x32_bf16 v[120:123], v[140:143], v[148:151], v[120:123]
	v_mfma_f32_16x16x32_bf16 v[104:107], v[140:143], v[156:159], v[104:107]
	v_mfma_f32_16x16x32_bf16 v[108:111], v[132:135], v[156:159], v[108:111]
	v_mfma_f32_16x16x32_bf16 v[92:95], v[132:135], v[180:183], v[92:95]
	v_mfma_f32_16x16x32_bf16 v[88:91], v[140:143], v[180:183], v[88:91]
	v_mfma_f32_16x16x32_bf16 v[72:75], v[140:143], v[188:191], v[72:75]
	v_mfma_f32_16x16x32_bf16 v[76:79], v[132:135], v[188:191], v[76:79]
	s_barrier
	s_add_i32 s16, 0, 0x1c000
	s_add_i32 s17, s38, s20
	v_add_u32_e32 v205, s16, v199
	v_lshl_add_u64 v[164:165], v[164:165], 0, s[8:9]
	s_mov_b32 m0, s17
	ds_read_b128 v[192:195], v205
	ds_read_b128 v[206:209], v205 offset:1024
	ds_read_b128 v[210:213], v205 offset:2048
	ds_read_b128 v[214:217], v205 offset:3072
	global_load_lds_dwordx4 v[164:165], off
	v_lshl_add_u64 v[164:165], v[218:219], 0, s[8:9]
	s_add_i32 m0, s17, 0x2000
	s_nop 0
	global_load_lds_dwordx4 v[164:165], off
	s_barrier
; #define PG8_STAGE(bufoff, gbase, voff) do { _Pragma("unroll") for (int _i = 0; _i < 2; ++_i) \
;         __builtin_amdgcn_global_load_lds((const unsigned*)((const char*)(gbase) + (voff)[_i]), (LAS unsigned*)(lds + (bufoff) + ldsw + _i * 8192), 16, 0, 0); } while (0)
; #define PG8_LDA(dst, b, h) do { _Pragma("unroll") for (int m = 0; m < 4; ++m) _Pragma("unroll") for (int k = 0; k < 2; ++k) dst[m][k] = *(const LAS bf16x8*)(lds + PG8_SA(b, h) + aoff + m * 2048 + k * 1024); } while (0)
; #define PG8_MMA(ai, bj, At, Bt) do { __builtin_amdgcn_s_setprio(1); _Pragma("unroll") for (int m = 0; m < 4; ++m) _Pragma("unroll") for (int n = 0; n < 2; ++n) _Pragma("unroll") for (int k = 0; k < 2; ++k) \
;         acc[ai][bj][m][n] = __builtin_amdgcn_mfma_f32_16x16x32_bf16(Bt[n][k], At[m][k], acc[ai][bj][m][n], 0, 0, 0); __builtin_amdgcn_s_setprio(0); } while (0)
; #define PG8_WAIT_V(n) asm volatile("s_waitcnt vmcnt(" #n ")" ::: "memory")
; #define PG8_WAIT_L(n) asm volatile("s_waitcnt lgkmcnt(" #n ")" ::: "memory")
; #define PG8_BAR __builtin_amdgcn_s_barrier()
; #define PG8_SCHED __builtin_amdgcn_sched_barrier(0)
; template <class Epi>
; DEVI void gemm_phase(LAS unsigned char* lds, const bf16_t* gA, const bf16_t* gBt, const int lda, const int ldb, const int K, const StaticOrder S_, const Epi E) {
;     ...
;             PG8_BAR; PG8_WAIT_L(0); PG8_MMA(0, 1, At, B1); PG8_BAR;
;             PG8_LDA(At, 1, 1); PG8_STAGE(PG8_SA(1, 0), a3, voffA);
;             PG8_BAR; PG8_WAIT_L(0); PG8_MMA(1, 0, At, B0); PG8_BAR; PG8_SCHED;
;             PG8_STAGE(PG8_SB(1, 1), b3 + hstepB, voffB);
;             PG8_WAIT_V(6); PG8_BAR; PG8_MMA(1, 1, At, B1); PG8_BAR;
	s_waitcnt lgkmcnt(0)
	v_mfma_f32_16x16x32_bf16 v[116:119], v[192:195], v[144:147], v[116:119]
	v_mfma_f32_16x16x32_bf16 v[112:115], v[210:213], v[144:147], v[112:115]
	v_mfma_f32_16x16x32_bf16 v[96:99], v[210:213], v[152:155], v[96:99]
	v_mfma_f32_16x16x32_bf16 v[100:103], v[192:195], v[152:155], v[100:103]
	v_mfma_f32_16x16x32_bf16 v[84:87], v[192:195], v[160:163], v[84:87]
	v_mfma_f32_16x16x32_bf16 v[80:83], v[210:213], v[160:163], v[80:83]
	v_mfma_f32_16x16x32_bf16 v[64:67], v[210:213], v[184:187], v[64:67]
	v_mfma_f32_16x16x32_bf16 v[68:71], v[192:195], v[184:187], v[68:71]
	v_mfma_f32_16x16x32_bf16 v[116:119], v[206:209], v[148:151], v[116:119]
	v_mfma_f32_16x16x32_bf16 v[112:115], v[214:217], v[148:151], v[112:115]
	v_mfma_f32_16x16x32_bf16 v[96:99], v[214:217], v[156:159], v[96:99]
	v_mfma_f32_16x16x32_bf16 v[100:103], v[206:209], v[156:159], v[100:103]
	v_mfma_f32_16x16x32_bf16 v[84:87], v[206:209], v[180:183], v[84:87]
	v_mfma_f32_16x16x32_bf16 v[80:83], v[214:217], v[180:183], v[80:83]
	v_mfma_f32_16x16x32_bf16 v[64:67], v[214:217], v[188:191], v[64:67]
	v_mfma_f32_16x16x32_bf16 v[68:71], v[206:209], v[188:191], v[68:71]
	s_mov_b32 m0, s26
	v_lshl_add_u64 v[164:165], v[220:221], 0, s[8:9]
	s_barrier
	ds_read_b128 v[144:147], v202 offset:49152
	ds_read_b128 v[148:151], v202 offset:50176
	ds_read_b128 v[152:155], v202 offset:51200
	ds_read_b128 v[156:159], v202 offset:52224
	ds_read_b128 v[160:163], v202 offset:53248
	ds_read_b128 v[180:183], v202 offset:54272
	ds_read_b128 v[184:187], v202 offset:55296
	ds_read_b128 v[188:191], v202 offset:56320
	global_load_lds_dwordx4 v[164:165], off
	v_lshl_add_u64 v[164:165], v[222:223], 0, s[8:9]
	s_mov_b32 m0, s27
	s_nop 0
	global_load_lds_dwordx4 v[164:165], off
	s_barrier
	s_waitcnt lgkmcnt(0)
	v_mfma_f32_16x16x32_bf16 v[60:63], v[128:131], v[144:147], v[60:63]
	v_mfma_f32_16x16x32_bf16 v[56:59], v[136:139], v[144:147], v[56:59]
	v_mfma_f32_16x16x32_bf16 v[40:43], v[136:139], v[152:155], v[40:43]
	v_mfma_f32_16x16x32_bf16 v[44:47], v[128:131], v[152:155], v[44:47]
	v_mfma_f32_16x16x32_bf16 v[28:31], v[128:131], v[160:163], v[28:31]
	v_mfma_f32_16x16x32_bf16 v[24:27], v[136:139], v[160:163], v[24:27]
	v_mfma_f32_16x16x32_bf16 v[8:11], v[136:139], v[184:187], v[8:11]
	v_mfma_f32_16x16x32_bf16 v[12:15], v[128:131], v[184:187], v[12:15]
	v_mfma_f32_16x16x32_bf16 v[60:63], v[132:135], v[148:151], v[60:63]
	v_mfma_f32_16x16x32_bf16 v[56:59], v[140:143], v[148:151], v[56:59]
	v_mfma_f32_16x16x32_bf16 v[40:43], v[140:143], v[156:159], v[40:43]
	v_mfma_f32_16x16x32_bf16 v[44:47], v[132:135], v[156:159], v[44:47]
	v_mfma_f32_16x16x32_bf16 v[28:31], v[132:135], v[180:183], v[28:31]
	v_mfma_f32_16x16x32_bf16 v[24:27], v[140:143], v[180:183], v[24:27]
	v_mfma_f32_16x16x32_bf16 v[8:11], v[140:143], v[188:191], v[8:11]
	v_mfma_f32_16x16x32_bf16 v[12:15], v[132:135], v[188:191], v[12:15]
	s_barrier
	s_add_i32 s16, s16, s20
	v_lshl_add_u64 v[128:129], v[224:225], 0, s[8:9]
	s_mov_b32 m0, s16
	s_nop 0
	global_load_lds_dwordx4 v[128:129], off
	v_lshl_add_u64 v[128:129], v[226:227], 0, s[8:9]
	s_add_i32 m0, s16, 0x2000
	s_nop 0
	global_load_lds_dwordx4 v[128:129], off
	s_waitcnt vmcnt(6)
	s_barrier
	v_mfma_f32_16x16x32_bf16 v[52:55], v[192:195], v[144:147], v[52:55]
	v_mfma_f32_16x16x32_bf16 v[48:51], v[210:213], v[144:147], v[48:51]
	v_mfma_f32_16x16x32_bf16 v[32:35], v[210:213], v[152:155], v[32:35]
	v_mfma_f32_16x16x32_bf16 v[36:39], v[192:195], v[152:155], v[36:39]
	v_mfma_f32_16x16x32_bf16 v[20:23], v[192:195], v[160:163], v[20:23]
	v_mfma_f32_16x16x32_bf16 v[16:19], v[210:213], v[160:163], v[16:19]
	v_mfma_f32_16x16x32_bf16 v[0:3], v[210:213], v[184:187], v[0:3]
	v_mfma_f32_16x16x32_bf16 v[4:7], v[192:195], v[184:187], v[4:7]
	v_mfma_f32_16x16x32_bf16 v[52:55], v[206:209], v[148:151], v[52:55]
	v_mfma_f32_16x16x32_bf16 v[48:51], v[214:217], v[148:151], v[48:51]
	v_mfma_f32_16x16x32_bf16 v[32:35], v[214:217], v[156:159], v[32:35]
	v_mfma_f32_16x16x32_bf16 v[36:39], v[206:209], v[156:159], v[36:39]
	v_mfma_f32_16x16x32_bf16 v[20:23], v[206:209], v[180:183], v[20:23]
	v_mfma_f32_16x16x32_bf16 v[16:19], v[214:217], v[180:183], v[16:19]
	v_mfma_f32_16x16x32_bf16 v[0:3], v[214:217], v[188:191], v[0:3]
	v_mfma_f32_16x16x32_bf16 v[4:7], v[206:209], v[188:191], v[4:7]
	s_add_u32 s14, s14, 0x100
	s_addc_u32 s15, s15, 0
	s_add_u32 s48, s48, 0x100
	s_addc_u32 s49, s49, 0
	s_cmp_ge_i32 s60, s25
	s_mov_b32 s16, s60
	s_barrier
	s_cbranch_scc0 .LBB0_2366

; #define PG8_STAGE(bufoff, gbase, voff) do { _Pragma("unroll") for (int _i = 0; _i < 2; ++_i) \
;         __builtin_amdgcn_global_load_lds((const unsigned*)((const char*)(gbase) + (voff)[_i]), (LAS unsigned*)(lds + (bufoff) + ldsw + _i * 8192), 16, 0, 0); } while (0)
; #define PG8_LDA(dst, b, h) do { _Pragma("unroll") for (int m = 0; m < 4; ++m) _Pragma("unroll") for (int k = 0; k < 2; ++k) dst[m][k] = *(const LAS bf16x8*)(lds + PG8_SA(b, h) + aoff + m * 2048 + k * 1024); } while (0)
; #define PG8_LDB(dst, b, h) do { _Pragma("unroll") for (int n = 0; n < 2; ++n) _Pragma("unroll") for (int k = 0; k < 2; ++k) dst[n][k] = *(const LAS bf16x8*)(lds + PG8_SB(b, h) + boff + n * 2048 + k * 1024); } while (0)
; #define PG8_MMA(ai, bj, At, Bt) do { __builtin_amdgcn_s_setprio(1); _Pragma("unroll") for (int m = 0; m < 4; ++m) _Pragma("unroll") for (int n = 0; n < 2; ++n) _Pragma("unroll") for (int k = 0; k < 2; ++k) \
;         acc[ai][bj][m][n] = __builtin_amdgcn_mfma_f32_16x16x32_bf16(Bt[n][k], At[m][k], acc[ai][bj][m][n], 0, 0, 0); __builtin_amdgcn_s_setprio(0); } while (0)
; #define PG8_WAIT_L(n) asm volatile("s_waitcnt lgkmcnt(" #n ")" ::: "memory")
; #define PG8_BAR __builtin_amdgcn_s_barrier()
; #define PG8_SCHED __builtin_amdgcn_sched_barrier(0)
; template <class Epi>
; DEVI void gemm_phase(LAS unsigned char* lds, const bf16_t* gA, const bf16_t* gBt, const int lda, const int ldb, const int K, const StaticOrder S_, const Epi E) {
;     ...
;         for (int t = 0; t < nt; t += 2) {
;             const bool last = (t == nt - 2);
;             const char* a1 = cA + (size_t)(t + 1) * kstep;
;             const char* a2 = last ? nA : cA + (size_t)(t + 2) * kstep; const char* b2 = last ? nB : cB + (size_t)(t + 2) * kstep;
;             const char* a3 = a2 + kstep; const char* b3 = b2 + kstep;
;             PG8_LDB(B0, 0, 0); PG8_SCHED; PG8_LDA(At, 0, 0); PG8_STAGE(PG8_SA(1, 1), a1 + hstepA, voffA);
;             PG8_WAIT_L(8); PG8_BAR; PG8_WAIT_L(0); PG8_MMA(0, 0, At, B0); PG8_BAR; PG8_SCHED;
;             PG8_LDB(B1, 0, 1); PG8_STAGE(PG8_SB(0, 0), b2, voffB);
;             PG8_BAR; PG8_WAIT_L(0); PG8_MMA(0, 1, At, B1); PG8_BAR;
;             PG8_LDA(At, 0, 1); PG8_STAGE(PG8_SA(0, 0), a2, voffA);
;             PG8_BAR; PG8_WAIT_L(0); PG8_MMA(1, 0, At, B0); PG8_BAR; PG8_SCHED;
.LBB0_2510:
	ds_read_b128 v[158:161], v151
	ds_read_b128 v[162:165], v151 offset:1024
	ds_read_b128 v[166:169], v151 offset:2048
	ds_read_b128 v[170:173], v151 offset:3072
	s_add_i32 s61, s16, 2
	s_add_u32 s48, s14, 0x80
	s_addc_u32 s17, s15, 0
	s_cmp_eq_u32 s26, s16
	s_cselect_b32 s16, s38, s48
	s_cselect_b32 s17, s39, s17
	s_cselect_b32 s49, s47, s60
	s_cselect_b32 s48, s46, s59
	v_lshl_add_u64 v[144:145], s[14:15], 0, v[138:139]
	s_add_i32 m0, s19, 0xc000
	ds_read_b128 v[174:177], v152
	ds_read_b128 v[178:181], v152 offset:1024
	ds_read_b128 v[182:185], v152 offset:2048
	ds_read_b128 v[186:189], v152 offset:3072
	ds_read_b128 v[190:193], v152 offset:4096
	ds_read_b128 v[198:201], v152 offset:5120
	ds_read_b128 v[202:205], v152 offset:6144
	ds_read_b128 v[206:209], v152 offset:7168
	global_load_lds_dwordx4 v[144:145], off
	v_lshl_add_u64 v[144:145], s[14:15], 0, v[140:141]
	s_add_i32 m0, s19, 0xe000
	s_nop 0
	global_load_lds_dwordx4 v[144:145], off
	s_waitcnt lgkmcnt(8)
	s_barrier
	s_waitcnt lgkmcnt(0)
	v_mfma_f32_16x16x32_bf16 v[120:123], v[158:161], v[174:177], v[120:123]
	v_mfma_f32_16x16x32_bf16 v[116:119], v[166:169], v[174:177], v[116:119]
	v_mfma_f32_16x16x32_bf16 v[100:103], v[166:169], v[182:185], v[100:103]
	v_mfma_f32_16x16x32_bf16 v[108:111], v[158:161], v[182:185], v[108:111]
	v_mfma_f32_16x16x32_bf16 v[92:95], v[158:161], v[190:193], v[92:95]
	v_mfma_f32_16x16x32_bf16 v[84:87], v[166:169], v[190:193], v[84:87]
	v_mfma_f32_16x16x32_bf16 v[68:71], v[166:169], v[202:205], v[68:71]
	v_mfma_f32_16x16x32_bf16 v[76:79], v[158:161], v[202:205], v[76:79]
	v_mfma_f32_16x16x32_bf16 v[120:123], v[162:165], v[178:181], v[120:123]
	v_mfma_f32_16x16x32_bf16 v[116:119], v[170:173], v[178:181], v[116:119]
	v_mfma_f32_16x16x32_bf16 v[100:103], v[170:173], v[186:189], v[100:103]
	v_mfma_f32_16x16x32_bf16 v[108:111], v[162:165], v[186:189], v[108:111]
	v_mfma_f32_16x16x32_bf16 v[92:95], v[162:165], v[198:201], v[92:95]
	v_mfma_f32_16x16x32_bf16 v[84:87], v[170:173], v[198:201], v[84:87]
	v_mfma_f32_16x16x32_bf16 v[68:71], v[170:173], v[206:209], v[68:71]
	v_mfma_f32_16x16x32_bf16 v[76:79], v[162:165], v[206:209], v[76:79]
	s_barrier
	s_add_i32 s62, s30, s18
	v_lshl_add_u64 v[144:145], s[48:49], 0, v[130:131]
	s_mov_b32 m0, s62
	ds_read_b128 v[210:213], v153
	ds_read_b128 v[214:217], v153 offset:1024
	ds_read_b128 v[218:221], v153 offset:2048
	ds_read_b128 v[222:225], v153 offset:3072
	global_load_lds_dwordx4 v[144:145], off
	v_lshl_add_u64 v[194:195], s[48:49], 0, v[134:135]
	s_add_i32 m0, s62, 0x2000
	s_nop 0
	global_load_lds_dwordx4 v[194:195], off
	s_barrier
	s_waitcnt lgkmcnt(0)
	v_mfma_f32_16x16x32_bf16 v[124:127], v[210:213], v[174:177], v[124:127]
	v_mfma_f32_16x16x32_bf16 v[112:115], v[218:221], v[174:177], v[112:115]
	v_mfma_f32_16x16x32_bf16 v[96:99], v[218:221], v[182:185], v[96:99]
	v_mfma_f32_16x16x32_bf16 v[104:107], v[210:213], v[182:185], v[104:107]
	v_mfma_f32_16x16x32_bf16 v[88:91], v[210:213], v[190:193], v[88:91]
	v_mfma_f32_16x16x32_bf16 v[80:83], v[218:221], v[190:193], v[80:83]
	v_mfma_f32_16x16x32_bf16 v[64:67], v[218:221], v[202:205], v[64:67]
	v_mfma_f32_16x16x32_bf16 v[72:75], v[210:213], v[202:205], v[72:75]
	v_mfma_f32_16x16x32_bf16 v[124:127], v[214:217], v[178:181], v[124:127]
	v_mfma_f32_16x16x32_bf16 v[112:115], v[222:225], v[178:181], v[112:115]
	v_mfma_f32_16x16x32_bf16 v[96:99], v[222:225], v[186:189], v[96:99]
	v_mfma_f32_16x16x32_bf16 v[104:107], v[214:217], v[186:189], v[104:107]
	v_mfma_f32_16x16x32_bf16 v[88:91], v[214:217], v[198:201], v[88:91]
	v_mfma_f32_16x16x32_bf16 v[80:83], v[222:225], v[198:201], v[80:83]
	v_mfma_f32_16x16x32_bf16 v[64:67], v[222:225], v[206:209], v[64:67]
	v_mfma_f32_16x16x32_bf16 v[72:75], v[214:217], v[206:209], v[72:75]
	s_mov_b32 m0, s19
	v_lshl_add_u64 v[226:227], s[16:17], 0, v[128:129]
	s_barrier
	ds_read_b128 v[174:177], v152 offset:16384
	ds_read_b128 v[178:181], v152 offset:17408
	ds_read_b128 v[182:185], v152 offset:18432
	ds_read_b128 v[186:189], v152 offset:19456
	ds_read_b128 v[190:193], v152 offset:20480
	ds_read_b128 v[198:201], v152 offset:21504
	ds_read_b128 v[202:205], v152 offset:22528
	ds_read_b128 v[206:209], v152 offset:23552
	global_load_lds_dwordx4 v[226:227], off
	v_lshl_add_u64 v[228:229], s[16:17], 0, v[132:133]
	s_mov_b32 m0, s20
	s_nop 0
	global_load_lds_dwordx4 v[228:229], off
	s_barrier
	s_waitcnt lgkmcnt(0)
	v_mfma_f32_16x16x32_bf16 v[60:63], v[158:161], v[174:177], v[60:63]
	v_mfma_f32_16x16x32_bf16 v[56:59], v[166:169], v[174:177], v[56:59]
	v_mfma_f32_16x16x32_bf16 v[40:43], v[166:169], v[182:185], v[40:43]
	v_mfma_f32_16x16x32_bf16 v[44:47], v[158:161], v[182:185], v[44:47]
	v_mfma_f32_16x16x32_bf16 v[28:31], v[158:161], v[190:193], v[28:31]
	v_mfma_f32_16x16x32_bf16 v[24:27], v[166:169], v[190:193], v[24:27]
	v_mfma_f32_16x16x32_bf16 v[8:11], v[166:169], v[202:205], v[8:11]
	v_mfma_f32_16x16x32_bf16 v[12:15], v[158:161], v[202:205], v[12:15]
	v_mfma_f32_16x16x32_bf16 v[60:63], v[162:165], v[178:181], v[60:63]
	v_mfma_f32_16x16x32_bf16 v[56:59], v[170:173], v[178:181], v[56:59]
	v_mfma_f32_16x16x32_bf16 v[40:43], v[170:173], v[186:189], v[40:43]
	v_mfma_f32_16x16x32_bf16 v[44:47], v[162:165], v[186:189], v[44:47]
	v_mfma_f32_16x16x32_bf16 v[28:31], v[162:165], v[198:201], v[28:31]
	v_mfma_f32_16x16x32_bf16 v[24:27], v[170:173], v[198:201], v[24:27]
	v_mfma_f32_16x16x32_bf16 v[8:11], v[170:173], v[206:209], v[8:11]
	v_mfma_f32_16x16x32_bf16 v[12:15], v[162:165], v[206:209], v[12:15]
	s_barrier
; #define PG8_STAGE(bufoff, gbase, voff) do { _Pragma("unroll") for (int _i = 0; _i < 2; ++_i) \
;         __builtin_amdgcn_global_load_lds((const unsigned*)((const char*)(gbase) + (voff)[_i]), (LAS unsigned*)(lds + (bufoff) + ldsw + _i * 8192), 16, 0, 0); } while (0)
; #define PG8_LDA(dst, b, h) do { _Pragma("unroll") for (int m = 0; m < 4; ++m) _Pragma("unroll") for (int k = 0; k < 2; ++k) dst[m][k] = *(const LAS bf16x8*)(lds + PG8_SA(b, h) + aoff + m * 2048 + k * 1024); } while (0)
; #define PG8_LDB(dst, b, h) do { _Pragma("unroll") for (int n = 0; n < 2; ++n) _Pragma("unroll") for (int k = 0; k < 2; ++k) dst[n][k] = *(const LAS bf16x8*)(lds + PG8_SB(b, h) + boff + n * 2048 + k * 1024); } while (0)
; #define PG8_MMA(ai, bj, At, Bt) do { __builtin_amdgcn_s_setprio(1); _Pragma("unroll") for (int m = 0; m < 4; ++m) _Pragma("unroll") for (int n = 0; n < 2; ++n) _Pragma("unroll") for (int k = 0; k < 2; ++k) \
;         acc[ai][bj][m][n] = __builtin_amdgcn_mfma_f32_16x16x32_bf16(Bt[n][k], At[m][k], acc[ai][bj][m][n], 0, 0, 0); __builtin_amdgcn_s_setprio(0); } while (0)
; #define PG8_WAIT_V(n) asm volatile("s_waitcnt vmcnt(" #n ")" ::: "memory")
; #define PG8_WAIT_L(n) asm volatile("s_waitcnt lgkmcnt(" #n ")" ::: "memory")
; #define PG8_BAR __builtin_amdgcn_s_barrier()
; #define PG8_SCHED __builtin_amdgcn_sched_barrier(0)
; template <class Epi>
; DEVI void gemm_phase(LAS unsigned char* lds, const bf16_t* gA, const bf16_t* gBt, const int lda, const int ldb, const int K, const StaticOrder S_, const Epi E) {
;     ...
;             PG8_STAGE(PG8_SB(0, 1), b2 + hstepB, voffB);
;             PG8_WAIT_V(6); PG8_BAR; PG8_MMA(1, 1, At, B1); PG8_BAR;
;             PG8_LDB(B0, 1, 0); PG8_SCHED; PG8_LDA(At, 1, 0); PG8_STAGE(PG8_SA(0, 1), a2 + hstepA, voffA);
;             PG8_WAIT_L(8); PG8_BAR; PG8_WAIT_L(0); PG8_MMA(0, 0, At, B0); PG8_BAR; PG8_SCHED;
;             PG8_LDB(B1, 1, 1); PG8_STAGE(PG8_SB(1, 0), b3, voffB);
	s_add_u32 s48, s48, s2
	s_addc_u32 s49, s49, s3
	s_add_i32 s62, s50, s18
	v_lshl_add_u64 v[230:231], s[48:49], 0, v[130:131]
	s_mov_b32 m0, s62
	v_lshl_add_u64 v[232:233], s[48:49], 0, v[134:135]
	global_load_lds_dwordx4 v[230:231], off
	s_add_i32 m0, s62, 0x2000
	s_nop 0
	global_load_lds_dwordx4 v[232:233], off
	s_waitcnt vmcnt(6)
	s_barrier
	v_mfma_f32_16x16x32_bf16 v[52:55], v[210:213], v[174:177], v[52:55]
	v_mfma_f32_16x16x32_bf16 v[48:51], v[218:221], v[174:177], v[48:51]
	v_mfma_f32_16x16x32_bf16 v[32:35], v[218:221], v[182:185], v[32:35]
	v_mfma_f32_16x16x32_bf16 v[36:39], v[210:213], v[182:185], v[36:39]
	v_mfma_f32_16x16x32_bf16 v[20:23], v[210:213], v[190:193], v[20:23]
	v_mfma_f32_16x16x32_bf16 v[16:19], v[218:221], v[190:193], v[16:19]
	v_mfma_f32_16x16x32_bf16 v[0:3], v[218:221], v[202:205], v[0:3]
	v_mfma_f32_16x16x32_bf16 v[4:7], v[210:213], v[202:205], v[4:7]
	v_mfma_f32_16x16x32_bf16 v[52:55], v[214:217], v[178:181], v[52:55]
	v_mfma_f32_16x16x32_bf16 v[48:51], v[222:225], v[178:181], v[48:51]
	v_mfma_f32_16x16x32_bf16 v[32:35], v[222:225], v[186:189], v[32:35]
	v_mfma_f32_16x16x32_bf16 v[36:39], v[214:217], v[186:189], v[36:39]
	v_mfma_f32_16x16x32_bf16 v[20:23], v[214:217], v[198:201], v[20:23]
	v_mfma_f32_16x16x32_bf16 v[16:19], v[222:225], v[198:201], v[16:19]
	v_mfma_f32_16x16x32_bf16 v[0:3], v[222:225], v[206:209], v[0:3]
	v_mfma_f32_16x16x32_bf16 v[4:7], v[214:217], v[206:209], v[4:7]
	s_barrier
	ds_read_b128 v[158:161], v154
	ds_read_b128 v[162:165], v154 offset:1024
	ds_read_b128 v[166:169], v154 offset:2048
	ds_read_b128 v[170:173], v154 offset:3072
	s_add_u32 s16, s16, s0
	s_addc_u32 s17, s17, s1
	s_mov_b32 m0, s21
	v_lshl_add_u64 v[210:211], s[16:17], 0, v[128:129]
	ds_read_b128 v[174:177], v152 offset:32768
	ds_read_b128 v[178:181], v152 offset:33792
	ds_read_b128 v[182:185], v152 offset:34816
	ds_read_b128 v[186:189], v152 offset:35840
	ds_read_b128 v[190:193], v152 offset:36864
	ds_read_b128 v[198:201], v152 offset:37888
	ds_read_b128 v[202:205], v152 offset:38912
	ds_read_b128 v[206:209], v152 offset:39936
	global_load_lds_dwordx4 v[210:211], off
	v_lshl_add_u64 v[210:211], s[16:17], 0, v[132:133]
	s_mov_b32 m0, s22
	s_nop 0
	global_load_lds_dwordx4 v[210:211], off
	s_waitcnt lgkmcnt(8)
	s_barrier
	s_waitcnt lgkmcnt(0)
	v_mfma_f32_16x16x32_bf16 v[120:123], v[158:161], v[174:177], v[120:123]
	v_mfma_f32_16x16x32_bf16 v[116:119], v[166:169], v[174:177], v[116:119]
	v_mfma_f32_16x16x32_bf16 v[100:103], v[166:169], v[182:185], v[100:103]
	v_mfma_f32_16x16x32_bf16 v[108:111], v[158:161], v[182:185], v[108:111]
	v_mfma_f32_16x16x32_bf16 v[92:95], v[158:161], v[190:193], v[92:95]
	v_mfma_f32_16x16x32_bf16 v[84:87], v[166:169], v[190:193], v[84:87]
	v_mfma_f32_16x16x32_bf16 v[68:71], v[166:169], v[202:205], v[68:71]
	v_mfma_f32_16x16x32_bf16 v[76:79], v[158:161], v[202:205], v[76:79]
	v_mfma_f32_16x16x32_bf16 v[120:123], v[162:165], v[178:181], v[120:123]
	v_mfma_f32_16x16x32_bf16 v[116:119], v[170:173], v[178:181], v[116:119]
	v_mfma_f32_16x16x32_bf16 v[100:103], v[170:173], v[186:189], v[100:103]
	v_mfma_f32_16x16x32_bf16 v[108:111], v[162:165], v[186:189], v[108:111]
	v_mfma_f32_16x16x32_bf16 v[92:95], v[162:165], v[198:201], v[92:95]
	v_mfma_f32_16x16x32_bf16 v[84:87], v[170:173], v[198:201], v[84:87]
	v_mfma_f32_16x16x32_bf16 v[68:71], v[170:173], v[206:209], v[68:71]
	v_mfma_f32_16x16x32_bf16 v[76:79], v[162:165], v[206:209], v[76:79]
	s_barrier
	s_add_i32 s16, s51, s18
	v_lshl_add_u64 v[144:145], v[144:145], 0, s[44:45]
	s_mov_b32 m0, s16
	ds_read_b128 v[210:213], v155
	ds_read_b128 v[214:217], v155 offset:1024
	ds_read_b128 v[218:221], v155 offset:2048
	ds_read_b128 v[222:225], v155 offset:3072
	global_load_lds_dwordx4 v[144:145], off
	v_lshl_add_u64 v[144:145], v[194:195], 0, s[44:45]
	s_add_i32 m0, s16, 0x2000
	s_nop 0
	global_load_lds_dwordx4 v[144:145], off
	s_barrier
; #define PG8_STAGE(bufoff, gbase, voff) do { _Pragma("unroll") for (int _i = 0; _i < 2; ++_i) \
;         __builtin_amdgcn_global_load_lds((const unsigned*)((const char*)(gbase) + (voff)[_i]), (LAS unsigned*)(lds + (bufoff) + ldsw + _i * 8192), 16, 0, 0); } while (0)
; #define PG8_LDA(dst, b, h) do { _Pragma("unroll") for (int m = 0; m < 4; ++m) _Pragma("unroll") for (int k = 0; k < 2; ++k) dst[m][k] = *(const LAS bf16x8*)(lds + PG8_SA(b, h) + aoff + m * 2048 + k * 1024); } while (0)
; #define PG8_MMA(ai, bj, At, Bt) do { __builtin_amdgcn_s_setprio(1); _Pragma("unroll") for (int m = 0; m < 4; ++m) _Pragma("unroll") for (int n = 0; n < 2; ++n) _Pragma("unroll") for (int k = 0; k < 2; ++k) \
;         acc[ai][bj][m][n] = __builtin_amdgcn_mfma_f32_16x16x32_bf16(Bt[n][k], At[m][k], acc[ai][bj][m][n], 0, 0, 0); __builtin_amdgcn_s_setprio(0); } while (0)
; #define PG8_WAIT_V(n) asm volatile("s_waitcnt vmcnt(" #n ")" ::: "memory")
; #define PG8_WAIT_L(n) asm volatile("s_waitcnt lgkmcnt(" #n ")" ::: "memory")
; #define PG8_BAR __builtin_amdgcn_s_barrier()
; #define PG8_SCHED __builtin_amdgcn_sched_barrier(0)
; template <class Epi>
; DEVI void gemm_phase(LAS unsigned char* lds, const bf16_t* gA, const bf16_t* gBt, const int lda, const int ldb, const int K, const StaticOrder S_, const Epi E) {
;     ...
;             PG8_BAR; PG8_WAIT_L(0); PG8_MMA(0, 1, At, B1); PG8_BAR;
;             PG8_LDA(At, 1, 1); PG8_STAGE(PG8_SA(1, 0), a3, voffA);
;             PG8_BAR; PG8_WAIT_L(0); PG8_MMA(1, 0, At, B0); PG8_BAR; PG8_SCHED;
;             PG8_STAGE(PG8_SB(1, 1), b3 + hstepB, voffB);
;             PG8_WAIT_V(6); PG8_BAR; PG8_MMA(1, 1, At, B1); PG8_BAR;
	s_waitcnt lgkmcnt(0)
	v_mfma_f32_16x16x32_bf16 v[124:127], v[210:213], v[174:177], v[124:127]
	v_mfma_f32_16x16x32_bf16 v[112:115], v[218:221], v[174:177], v[112:115]
	v_mfma_f32_16x16x32_bf16 v[96:99], v[218:221], v[182:185], v[96:99]
	v_mfma_f32_16x16x32_bf16 v[104:107], v[210:213], v[182:185], v[104:107]
	v_mfma_f32_16x16x32_bf16 v[88:91], v[210:213], v[190:193], v[88:91]
	v_mfma_f32_16x16x32_bf16 v[80:83], v[218:221], v[190:193], v[80:83]
	v_mfma_f32_16x16x32_bf16 v[64:67], v[218:221], v[202:205], v[64:67]
	v_mfma_f32_16x16x32_bf16 v[72:75], v[210:213], v[202:205], v[72:75]
	v_mfma_f32_16x16x32_bf16 v[124:127], v[214:217], v[178:181], v[124:127]
	v_mfma_f32_16x16x32_bf16 v[112:115], v[222:225], v[178:181], v[112:115]
	v_mfma_f32_16x16x32_bf16 v[96:99], v[222:225], v[186:189], v[96:99]
	v_mfma_f32_16x16x32_bf16 v[104:107], v[214:217], v[186:189], v[104:107]
	v_mfma_f32_16x16x32_bf16 v[88:91], v[214:217], v[198:201], v[88:91]
	v_mfma_f32_16x16x32_bf16 v[80:83], v[222:225], v[198:201], v[80:83]
	v_mfma_f32_16x16x32_bf16 v[64:67], v[222:225], v[206:209], v[64:67]
	v_mfma_f32_16x16x32_bf16 v[72:75], v[214:217], v[206:209], v[72:75]
	s_mov_b32 m0, s23
	v_lshl_add_u64 v[144:145], v[226:227], 0, s[44:45]
	s_barrier
	ds_read_b128 v[174:177], v152 offset:49152
	ds_read_b128 v[178:181], v152 offset:50176
	ds_read_b128 v[182:185], v152 offset:51200
	ds_read_b128 v[186:189], v152 offset:52224
	ds_read_b128 v[190:193], v152 offset:53248
	ds_read_b128 v[198:201], v152 offset:54272
	ds_read_b128 v[202:205], v152 offset:55296
	ds_read_b128 v[206:209], v152 offset:56320
	global_load_lds_dwordx4 v[144:145], off
	v_lshl_add_u64 v[144:145], v[228:229], 0, s[44:45]
	s_mov_b32 m0, s24
	s_nop 0
	global_load_lds_dwordx4 v[144:145], off
	s_barrier
	s_waitcnt lgkmcnt(0)
	v_mfma_f32_16x16x32_bf16 v[60:63], v[158:161], v[174:177], v[60:63]
	v_mfma_f32_16x16x32_bf16 v[56:59], v[166:169], v[174:177], v[56:59]
	v_mfma_f32_16x16x32_bf16 v[40:43], v[166:169], v[182:185], v[40:43]
	v_mfma_f32_16x16x32_bf16 v[44:47], v[158:161], v[182:185], v[44:47]
	v_mfma_f32_16x16x32_bf16 v[28:31], v[158:161], v[190:193], v[28:31]
	v_mfma_f32_16x16x32_bf16 v[24:27], v[166:169], v[190:193], v[24:27]
	v_mfma_f32_16x16x32_bf16 v[8:11], v[166:169], v[202:205], v[8:11]
	v_mfma_f32_16x16x32_bf16 v[12:15], v[158:161], v[202:205], v[12:15]
	v_mfma_f32_16x16x32_bf16 v[60:63], v[162:165], v[178:181], v[60:63]
	v_mfma_f32_16x16x32_bf16 v[56:59], v[170:173], v[178:181], v[56:59]
	v_mfma_f32_16x16x32_bf16 v[40:43], v[170:173], v[186:189], v[40:43]
	v_mfma_f32_16x16x32_bf16 v[44:47], v[162:165], v[186:189], v[44:47]
	v_mfma_f32_16x16x32_bf16 v[28:31], v[162:165], v[198:201], v[28:31]
	v_mfma_f32_16x16x32_bf16 v[24:27], v[170:173], v[198:201], v[24:27]
	v_mfma_f32_16x16x32_bf16 v[8:11], v[170:173], v[206:209], v[8:11]
	v_mfma_f32_16x16x32_bf16 v[12:15], v[162:165], v[206:209], v[12:15]
	s_barrier
	s_add_i32 s16, s31, s18
	v_lshl_add_u64 v[144:145], v[230:231], 0, s[44:45]
	s_mov_b32 m0, s16
	s_nop 0
	global_load_lds_dwordx4 v[144:145], off
	v_lshl_add_u64 v[144:145], v[232:233], 0, s[44:45]
	s_add_i32 m0, s16, 0x2000
	s_nop 0
	global_load_lds_dwordx4 v[144:145], off
	s_waitcnt vmcnt(6)
	s_barrier
	v_mfma_f32_16x16x32_bf16 v[52:55], v[210:213], v[174:177], v[52:55]
	v_mfma_f32_16x16x32_bf16 v[48:51], v[218:221], v[174:177], v[48:51]
	v_mfma_f32_16x16x32_bf16 v[32:35], v[218:221], v[182:185], v[32:35]
	v_mfma_f32_16x16x32_bf16 v[36:39], v[210:213], v[182:185], v[36:39]
	v_mfma_f32_16x16x32_bf16 v[20:23], v[210:213], v[190:193], v[20:23]
	v_mfma_f32_16x16x32_bf16 v[16:19], v[218:221], v[190:193], v[16:19]
	v_mfma_f32_16x16x32_bf16 v[0:3], v[218:221], v[202:205], v[0:3]
	v_mfma_f32_16x16x32_bf16 v[4:7], v[210:213], v[202:205], v[4:7]
	v_mfma_f32_16x16x32_bf16 v[52:55], v[214:217], v[178:181], v[52:55]
	v_mfma_f32_16x16x32_bf16 v[48:51], v[222:225], v[178:181], v[48:51]
	v_mfma_f32_16x16x32_bf16 v[32:35], v[222:225], v[186:189], v[32:35]
	v_mfma_f32_16x16x32_bf16 v[36:39], v[214:217], v[186:189], v[36:39]
	v_mfma_f32_16x16x32_bf16 v[20:23], v[214:217], v[198:201], v[20:23]
	v_mfma_f32_16x16x32_bf16 v[16:19], v[222:225], v[198:201], v[16:19]
	v_mfma_f32_16x16x32_bf16 v[0:3], v[222:225], v[206:209], v[0:3]
	v_mfma_f32_16x16x32_bf16 v[4:7], v[214:217], v[206:209], v[4:7]
	s_add_u32 s14, s14, 0x100
	s_addc_u32 s15, s15, 0
	s_add_u32 s59, s59, 0x100
	s_addc_u32 s60, s60, 0
	s_cmp_ge_i32 s61, s25
	s_mov_b32 s16, s61
	s_barrier
	s_cbranch_scc0 .LBB0_2510

; #define PG8_STAGE(bufoff, gbase, voff) do { _Pragma("unroll") for (int _i = 0; _i < 2; ++_i) \
;         __builtin_amdgcn_global_load_lds((const unsigned*)((const char*)(gbase) + (voff)[_i]), (LAS unsigned*)(lds + (bufoff) + ldsw + _i * 8192), 16, 0, 0); } while (0)
; #define PG8_LDA(dst, b, h) do { _Pragma("unroll") for (int m = 0; m < 4; ++m) _Pragma("unroll") for (int k = 0; k < 2; ++k) dst[m][k] = *(const LAS bf16x8*)(lds + PG8_SA(b, h) + aoff + m * 2048 + k * 1024); } while (0)
; #define PG8_LDB(dst, b, h) do { _Pragma("unroll") for (int n = 0; n < 2; ++n) _Pragma("unroll") for (int k = 0; k < 2; ++k) dst[n][k] = *(const LAS bf16x8*)(lds + PG8_SB(b, h) + boff + n * 2048 + k * 1024); } while (0)
; #define PG8_MMA(ai, bj, At, Bt) do { __builtin_amdgcn_s_setprio(1); _Pragma("unroll") for (int m = 0; m < 4; ++m) _Pragma("unroll") for (int n = 0; n < 2; ++n) _Pragma("unroll") for (int k = 0; k < 2; ++k) \
;         acc[ai][bj][m][n] = __builtin_amdgcn_mfma_f32_16x16x32_bf16(Bt[n][k], At[m][k], acc[ai][bj][m][n], 0, 0, 0); __builtin_amdgcn_s_setprio(0); } while (0)
; #define PG8_WAIT_L(n) asm volatile("s_waitcnt lgkmcnt(" #n ")" ::: "memory")
; #define PG8_BAR __builtin_amdgcn_s_barrier()
; #define PG8_SCHED __builtin_amdgcn_sched_barrier(0)
; template <class Epi>
; DEVI void gemm_phase(LAS unsigned char* lds, const bf16_t* gA, const bf16_t* gBt, const int lda, const int ldb, const int K, const StaticOrder S_, const Epi E) {
;     ...
;         for (int t = 0; t < nt; t += 2) {
;             const bool last = (t == nt - 2);
;             const char* a1 = cA + (size_t)(t + 1) * kstep;
;             const char* a2 = last ? nA : cA + (size_t)(t + 2) * kstep; const char* b2 = last ? nB : cB + (size_t)(t + 2) * kstep;
;             const char* a3 = a2 + kstep; const char* b3 = b2 + kstep;
;             PG8_LDB(B0, 0, 0); PG8_SCHED; PG8_LDA(At, 0, 0); PG8_STAGE(PG8_SA(1, 1), a1 + hstepA, voffA);
;             PG8_WAIT_L(8); PG8_BAR; PG8_WAIT_L(0); PG8_MMA(0, 0, At, B0); PG8_BAR; PG8_SCHED;
;             PG8_LDB(B1, 0, 1); PG8_STAGE(PG8_SB(0, 0), b2, voffB);
;             PG8_BAR; PG8_WAIT_L(0); PG8_MMA(0, 1, At, B1); PG8_BAR;
;             PG8_LDA(At, 0, 1); PG8_STAGE(PG8_SA(0, 0), a2, voffA);
;             PG8_BAR; PG8_WAIT_L(0); PG8_MMA(1, 0, At, B0); PG8_BAR; PG8_SCHED;
.LBB0_2589:
	ds_read_b128 v[128:131], v200
	ds_read_b128 v[132:135], v200 offset:1024
	ds_read_b128 v[136:139], v200 offset:2048
	ds_read_b128 v[140:143], v200 offset:3072
	s_add_i32 s56, s24, 2
	s_add_u32 s26, s4, 0x80
	s_addc_u32 s25, s5, 0
	s_cmp_eq_u32 s43, s24
	s_cselect_b32 s24, s22, s26
	s_cselect_b32 s25, s23, s25
	s_cselect_b32 s27, s7, s55
	s_cselect_b32 s26, s6, s54
	v_lshl_add_u64 v[164:165], s[4:5], 0, v[174:175]
	s_add_i32 m0, s34, 0xc000
	ds_read_b128 v[144:147], v201
	ds_read_b128 v[148:151], v201 offset:1024
	ds_read_b128 v[152:155], v201 offset:2048
	ds_read_b128 v[156:159], v201 offset:3072
	ds_read_b128 v[160:163], v201 offset:4096
	ds_read_b128 v[180:183], v201 offset:5120
	ds_read_b128 v[184:187], v201 offset:6144
	ds_read_b128 v[188:191], v201 offset:7168
	global_load_lds_dwordx4 v[164:165], off
	v_lshl_add_u64 v[164:165], s[4:5], 0, v[176:177]
	s_add_i32 m0, s34, 0xe000
	s_nop 0
	global_load_lds_dwordx4 v[164:165], off
	s_waitcnt lgkmcnt(8)
	s_barrier
	s_waitcnt lgkmcnt(0)
	v_mfma_f32_16x16x32_bf16 v[124:127], v[128:131], v[144:147], v[124:127]
	v_mfma_f32_16x16x32_bf16 v[120:123], v[136:139], v[144:147], v[120:123]
	v_mfma_f32_16x16x32_bf16 v[104:107], v[136:139], v[152:155], v[104:107]
	v_mfma_f32_16x16x32_bf16 v[108:111], v[128:131], v[152:155], v[108:111]
	v_mfma_f32_16x16x32_bf16 v[92:95], v[128:131], v[160:163], v[92:95]
	v_mfma_f32_16x16x32_bf16 v[88:91], v[136:139], v[160:163], v[88:91]
	v_mfma_f32_16x16x32_bf16 v[72:75], v[136:139], v[184:187], v[72:75]
	v_mfma_f32_16x16x32_bf16 v[76:79], v[128:131], v[184:187], v[76:79]
	v_mfma_f32_16x16x32_bf16 v[124:127], v[132:135], v[148:151], v[124:127]
	v_mfma_f32_16x16x32_bf16 v[120:123], v[140:143], v[148:151], v[120:123]
	v_mfma_f32_16x16x32_bf16 v[104:107], v[140:143], v[156:159], v[104:107]
	v_mfma_f32_16x16x32_bf16 v[108:111], v[132:135], v[156:159], v[108:111]
	v_mfma_f32_16x16x32_bf16 v[92:95], v[132:135], v[180:183], v[92:95]
	v_mfma_f32_16x16x32_bf16 v[88:91], v[140:143], v[180:183], v[88:91]
	v_mfma_f32_16x16x32_bf16 v[72:75], v[140:143], v[188:191], v[72:75]
	v_mfma_f32_16x16x32_bf16 v[76:79], v[132:135], v[188:191], v[76:79]
	s_barrier
	s_add_i32 s57, s49, s30
	v_lshl_add_u64 v[164:165], s[26:27], 0, v[168:169]
	s_mov_b32 m0, s57
	ds_read_b128 v[192:195], v202
	ds_read_b128 v[204:207], v202 offset:1024
	ds_read_b128 v[208:211], v202 offset:2048
	ds_read_b128 v[212:215], v202 offset:3072
	global_load_lds_dwordx4 v[164:165], off
	v_lshl_add_u64 v[216:217], s[26:27], 0, v[172:173]
	s_add_i32 m0, s57, 0x2000
	s_nop 0
	global_load_lds_dwordx4 v[216:217], off
	s_barrier
	s_waitcnt lgkmcnt(0)
	v_mfma_f32_16x16x32_bf16 v[116:119], v[192:195], v[144:147], v[116:119]
	v_mfma_f32_16x16x32_bf16 v[112:115], v[208:211], v[144:147], v[112:115]
	v_mfma_f32_16x16x32_bf16 v[96:99], v[208:211], v[152:155], v[96:99]
	v_mfma_f32_16x16x32_bf16 v[100:103], v[192:195], v[152:155], v[100:103]
	v_mfma_f32_16x16x32_bf16 v[84:87], v[192:195], v[160:163], v[84:87]
	v_mfma_f32_16x16x32_bf16 v[80:83], v[208:211], v[160:163], v[80:83]
	v_mfma_f32_16x16x32_bf16 v[64:67], v[208:211], v[184:187], v[64:67]
	v_mfma_f32_16x16x32_bf16 v[68:71], v[192:195], v[184:187], v[68:71]
	v_mfma_f32_16x16x32_bf16 v[116:119], v[204:207], v[148:151], v[116:119]
	v_mfma_f32_16x16x32_bf16 v[112:115], v[212:215], v[148:151], v[112:115]
	v_mfma_f32_16x16x32_bf16 v[96:99], v[212:215], v[156:159], v[96:99]
	v_mfma_f32_16x16x32_bf16 v[100:103], v[204:207], v[156:159], v[100:103]
	v_mfma_f32_16x16x32_bf16 v[84:87], v[204:207], v[180:183], v[84:87]
	v_mfma_f32_16x16x32_bf16 v[80:83], v[212:215], v[180:183], v[80:83]
	v_mfma_f32_16x16x32_bf16 v[64:67], v[212:215], v[188:191], v[64:67]
	v_mfma_f32_16x16x32_bf16 v[68:71], v[204:207], v[188:191], v[68:71]
	s_mov_b32 m0, s34
	v_lshl_add_u64 v[218:219], s[24:25], 0, v[166:167]
	s_barrier
	ds_read_b128 v[144:147], v201 offset:16384
	ds_read_b128 v[148:151], v201 offset:17408
	ds_read_b128 v[152:155], v201 offset:18432
	ds_read_b128 v[156:159], v201 offset:19456
	ds_read_b128 v[160:163], v201 offset:20480
	ds_read_b128 v[180:183], v201 offset:21504
	ds_read_b128 v[184:187], v201 offset:22528
	ds_read_b128 v[188:191], v201 offset:23552
	global_load_lds_dwordx4 v[218:219], off
	v_lshl_add_u64 v[220:221], s[24:25], 0, v[170:171]
	s_mov_b32 m0, s35
	s_nop 0
	global_load_lds_dwordx4 v[220:221], off
	s_barrier
	s_waitcnt lgkmcnt(0)
	v_mfma_f32_16x16x32_bf16 v[60:63], v[128:131], v[144:147], v[60:63]
	v_mfma_f32_16x16x32_bf16 v[56:59], v[136:139], v[144:147], v[56:59]
	v_mfma_f32_16x16x32_bf16 v[40:43], v[136:139], v[152:155], v[40:43]
	v_mfma_f32_16x16x32_bf16 v[44:47], v[128:131], v[152:155], v[44:47]
	v_mfma_f32_16x16x32_bf16 v[28:31], v[128:131], v[160:163], v[28:31]
	v_mfma_f32_16x16x32_bf16 v[24:27], v[136:139], v[160:163], v[24:27]
	v_mfma_f32_16x16x32_bf16 v[8:11], v[136:139], v[184:187], v[8:11]
	v_mfma_f32_16x16x32_bf16 v[12:15], v[128:131], v[184:187], v[12:15]
	v_mfma_f32_16x16x32_bf16 v[60:63], v[132:135], v[148:151], v[60:63]
	v_mfma_f32_16x16x32_bf16 v[56:59], v[140:143], v[148:151], v[56:59]
	v_mfma_f32_16x16x32_bf16 v[40:43], v[140:143], v[156:159], v[40:43]
	v_mfma_f32_16x16x32_bf16 v[44:47], v[132:135], v[156:159], v[44:47]
	v_mfma_f32_16x16x32_bf16 v[28:31], v[132:135], v[180:183], v[28:31]
	v_mfma_f32_16x16x32_bf16 v[24:27], v[140:143], v[180:183], v[24:27]
	v_mfma_f32_16x16x32_bf16 v[8:11], v[140:143], v[188:191], v[8:11]
	v_mfma_f32_16x16x32_bf16 v[12:15], v[132:135], v[188:191], v[12:15]
	s_barrier
; #define PG8_STAGE(bufoff, gbase, voff) do { _Pragma("unroll") for (int _i = 0; _i < 2; ++_i) \
;         __builtin_amdgcn_global_load_lds((const unsigned*)((const char*)(gbase) + (voff)[_i]), (LAS unsigned*)(lds + (bufoff) + ldsw + _i * 8192), 16, 0, 0); } while (0)
; #define PG8_LDA(dst, b, h) do { _Pragma("unroll") for (int m = 0; m < 4; ++m) _Pragma("unroll") for (int k = 0; k < 2; ++k) dst[m][k] = *(const LAS bf16x8*)(lds + PG8_SA(b, h) + aoff + m * 2048 + k * 1024); } while (0)
; #define PG8_LDB(dst, b, h) do { _Pragma("unroll") for (int n = 0; n < 2; ++n) _Pragma("unroll") for (int k = 0; k < 2; ++k) dst[n][k] = *(const LAS bf16x8*)(lds + PG8_SB(b, h) + boff + n * 2048 + k * 1024); } while (0)
; #define PG8_MMA(ai, bj, At, Bt) do { __builtin_amdgcn_s_setprio(1); _Pragma("unroll") for (int m = 0; m < 4; ++m) _Pragma("unroll") for (int n = 0; n < 2; ++n) _Pragma("unroll") for (int k = 0; k < 2; ++k) \
;         acc[ai][bj][m][n] = __builtin_amdgcn_mfma_f32_16x16x32_bf16(Bt[n][k], At[m][k], acc[ai][bj][m][n], 0, 0, 0); __builtin_amdgcn_s_setprio(0); } while (0)
; #define PG8_WAIT_V(n) asm volatile("s_waitcnt vmcnt(" #n ")" ::: "memory")
; #define PG8_WAIT_L(n) asm volatile("s_waitcnt lgkmcnt(" #n ")" ::: "memory")
; #define PG8_BAR __builtin_amdgcn_s_barrier()
; #define PG8_SCHED __builtin_amdgcn_sched_barrier(0)
; template <class Epi>
; DEVI void gemm_phase(LAS unsigned char* lds, const bf16_t* gA, const bf16_t* gBt, const int lda, const int ldb, const int K, const StaticOrder S_, const Epi E) {
;     ...
;             PG8_STAGE(PG8_SB(0, 1), b2 + hstepB, voffB);
;             PG8_WAIT_V(6); PG8_BAR; PG8_MMA(1, 1, At, B1); PG8_BAR;
;             PG8_LDB(B0, 1, 0); PG8_SCHED; PG8_LDA(At, 1, 0); PG8_STAGE(PG8_SA(0, 1), a2 + hstepA, voffA);
;             PG8_WAIT_L(8); PG8_BAR; PG8_WAIT_L(0); PG8_MMA(0, 0, At, B0); PG8_BAR; PG8_SCHED;
;             PG8_LDB(B1, 1, 1); PG8_STAGE(PG8_SB(1, 0), b3, voffB);
	s_add_u32 s26, s26, s10
	s_addc_u32 s27, s27, s11
	s_add_i32 s57, s50, s30
	v_lshl_add_u64 v[222:223], s[26:27], 0, v[168:169]
	s_mov_b32 m0, s57
	v_lshl_add_u64 v[224:225], s[26:27], 0, v[172:173]
	global_load_lds_dwordx4 v[222:223], off
	s_add_i32 m0, s57, 0x2000
	s_nop 0
	global_load_lds_dwordx4 v[224:225], off
	s_waitcnt vmcnt(6)
	s_barrier
	v_mfma_f32_16x16x32_bf16 v[52:55], v[192:195], v[144:147], v[52:55]
	v_mfma_f32_16x16x32_bf16 v[48:51], v[208:211], v[144:147], v[48:51]
	v_mfma_f32_16x16x32_bf16 v[32:35], v[208:211], v[152:155], v[32:35]
	v_mfma_f32_16x16x32_bf16 v[36:39], v[192:195], v[152:155], v[36:39]
	v_mfma_f32_16x16x32_bf16 v[20:23], v[192:195], v[160:163], v[20:23]
	v_mfma_f32_16x16x32_bf16 v[16:19], v[208:211], v[160:163], v[16:19]
	v_mfma_f32_16x16x32_bf16 v[0:3], v[208:211], v[184:187], v[0:3]
	v_mfma_f32_16x16x32_bf16 v[4:7], v[192:195], v[184:187], v[4:7]
	v_mfma_f32_16x16x32_bf16 v[52:55], v[204:207], v[148:151], v[52:55]
	v_mfma_f32_16x16x32_bf16 v[48:51], v[212:215], v[148:151], v[48:51]
	v_mfma_f32_16x16x32_bf16 v[32:35], v[212:215], v[156:159], v[32:35]
	v_mfma_f32_16x16x32_bf16 v[36:39], v[204:207], v[156:159], v[36:39]
	v_mfma_f32_16x16x32_bf16 v[20:23], v[204:207], v[180:183], v[20:23]
	v_mfma_f32_16x16x32_bf16 v[16:19], v[212:215], v[180:183], v[16:19]
	v_mfma_f32_16x16x32_bf16 v[0:3], v[212:215], v[188:191], v[0:3]
	v_mfma_f32_16x16x32_bf16 v[4:7], v[204:207], v[188:191], v[4:7]
	s_add_i32 s26, 0, 0x18000
	v_add_u32_e32 v140, s26, v196
	s_barrier
	ds_read_b128 v[128:131], v140
	ds_read_b128 v[132:135], v140 offset:1024
	ds_read_b128 v[136:139], v140 offset:2048
	ds_read_b128 v[140:143], v140 offset:3072
	s_add_u32 s24, s24, s2
	s_addc_u32 s25, s25, s3
	s_mov_b32 m0, s36
	v_lshl_add_u64 v[192:193], s[24:25], 0, v[166:167]
	ds_read_b128 v[144:147], v201 offset:32768
	ds_read_b128 v[148:151], v201 offset:33792
	ds_read_b128 v[152:155], v201 offset:34816
	ds_read_b128 v[156:159], v201 offset:35840
	ds_read_b128 v[160:163], v201 offset:36864
	ds_read_b128 v[180:183], v201 offset:37888
	ds_read_b128 v[184:187], v201 offset:38912
	ds_read_b128 v[188:191], v201 offset:39936
	global_load_lds_dwordx4 v[192:193], off
	v_lshl_add_u64 v[192:193], s[24:25], 0, v[170:171]
	s_mov_b32 m0, s37
	s_nop 0
	global_load_lds_dwordx4 v[192:193], off
	s_waitcnt lgkmcnt(8)
	s_barrier
	s_waitcnt lgkmcnt(0)
	v_mfma_f32_16x16x32_bf16 v[124:127], v[128:131], v[144:147], v[124:127]
	v_mfma_f32_16x16x32_bf16 v[120:123], v[136:139], v[144:147], v[120:123]
	v_mfma_f32_16x16x32_bf16 v[104:107], v[136:139], v[152:155], v[104:107]
	v_mfma_f32_16x16x32_bf16 v[108:111], v[128:131], v[152:155], v[108:111]
	v_mfma_f32_16x16x32_bf16 v[92:95], v[128:131], v[160:163], v[92:95]
	v_mfma_f32_16x16x32_bf16 v[88:91], v[136:139], v[160:163], v[88:91]
	v_mfma_f32_16x16x32_bf16 v[72:75], v[136:139], v[184:187], v[72:75]
	v_mfma_f32_16x16x32_bf16 v[76:79], v[128:131], v[184:187], v[76:79]
	v_mfma_f32_16x16x32_bf16 v[124:127], v[132:135], v[148:151], v[124:127]
	v_mfma_f32_16x16x32_bf16 v[120:123], v[140:143], v[148:151], v[120:123]
	v_mfma_f32_16x16x32_bf16 v[104:107], v[140:143], v[156:159], v[104:107]
	v_mfma_f32_16x16x32_bf16 v[108:111], v[132:135], v[156:159], v[108:111]
	v_mfma_f32_16x16x32_bf16 v[92:95], v[132:135], v[180:183], v[92:95]
	v_mfma_f32_16x16x32_bf16 v[88:91], v[140:143], v[180:183], v[88:91]
	v_mfma_f32_16x16x32_bf16 v[72:75], v[140:143], v[188:191], v[72:75]
	v_mfma_f32_16x16x32_bf16 v[76:79], v[132:135], v[188:191], v[76:79]
	s_barrier
	s_add_i32 s24, 0, 0x1c000
	s_add_i32 s25, s26, s30
	v_add_u32_e32 v212, s24, v196
	v_lshl_add_u64 v[164:165], v[164:165], 0, s[16:17]
	s_mov_b32 m0, s25
	ds_read_b128 v[192:195], v212
	ds_read_b128 v[204:207], v212 offset:1024
	ds_read_b128 v[208:211], v212 offset:2048
	ds_read_b128 v[212:215], v212 offset:3072
	global_load_lds_dwordx4 v[164:165], off
	v_lshl_add_u64 v[164:165], v[216:217], 0, s[16:17]
	s_add_i32 m0, s25, 0x2000
	s_nop 0
	global_load_lds_dwordx4 v[164:165], off
	s_barrier
; #define LAS __attribute__((address_space(3)))
; #define PG8_STAGE(bufoff, gbase, voff) do { _Pragma("unroll") for (int _i = 0; _i < 2; ++_i) \
;         __builtin_amdgcn_global_load_lds((const unsigned*)((const char*)(gbase) + (voff)[_i]), (LAS unsigned*)(lds + (bufoff) + ldsw + _i * 8192), 16, 0, 0); } while (0)
; #define PG8_LDA(dst, b, h) do { _Pragma("unroll") for (int m = 0; m < 4; ++m) _Pragma("unroll") for (int k = 0; k < 2; ++k) dst[m][k] = *(const LAS bf16x8*)(lds + PG8_SA(b, h) + aoff + m * 2048 + k * 1024); } while (0)
; #define PG8_MMA(ai, bj, At, Bt) do { __builtin_amdgcn_s_setprio(1); _Pragma("unroll") for (int m = 0; m < 4; ++m) _Pragma("unroll") for (int n = 0; n < 2; ++n) _Pragma("unroll") for (int k = 0; k < 2; ++k) \
;         acc[ai][bj][m][n] = __builtin_amdgcn_mfma_f32_16x16x32_bf16(Bt[n][k], At[m][k], acc[ai][bj][m][n], 0, 0, 0); __builtin_amdgcn_s_setprio(0); } while (0)
; #define PG8_WAIT_V(n) asm volatile("s_waitcnt vmcnt(" #n ")" ::: "memory")
; #define PG8_WAIT_L(n) asm volatile("s_waitcnt lgkmcnt(" #n ")" ::: "memory")
; #define PG8_BAR __builtin_amdgcn_s_barrier()
; #define PG8_SCHED __builtin_amdgcn_sched_barrier(0)
; template <class Epi>
; DEVI void gemm_phase(LAS unsigned char* lds, const bf16_t* gA, const bf16_t* gBt, const int lda, const int ldb, const int K, const StaticOrder S_, const Epi E) {
;     ...
;             PG8_BAR; PG8_WAIT_L(0); PG8_MMA(0, 1, At, B1); PG8_BAR;
;             PG8_LDA(At, 1, 1); PG8_STAGE(PG8_SA(1, 0), a3, voffA);
;             PG8_BAR; PG8_WAIT_L(0); PG8_MMA(1, 0, At, B0); PG8_BAR; PG8_SCHED;
;             PG8_STAGE(PG8_SB(1, 1), b3 + hstepB, voffB);
;             PG8_WAIT_V(6); PG8_BAR; PG8_MMA(1, 1, At, B1); PG8_BAR;
;         }
;         E(acc, cur, wr, wc, fr, fq, (const LAS float*)(lds + STAGE_BYTES + (ui & 1) * 2048));
	s_waitcnt lgkmcnt(0)
	v_mfma_f32_16x16x32_bf16 v[116:119], v[192:195], v[144:147], v[116:119]
	v_mfma_f32_16x16x32_bf16 v[112:115], v[208:211], v[144:147], v[112:115]
	v_mfma_f32_16x16x32_bf16 v[96:99], v[208:211], v[152:155], v[96:99]
	v_mfma_f32_16x16x32_bf16 v[100:103], v[192:195], v[152:155], v[100:103]
	v_mfma_f32_16x16x32_bf16 v[84:87], v[192:195], v[160:163], v[84:87]
	v_mfma_f32_16x16x32_bf16 v[80:83], v[208:211], v[160:163], v[80:83]
	v_mfma_f32_16x16x32_bf16 v[64:67], v[208:211], v[184:187], v[64:67]
	v_mfma_f32_16x16x32_bf16 v[68:71], v[192:195], v[184:187], v[68:71]
	v_mfma_f32_16x16x32_bf16 v[116:119], v[204:207], v[148:151], v[116:119]
	v_mfma_f32_16x16x32_bf16 v[112:115], v[212:215], v[148:151], v[112:115]
	v_mfma_f32_16x16x32_bf16 v[96:99], v[212:215], v[156:159], v[96:99]
	v_mfma_f32_16x16x32_bf16 v[100:103], v[204:207], v[156:159], v[100:103]
	v_mfma_f32_16x16x32_bf16 v[84:87], v[204:207], v[180:183], v[84:87]
	v_mfma_f32_16x16x32_bf16 v[80:83], v[212:215], v[180:183], v[80:83]
	v_mfma_f32_16x16x32_bf16 v[64:67], v[212:215], v[188:191], v[64:67]
	v_mfma_f32_16x16x32_bf16 v[68:71], v[204:207], v[188:191], v[68:71]
	s_mov_b32 m0, s39
	v_lshl_add_u64 v[164:165], v[218:219], 0, s[16:17]
	s_barrier
	ds_read_b128 v[144:147], v201 offset:49152
	ds_read_b128 v[148:151], v201 offset:50176
	ds_read_b128 v[152:155], v201 offset:51200
	ds_read_b128 v[156:159], v201 offset:52224
	ds_read_b128 v[160:163], v201 offset:53248
	ds_read_b128 v[180:183], v201 offset:54272
	ds_read_b128 v[184:187], v201 offset:55296
	ds_read_b128 v[188:191], v201 offset:56320
	global_load_lds_dwordx4 v[164:165], off
	v_lshl_add_u64 v[164:165], v[220:221], 0, s[16:17]
	s_mov_b32 m0, s40
	s_nop 0
	global_load_lds_dwordx4 v[164:165], off
	s_barrier
	s_waitcnt lgkmcnt(0)
	v_mfma_f32_16x16x32_bf16 v[60:63], v[128:131], v[144:147], v[60:63]
	v_mfma_f32_16x16x32_bf16 v[56:59], v[136:139], v[144:147], v[56:59]
	v_mfma_f32_16x16x32_bf16 v[40:43], v[136:139], v[152:155], v[40:43]
	v_mfma_f32_16x16x32_bf16 v[44:47], v[128:131], v[152:155], v[44:47]
	v_mfma_f32_16x16x32_bf16 v[28:31], v[128:131], v[160:163], v[28:31]
	v_mfma_f32_16x16x32_bf16 v[24:27], v[136:139], v[160:163], v[24:27]
	v_mfma_f32_16x16x32_bf16 v[8:11], v[136:139], v[184:187], v[8:11]
	v_mfma_f32_16x16x32_bf16 v[12:15], v[128:131], v[184:187], v[12:15]
	v_mfma_f32_16x16x32_bf16 v[60:63], v[132:135], v[148:151], v[60:63]
	v_mfma_f32_16x16x32_bf16 v[56:59], v[140:143], v[148:151], v[56:59]
	v_mfma_f32_16x16x32_bf16 v[40:43], v[140:143], v[156:159], v[40:43]
	v_mfma_f32_16x16x32_bf16 v[44:47], v[132:135], v[156:159], v[44:47]
	v_mfma_f32_16x16x32_bf16 v[28:31], v[132:135], v[180:183], v[28:31]
	v_mfma_f32_16x16x32_bf16 v[24:27], v[140:143], v[180:183], v[24:27]
	v_mfma_f32_16x16x32_bf16 v[8:11], v[140:143], v[188:191], v[8:11]
	v_mfma_f32_16x16x32_bf16 v[12:15], v[132:135], v[188:191], v[12:15]
	s_barrier
	s_add_i32 s24, s24, s30
	v_lshl_add_u64 v[128:129], v[222:223], 0, s[16:17]
	s_mov_b32 m0, s24
	s_nop 0
	global_load_lds_dwordx4 v[128:129], off
	v_lshl_add_u64 v[128:129], v[224:225], 0, s[16:17]
	s_add_i32 m0, s24, 0x2000
	s_nop 0
	global_load_lds_dwordx4 v[128:129], off
	s_waitcnt vmcnt(6)
	s_barrier
	v_mfma_f32_16x16x32_bf16 v[52:55], v[192:195], v[144:147], v[52:55]
	v_mfma_f32_16x16x32_bf16 v[48:51], v[208:211], v[144:147], v[48:51]
	v_mfma_f32_16x16x32_bf16 v[32:35], v[208:211], v[152:155], v[32:35]
	v_mfma_f32_16x16x32_bf16 v[36:39], v[192:195], v[152:155], v[36:39]
	v_mfma_f32_16x16x32_bf16 v[20:23], v[192:195], v[160:163], v[20:23]
	v_mfma_f32_16x16x32_bf16 v[16:19], v[208:211], v[160:163], v[16:19]
	v_mfma_f32_16x16x32_bf16 v[0:3], v[208:211], v[184:187], v[0:3]
	v_mfma_f32_16x16x32_bf16 v[4:7], v[192:195], v[184:187], v[4:7]
	v_mfma_f32_16x16x32_bf16 v[52:55], v[204:207], v[148:151], v[52:55]
	v_mfma_f32_16x16x32_bf16 v[48:51], v[212:215], v[148:151], v[48:51]
	v_mfma_f32_16x16x32_bf16 v[32:35], v[212:215], v[156:159], v[32:35]
	v_mfma_f32_16x16x32_bf16 v[36:39], v[204:207], v[156:159], v[36:39]
	v_mfma_f32_16x16x32_bf16 v[20:23], v[204:207], v[180:183], v[20:23]
	v_mfma_f32_16x16x32_bf16 v[16:19], v[212:215], v[180:183], v[16:19]
	v_mfma_f32_16x16x32_bf16 v[0:3], v[212:215], v[188:191], v[0:3]
	v_mfma_f32_16x16x32_bf16 v[4:7], v[204:207], v[188:191], v[4:7]
	s_add_u32 s4, s4, 0x100
	s_addc_u32 s5, s5, 0
	s_add_u32 s54, s54, 0x100
	s_addc_u32 s55, s55, 0
	s_cmp_ge_i32 s56, s41
	s_mov_b32 s24, s56
	s_barrier
	s_cbranch_scc0 .LBB0_2589
	v_readlane_b32 s56, v241, 26
	v_readlane_b32 s58, v241, 28
	v_readlane_b32 s57, v241, 27
	v_readlane_b32 s59, v241, 29
